# write-through (sc1) policy on the conversion loops' bf16 weight stores, so tail-slot barriers have less dirty L2 to flush
# baseline (speedup 1.0000x reference)
; #define LAS __attribute__((address_space(3)))
; DI unsigned cvtpk(float lo, float hi) { f32x2 v = {lo, hi}; bf16x2_t b = __builtin_convertvector(v, bf16x2_t); return __builtin_bit_cast(unsigned, b); }
; template <int KIND>
; DI void transpose_item(const float* W, int K, int N, bf16_t* WT, int ldk, const float* g0, const float* g1, const float* g2, LAS float* scr, int item, int lane) {
;     ...
;     for (int j = 0; j < 4; ++j) { const int n = (lane >> 3) + 8 * j; const LAS float* s = scr + (8 * c) * 33 + n;
;         u32x4 o; o.x = cvtpk(s[0 * 33], s[1 * 33]); o.y = cvtpk(s[2 * 33], s[3 * 33]); o.z = cvtpk(s[4 * 33], s[5 * 33]); o.w = cvtpk(s[6 * 33], s[7 * 33]);
;         *(u32x4*)(WT + (size_t)map_n<KIND>(n0 + n) * ldk + kd0 + 8 * c) = o; }
;     asm volatile("s_waitcnt lgkmcnt(0)" ::: "memory");
.LBB0_51:
	s_or_b64 exec, exec, s[8:9]
	v_ashrrev_i32_e32 v15, 31, v14
	v_lshlrev_b64 v[2:3], 12, v[14:15]
	s_waitcnt lgkmcnt(3)
	v_cvt_pk_bf16_f32 v6, v6, v7
	s_waitcnt lgkmcnt(2)
	v_cvt_pk_bf16_f32 v7, v8, v9
	s_waitcnt lgkmcnt(1)
	v_cvt_pk_bf16_f32 v8, v10, v11
	s_waitcnt lgkmcnt(0)
	v_cvt_pk_bf16_f32 v9, v12, v13
	v_lshl_add_u64 v[2:3], v[4:5], 0, v[2:3]
	global_store_dwordx4 v[2:3], v[6:9], off sc1
	s_waitcnt lgkmcnt(0)

; template <int KIND>
; DI void transpose_item(const float* W, int K, int N, bf16_t* WT, int ldk, const float* g0, const float* g1, const float* g2, LAS float* scr, int item, int lane) {
;     const int nblk = N / 32, kb = item / nblk, nb = item % nblk, k0 = 64 * kb, n0 = 32 * nb;
;     f32x4 tv[8];
; #pragma unroll
;     for (int i = 0; i < 8; ++i) tv[i] = *(const f32x4*)(W + (size_t)(k0 + 8 * i + (lane >> 3)) * N + n0 + 4 * (lane & 7));
; #pragma unroll
;     for (int i = 0; i < 8; ++i) {
;         const int kk = 8 * i + (lane >> 3), k = k0 + kk;
;         float gn = 1.f;
;         if (KIND == 0 || KIND == 1 || KIND == 2 || KIND == 5 || KIND == 6) gn = g0[k];
; DI void convert_weights(PP p, LAS unsigned char* lds, int l, int worker, int nworkers) {
;     ...
;     for (int it = worker; it < I_LAYER; it += nworkers) {
;         int r = it;
;         if (r < I_IN) { transpose_item<0>(p->in[2] + (size_t)l * 2048 * 2880, 2048, 2880, (bf16_t*)(wl + W_IN), 2048, p->in[1] + l * 2048, nullptr, nullptr, scr, r, lane); continue; } r -= I_IN;
;         if (r < I_UQ) { transpose_item<1>(p->in[4] + (size_t)l * 512 * 1536, 512, 1536, (bf16_t*)(wl + W_UQ), 512, p->in[3] + l * 512, nullptr, nullptr, scr, r, lane); continue; } r -= I_UQ;
;         if (r < I_UKV) { transpose_item<2>(p->in[6] + (size_t)l * 256 * 2048, 256, 2048, (bf16_t*)(wl + W_UKV), 256, p->in[5] + l * 256, nullptr, nullptr, scr, r, lane); continue; } r -= I_UKV;
;         if (r < I_GLU) { transpose_item<3>(p->in[15] + (size_t)l * 512 * 1024, 512, 1024, (bf16_t*)(wl + W_GLU), 512, nullptr, nullptr, nullptr, scr, r, lane); continue; } r -= I_GLU;
;         if (r < I_O) { transpose_item<4>(p->in[20] + (size_t)l * 2048 * 2048, 2048, 2048, (bf16_t*)(wl + W_O), 2048, p->in[17] + l * 1024, p->in[18] + l * 512, p->in[19] + l * 512, scr, r, lane); continue; } r -= I_O;
;         if (r < I_G) { transpose_item<5>(p->in[22] + (size_t)l * 2048 * DFF_, 2048, DFF_, (bf16_t*)(wl + W_GU), 2048, p->in[21] + l * 2048, nullptr, nullptr, scr, r, lane); continue; } r -= I_G;
;         if (r < I_G) { transpose_item<6>(p->in[23] + (size_t)l * 2048 * DFF_, 2048, DFF_, (bf16_t*)(wl + W_GU), 2048, p->in[21] + l * 2048, nullptr, nullptr, scr, r, lane); continue; } r -= I_G;
;         transpose_item<7>(p->in[24] + (size_t)l * DFF_ * 2048, DFF_, 2048, (bf16_t*)(wl + W_DN), DFF_, nullptr, nullptr, nullptr, scr, r, lane);
.LBB0_53:
	s_movk_i32 s6, 0xb3f
	v_cmp_lt_i32_e32 vcc, s6, v1
	s_and_saveexec_b64 s[6:7], vcc
	s_xor_b64 s[56:57], exec, s[6:7]
	s_cbranch_execz .LBB0_143
	s_movk_i32 s6, 0xcbf
	v_cmp_lt_u32_e32 vcc, s6, v1
	s_and_saveexec_b64 s[6:7], vcc
	s_xor_b64 s[58:59], exec, s[6:7]
	s_cbranch_execz .LBB0_140
	s_movk_i32 s6, 0xdbf
	v_cmp_lt_u32_e32 vcc, s6, v1
	s_and_saveexec_b64 s[6:7], vcc
	s_xor_b64 s[60:61], exec, s[6:7]
	s_cbranch_execz .LBB0_137
	s_movk_i32 s6, 0xebf
	v_cmp_lt_u32_e32 vcc, s6, v1
	s_and_saveexec_b64 s[6:7], vcc
	s_xor_b64 s[62:63], exec, s[6:7]
	s_cbranch_execz .LBB0_134
	s_movk_i32 s6, 0x16bf
	v_cmp_lt_u32_e32 vcc, s6, v1
	s_and_saveexec_b64 s[6:7], vcc
	s_xor_b64 s[6:7], exec, s[6:7]
	s_cbranch_execz .LBB0_67
	s_movk_i32 s8, 0x2cbf
	v_cmp_lt_u32_e32 vcc, s8, v1
	s_and_saveexec_b64 s[8:9], vcc
	s_xor_b64 s[8:9], exec, s[8:9]
	s_cbranch_execz .LBB0_64
	s_movk_i32 s10, 0x42bf
	v_cmp_lt_u32_e32 vcc, s10, v1
	s_and_saveexec_b64 s[10:11], vcc
	s_xor_b64 s[10:11], exec, s[10:11]
	s_cbranch_execz .LBB0_61
	s_load_dwordx2 s[12:13], s[4:5], 0xc0
	v_add_u32_e32 v2, 0xffffbd40, v1
	v_and_b32_e32 v55, 0x1fc0, v2
	v_add_u32_e32 v2, 0xfff7a800, v52
	v_and_b32_e32 v88, 0x7e0, v2
	v_lshlrev_b32_e32 v2, 2, v88
	v_mov_b32_e32 v3, v37
	v_or_b32_e32 v4, v55, v34
	s_waitcnt lgkmcnt(0)
	v_lshl_add_u64 v[2:3], s[12:13], 0, v[2:3]
	v_lshl_add_u64 v[2:3], v[2:3], 0, v[36:37]
	v_lshlrev_b32_e32 v4, 13, v4
	v_mov_b32_e32 v5, v37
	v_lshl_add_u64 v[30:31], v[2:3], 0, v[4:5]
	v_add_co_u32_e32 v6, vcc, s66, v30
	v_mov_b32_e32 v57, v37
	s_nop 0
	v_addc_co_u32_e32 v7, vcc, 0, v31, vcc
	v_add_co_u32_e32 v10, vcc, s67, v30
	global_load_dwordx4 v[2:5], v[30:31], off nt
	s_nop 0
	global_load_dwordx4 v[6:9], v[6:7], off nt
	v_addc_co_u32_e32 v11, vcc, 0, v31, vcc
	v_add_co_u32_e32 v14, vcc, s68, v30
	v_lshlrev_b32_e32 v56, 1, v55
	s_nop 0
	v_addc_co_u32_e32 v15, vcc, 0, v31, vcc
	v_add_co_u32_e32 v18, vcc, s69, v30
	global_load_dwordx4 v[10:13], v[10:11], off nt
	s_nop 0
	global_load_dwordx4 v[14:17], v[14:15], off nt
	v_addc_co_u32_e32 v19, vcc, 0, v31, vcc
	v_add_co_u32_e32 v22, vcc, s70, v30
	v_or_b32_e32 v55, v88, v34
	s_nop 0
	v_addc_co_u32_e32 v23, vcc, 0, v31, vcc
	global_load_dwordx4 v[18:21], v[18:19], off nt
	s_nop 0
	global_load_dwordx4 v[22:25], v[22:23], off nt
	v_add_co_u32_e32 v26, vcc, s71, v30
	v_mov_b32_e32 v85, v37
	s_nop 0
	v_addc_co_u32_e32 v27, vcc, 0, v31, vcc
	global_load_dwordx4 v[26:29], v[26:27], off nt
	v_add_co_u32_e32 v30, vcc, s72, v30
	v_lshl_add_u64 v[56:57], v[38:39], 0, v[56:57]
	s_nop 0
	v_addc_co_u32_e32 v31, vcc, 0, v31, vcc
	global_load_dwordx4 v[30:33], v[30:31], off nt
	v_mul_u32_u24_e32 v84, 0x2c00, v55
	v_lshl_add_u64 v[84:85], v[56:57], 0, v[84:85]
	v_or_b32_e32 v86, v88, v53
	v_mov_b32_e32 v87, v37
	v_mul_u32_u24_e32 v86, 0x2c00, v86
	v_lshl_add_u64 v[86:87], v[56:57], 0, v[86:87]
	s_waitcnt vmcnt(7)
	ds_write2_b32 v65, v2, v3 offset1:1
	ds_write2_b32 v65, v4, v5 offset0:2 offset1:3
	s_waitcnt vmcnt(6)
	ds_write2_b32 v66, v6, v7 offset1:1
	ds_write2_b32 v67, v8, v9 offset1:1
	s_waitcnt vmcnt(5)
	ds_write2_b32 v68, v10, v11 offset1:1
	ds_write2_b32 v69, v12, v13 offset1:1
	s_waitcnt vmcnt(4)
	ds_write2_b32 v70, v14, v15 offset1:1
	ds_write2_b32 v71, v16, v17 offset1:1
	s_waitcnt vmcnt(3)
	ds_write2_b32 v72, v18, v19 offset1:1
	ds_write2_b32 v73, v20, v21 offset1:1
	s_waitcnt vmcnt(2)
	ds_write2_b32 v74, v22, v23 offset1:1
	ds_write2_b32 v75, v24, v25 offset1:1
	s_waitcnt vmcnt(1)
	ds_write2_b32 v76, v26, v27 offset1:1
	ds_write2_b32 v77, v28, v29 offset1:1
	s_waitcnt vmcnt(0)
	ds_write2_b32 v78, v30, v31 offset1:1
	ds_write2_b32 v79, v32, v33 offset1:1
	s_waitcnt lgkmcnt(0)
	ds_read2_b32 v[6:7], v60 offset0:33 offset1:41
	ds_read2_b32 v[8:9], v60 offset1:8
	ds_read2_b32 v[10:11], v60 offset0:66 offset1:74
	ds_read2_b32 v[12:13], v60 offset0:99 offset1:107
	ds_read2_b32 v[14:15], v60 offset0:132 offset1:140
	ds_read2_b32 v[16:17], v60 offset0:165 offset1:173
	ds_read2_b32 v[18:19], v60 offset0:198 offset1:206
	ds_read2_b32 v[20:21], v60 offset0:231 offset1:239
	ds_read2_b32 v[22:23], v60 offset0:16 offset1:24
	ds_read2_b32 v[24:25], v60 offset0:49 offset1:57
	ds_read2_b32 v[26:27], v60 offset0:82 offset1:90
	ds_read2_b32 v[28:29], v60 offset0:115 offset1:123
	s_waitcnt lgkmcnt(10)
	v_cvt_pk_bf16_f32 v2, v8, v6
	s_waitcnt lgkmcnt(8)
	v_cvt_pk_bf16_f32 v3, v10, v12
	s_waitcnt lgkmcnt(6)
	v_cvt_pk_bf16_f32 v4, v14, v16
	s_waitcnt lgkmcnt(4)
	v_cvt_pk_bf16_f32 v5, v18, v20
	global_store_dwordx4 v[84:85], v[2:5], off sc1
	v_cvt_pk_bf16_f32 v6, v9, v7
	v_cvt_pk_bf16_f32 v7, v11, v13
	v_cvt_pk_bf16_f32 v8, v15, v17
	ds_read2_b32 v[10:11], v60 offset0:148 offset1:156
	ds_read2_b32 v[12:13], v60 offset0:181 offset1:189
	ds_read2_b32 v[14:15], v60 offset0:214 offset1:222
	ds_read2_b32 v[16:17], v60 offset0:247 offset1:255
	v_cvt_pk_bf16_f32 v9, v19, v21
	global_store_dwordx4 v[86:87], v[6:9], off sc1
	s_waitcnt lgkmcnt(6)
	v_cvt_pk_bf16_f32 v2, v22, v24
	s_waitcnt lgkmcnt(4)
	v_cvt_pk_bf16_f32 v3, v26, v28
	v_or_b32_e32 v6, v88, v58
	v_mul_u32_u24_e32 v6, 0x2c00, v6
	v_mov_b32_e32 v7, v37
	s_waitcnt lgkmcnt(2)
	v_cvt_pk_bf16_f32 v4, v10, v12
	s_waitcnt lgkmcnt(0)
	v_cvt_pk_bf16_f32 v5, v14, v16
	v_lshl_add_u64 v[6:7], v[56:57], 0, v[6:7]
	global_store_dwordx4 v[6:7], v[2:5], off sc1
	v_or_b32_e32 v6, v88, v59
	v_mul_u32_u24_e32 v6, 0x2c00, v6
	v_mov_b32_e32 v7, v37
	v_cvt_pk_bf16_f32 v2, v23, v25
	v_cvt_pk_bf16_f32 v3, v27, v29
	v_cvt_pk_bf16_f32 v4, v11, v13
	v_cvt_pk_bf16_f32 v5, v15, v17
	v_lshl_add_u64 v[6:7], v[56:57], 0, v[6:7]
	global_store_dwordx4 v[6:7], v[2:5], off sc1
	s_waitcnt lgkmcnt(0)
; #define LAS __attribute__((address_space(3)))
; DI unsigned cvtpk(float lo, float hi) { f32x2 v = {lo, hi}; bf16x2_t b = __builtin_convertvector(v, bf16x2_t); return __builtin_bit_cast(unsigned, b); }
; template <int KIND>
; DI void transpose_item(const float* W, int K, int N, bf16_t* WT, int ldk, const float* g0, const float* g1, const float* g2, LAS float* scr, int item, int lane) {
;     const int nblk = N / 32, kb = item / nblk, nb = item % nblk, k0 = 64 * kb, n0 = 32 * nb;
;     f32x4 tv[8];
; #pragma unroll
;     for (int i = 0; i < 8; ++i) tv[i] = *(const f32x4*)(W + (size_t)(k0 + 8 * i + (lane >> 3)) * N + n0 + 4 * (lane & 7));
; #pragma unroll
;     for (int i = 0; i < 8; ++i) {
;         const int kk = 8 * i + (lane >> 3), k = k0 + kk;
;         float gn = 1.f;
;         if (KIND == 0 || KIND == 1 || KIND == 2 || KIND == 5 || KIND == 6) gn = g0[k];
;         if (KIND == 4) gn = k < 1024 ? g0[k] : (k < 1536 ? g1[k - 1024] : g2[k - 1536]);
;         LAS float* d = scr + kk * 33 + 4 * (lane & 7);
;         d[0] = tv[i][0] * gn; d[1] = tv[i][1] * gn; d[2] = tv[i][2] * gn; d[3] = tv[i][3] * gn;
;     }
;     asm volatile("s_waitcnt lgkmcnt(0)" ::: "memory");
;     int kd0 = k0;
;     if (KIND == 4) kd0 = k0 < 1024 ? k0 + 512 : (k0 < 1536 ? k0 - 1024 : k0);
;     const int c = lane & 7;
; #pragma unroll
;     for (int j = 0; j < 4; ++j) { const int n = (lane >> 3) + 8 * j; const LAS float* s = scr + (8 * c) * 33 + n;
;         u32x4 o; o.x = cvtpk(s[0 * 33], s[1 * 33]); o.y = cvtpk(s[2 * 33], s[3 * 33]); o.z = cvtpk(s[4 * 33], s[5 * 33]); o.w = cvtpk(s[6 * 33], s[7 * 33]);
;         *(u32x4*)(WT + (size_t)map_n<KIND>(n0 + n) * ldk + kd0 + 8 * c) = o; }
;     asm volatile("s_waitcnt lgkmcnt(0)" ::: "memory");
.LBB0_61:
	s_andn2_saveexec_b64 s[10:11], s[10:11]
	s_cbranch_execz .LBB0_63
	v_add_u16_e32 v2, 0xd340, v1
	v_mul_u32_u24_e32 v3, 0xba2f, v2
	s_load_dwordx2 s[12:13], s[4:5], 0xa8
	s_load_dwordx2 s[14:15], s[4:5], 0xb8
	v_lshrrev_b32_e32 v3, 23, v3
	v_mul_lo_u16_e32 v4, 0xb0, v3
	v_sub_u16_e32 v2, v2, v4
	v_lshlrev_b16_e32 v55, 6, v3
	v_lshlrev_b16_e32 v57, 5, v2
	v_or_b32_e32 v20, v34, v55
	v_lshlrev_b32_e32 v2, 2, v57
	v_mov_b32_e32 v3, v37
	s_waitcnt lgkmcnt(0)
	v_lshl_add_u64 v[2:3], s[14:15], 0, v[2:3]
	v_mul_u32_u24_e32 v4, 0x1600, v20
	v_lshl_add_u64 v[2:3], v[2:3], 0, v[36:37]
	v_lshlrev_b32_e32 v4, 2, v4
	v_mov_b32_e32 v5, v37
	v_lshl_add_u64 v[30:31], v[2:3], 0, v[4:5]
	v_add_co_u32_e32 v6, vcc, s73, v30
	v_lshlrev_b32_e32 v32, 2, v20
	s_nop 0
	v_addc_co_u32_e32 v7, vcc, 0, v31, vcc
	v_add_co_u32_e32 v10, vcc, s74, v30
	global_load_dwordx4 v[2:5], v[30:31], off nt
	s_nop 0
	global_load_dwordx4 v[6:9], v[6:7], off nt
	v_addc_co_u32_e32 v11, vcc, 0, v31, vcc
	v_add_co_u32_e32 v14, vcc, s75, v30
	v_add_u32_e32 v85, v35, v61
	s_nop 0
	v_addc_co_u32_e32 v15, vcc, 0, v31, vcc
	v_add_co_u32_e32 v18, vcc, s76, v30
	global_load_dwordx4 v[10:13], v[10:11], off nt
	s_nop 0
	global_load_dwordx4 v[14:17], v[14:15], off nt
	v_addc_co_u32_e32 v19, vcc, 0, v31, vcc
	v_add_co_u32_e32 v22, vcc, s77, v30
	global_load_dword v56, v32, s[12:13]
	s_nop 0
	v_addc_co_u32_e32 v23, vcc, 0, v31, vcc
	v_add_co_u32_e32 v26, vcc, s78, v30
	global_load_dwordx4 v[18:21], v[18:19], off nt
	s_nop 0
	global_load_dwordx4 v[22:25], v[22:23], off nt
	s_nop 0
	global_load_dword v84, v32, s[12:13] offset:32
	global_load_dword v86, v32, s[12:13] offset:64
	global_load_dword v88, v32, s[12:13] offset:96
	global_load_dword v90, v32, s[12:13] offset:128
	v_addc_co_u32_e32 v27, vcc, 0, v31, vcc
	v_add_co_u32_e32 v30, vcc, s79, v30
	global_load_dword v92, v32, s[12:13] offset:160
	s_nop 0
	global_load_dwordx4 v[26:29], v[26:27], off nt
	s_nop 0
	global_load_dword v94, v32, s[12:13] offset:192
	v_addc_co_u32_e32 v31, vcc, 0, v31, vcc
	global_load_dword v96, v32, s[12:13] offset:224
	s_nop 0
	global_load_dwordx4 v[30:33], v[30:31], off nt
	v_add_u32_e32 v87, 0x420, v85
	v_add_u32_e32 v89, 0x428, v85
	v_add_u32_e32 v91, 0x840, v85
	s_waitcnt vmcnt(11)
	v_pk_mul_f32 v[2:3], v[2:3], v[56:57] op_sel_hi:[1,0]
	v_pk_mul_f32 v[4:5], v[4:5], v[56:57] op_sel_hi:[1,0]
	ds_write2_b32 v65, v2, v3 offset1:1
	ds_write2_b32 v65, v4, v5 offset0:2 offset1:3
	s_waitcnt vmcnt(8)
	v_pk_mul_f32 v[2:3], v[6:7], v[84:85] op_sel_hi:[1,0]
	v_pk_mul_f32 v[4:5], v[8:9], v[84:85] op_sel_hi:[1,0]
	s_waitcnt vmcnt(7)
	v_pk_mul_f32 v[6:7], v[10:11], v[86:87] op_sel_hi:[1,0]
	v_pk_mul_f32 v[8:9], v[12:13], v[86:87] op_sel_hi:[1,0]
	s_waitcnt vmcnt(6)
	v_pk_mul_f32 v[10:11], v[14:15], v[88:89] op_sel_hi:[1,0]
	v_pk_mul_f32 v[12:13], v[16:17], v[88:89] op_sel_hi:[1,0]
	s_waitcnt vmcnt(5)
	v_pk_mul_f32 v[14:15], v[18:19], v[90:91] op_sel_hi:[1,0]
	v_pk_mul_f32 v[16:17], v[20:21], v[90:91] op_sel_hi:[1,0]
	s_waitcnt vmcnt(4)
	v_pk_mul_f32 v[18:19], v[22:23], v[92:93] op_sel_hi:[1,0]
	v_pk_mul_f32 v[20:21], v[24:25], v[92:93] op_sel_hi:[1,0]
	s_waitcnt vmcnt(2)
	v_pk_mul_f32 v[22:23], v[26:27], v[94:95] op_sel_hi:[1,0]
	ds_write2_b32 v66, v2, v3 offset1:1
	ds_write2_b32 v67, v4, v5 offset1:1
	ds_write2_b32 v68, v6, v7 offset1:1
	ds_write2_b32 v69, v8, v9 offset1:1
	ds_write2_b32 v70, v10, v11 offset1:1
	ds_write2_b32 v71, v12, v13 offset1:1
	ds_write2_b32 v85, v14, v15 offset1:1
	ds_write2_b32 v85, v16, v17 offset0:2 offset1:3
	ds_write2_b32 v87, v18, v19 offset1:1
	ds_write2_b32 v89, v20, v21 offset1:1
	ds_write2_b32 v91, v22, v23 offset1:1
	v_pk_mul_f32 v[2:3], v[28:29], v[94:95] op_sel_hi:[1,0]
	v_add_u32_e32 v4, 0x848, v85
	ds_write2_b32 v4, v2, v3 offset1:1
	s_waitcnt vmcnt(0)
	v_pk_mul_f32 v[2:3], v[30:31], v[96:97] op_sel_hi:[1,0]
	v_add_u32_e32 v4, 0xc60, v85
	ds_write2_b32 v4, v2, v3 offset1:1
	v_pk_mul_f32 v[2:3], v[32:33], v[96:97] op_sel_hi:[1,0]
	v_add_u32_e32 v4, 0xc68, v85
	ds_write2_b32 v4, v2, v3 offset1:1
	s_waitcnt lgkmcnt(0)
	ds_read2_b32 v[6:7], v60 offset0:33 offset1:41
	ds_read2_b32 v[8:9], v60 offset1:8
	ds_read2_b32 v[10:11], v60 offset0:66 offset1:74
	ds_read2_b32 v[12:13], v60 offset0:99 offset1:107
	ds_read2_b32 v[14:15], v60 offset0:132 offset1:140
	ds_read2_b32 v[16:17], v60 offset0:165 offset1:173
	ds_read2_b32 v[18:19], v60 offset0:198 offset1:206
	ds_read2_b32 v[20:21], v60 offset0:231 offset1:239
	s_waitcnt lgkmcnt(6)
	v_cvt_pk_bf16_f32 v2, v8, v6
	v_or_b32_e32 v6, v34, v57
	v_lshlrev_b32_e32 v22, 13, v6
	v_mov_b32_e32 v23, v37
	v_lshl_add_u64 v[22:23], s[22:23], 0, v[22:23]
	v_lshlrev_b32_e32 v24, 1, v55
	v_mov_b32_e32 v25, v37
	v_lshl_add_u64 v[22:23], v[22:23], 0, v[24:25]
	v_mov_b32_e32 v55, v37
	v_lshl_add_u64 v[22:23], v[22:23], 0, v[54:55]
	v_add_co_u32_e32 v22, vcc, s80, v22
	s_waitcnt lgkmcnt(4)
	v_cvt_pk_bf16_f32 v3, v10, v12
	s_waitcnt lgkmcnt(2)
	v_cvt_pk_bf16_f32 v4, v14, v16
	s_waitcnt lgkmcnt(0)
	v_cvt_pk_bf16_f32 v5, v18, v20
	v_addc_co_u32_e32 v23, vcc, 0, v23, vcc
	v_or_b32_e32 v6, v53, v57
	global_store_dwordx4 v[22:23], v[2:5], off sc1
	v_lshlrev_b32_e32 v6, 13, v6
	s_nop 0
	v_cvt_pk_bf16_f32 v2, v9, v7
	v_mov_b32_e32 v7, v37
	v_lshl_add_u64 v[6:7], s[22:23], 0, v[6:7]
	v_lshl_add_u64 v[6:7], v[6:7], 0, v[24:25]
	v_lshl_add_u64 v[6:7], v[6:7], 0, v[54:55]
	v_add_co_u32_e32 v6, vcc, s80, v6
	v_cvt_pk_bf16_f32 v3, v11, v13
	v_cvt_pk_bf16_f32 v4, v15, v17
	v_cvt_pk_bf16_f32 v5, v19, v21
	v_addc_co_u32_e32 v7, vcc, 0, v7, vcc
	ds_read2_b32 v[8:9], v60 offset0:49 offset1:57
	ds_read2_b32 v[10:11], v60 offset0:16 offset1:24
	ds_read2_b32 v[12:13], v60 offset0:82 offset1:90
	ds_read2_b32 v[14:15], v60 offset0:115 offset1:123
	ds_read2_b32 v[16:17], v60 offset0:148 offset1:156
	ds_read2_b32 v[18:19], v60 offset0:181 offset1:189
	ds_read2_b32 v[20:21], v60 offset0:214 offset1:222
	ds_read2_b32 v[22:23], v60 offset0:247 offset1:255
	global_store_dwordx4 v[6:7], v[2:5], off sc1
	v_or_b32_e32 v6, v58, v57
	v_lshlrev_b32_e32 v6, 13, v6
	v_mov_b32_e32 v7, v37
	v_lshl_add_u64 v[6:7], s[22:23], 0, v[6:7]
	v_lshl_add_u64 v[6:7], v[6:7], 0, v[24:25]
	v_lshl_add_u64 v[6:7], v[6:7], 0, v[54:55]
	v_add_co_u32_e32 v6, vcc, s80, v6
	s_waitcnt lgkmcnt(6)
	v_cvt_pk_bf16_f32 v2, v10, v8
	s_waitcnt lgkmcnt(4)
	v_cvt_pk_bf16_f32 v3, v12, v14
	s_waitcnt lgkmcnt(2)
	v_cvt_pk_bf16_f32 v4, v16, v18
	s_waitcnt lgkmcnt(0)
	v_cvt_pk_bf16_f32 v5, v20, v22
	v_addc_co_u32_e32 v7, vcc, 0, v7, vcc
	global_store_dwordx4 v[6:7], v[2:5], off sc1
	v_or_b32_e32 v6, v59, v57
	v_lshlrev_b32_e32 v6, 13, v6
	v_mov_b32_e32 v7, v37
	v_lshl_add_u64 v[6:7], s[22:23], 0, v[6:7]
	v_lshl_add_u64 v[6:7], v[6:7], 0, v[24:25]
	v_lshl_add_u64 v[6:7], v[6:7], 0, v[54:55]
	v_add_co_u32_e32 v6, vcc, 0x1000, v6
	v_cvt_pk_bf16_f32 v2, v11, v9
	v_cvt_pk_bf16_f32 v3, v13, v15
	v_cvt_pk_bf16_f32 v4, v17, v19
	v_cvt_pk_bf16_f32 v5, v21, v23
	v_addc_co_u32_e32 v7, vcc, 0, v7, vcc
	global_store_dwordx4 v[6:7], v[2:5], off sc1
	s_waitcnt lgkmcnt(0)

; #define LAS __attribute__((address_space(3)))
; DI unsigned cvtpk(float lo, float hi) { f32x2 v = {lo, hi}; bf16x2_t b = __builtin_convertvector(v, bf16x2_t); return __builtin_bit_cast(unsigned, b); }
; template <int KIND>
; DI void transpose_item(const float* W, int K, int N, bf16_t* WT, int ldk, const float* g0, const float* g1, const float* g2, LAS float* scr, int item, int lane) {
;     const int nblk = N / 32, kb = item / nblk, nb = item % nblk, k0 = 64 * kb, n0 = 32 * nb;
;     f32x4 tv[8];
; #pragma unroll
;     for (int i = 0; i < 8; ++i) tv[i] = *(const f32x4*)(W + (size_t)(k0 + 8 * i + (lane >> 3)) * N + n0 + 4 * (lane & 7));
; #pragma unroll
;     for (int i = 0; i < 8; ++i) {
;         const int kk = 8 * i + (lane >> 3), k = k0 + kk;
;         float gn = 1.f;
;         if (KIND == 0 || KIND == 1 || KIND == 2 || KIND == 5 || KIND == 6) gn = g0[k];
;         if (KIND == 4) gn = k < 1024 ? g0[k] : (k < 1536 ? g1[k - 1024] : g2[k - 1536]);
;         LAS float* d = scr + kk * 33 + 4 * (lane & 7);
;         d[0] = tv[i][0] * gn; d[1] = tv[i][1] * gn; d[2] = tv[i][2] * gn; d[3] = tv[i][3] * gn;
;     }
;     asm volatile("s_waitcnt lgkmcnt(0)" ::: "memory");
;     int kd0 = k0;
;     if (KIND == 4) kd0 = k0 < 1024 ? k0 + 512 : (k0 < 1536 ? k0 - 1024 : k0);
;     const int c = lane & 7;
; #pragma unroll
;     for (int j = 0; j < 4; ++j) { const int n = (lane >> 3) + 8 * j; const LAS float* s = scr + (8 * c) * 33 + n;
;         u32x4 o; o.x = cvtpk(s[0 * 33], s[1 * 33]); o.y = cvtpk(s[2 * 33], s[3 * 33]); o.z = cvtpk(s[4 * 33], s[5 * 33]); o.w = cvtpk(s[6 * 33], s[7 * 33]);
;         *(u32x4*)(WT + (size_t)map_n<KIND>(n0 + n) * ldk + kd0 + 8 * c) = o; }
;     asm volatile("s_waitcnt lgkmcnt(0)" ::: "memory");
.LBB0_64:
	s_andn2_saveexec_b64 s[12:13], s[8:9]
	s_cbranch_execz .LBB0_66
	v_add_u16_e32 v2, 0xe940, v1
	v_mul_u32_u24_e32 v3, 0xba2f, v2
	s_load_dwordx4 s[8:11], s[4:5], 0xa8
	v_lshrrev_b32_e32 v3, 23, v3
	v_mul_lo_u16_e32 v4, 0xb0, v3
	v_sub_u16_e32 v2, v2, v4
	v_lshlrev_b16_e32 v55, 6, v3
	v_lshlrev_b16_e32 v57, 5, v2
	v_or_b32_e32 v20, v34, v55
	v_lshlrev_b32_e32 v2, 2, v57
	v_mov_b32_e32 v3, v37
	s_waitcnt lgkmcnt(0)
	v_lshl_add_u64 v[2:3], s[10:11], 0, v[2:3]
	v_mul_u32_u24_e32 v4, 0x1600, v20
	v_lshl_add_u64 v[2:3], v[2:3], 0, v[36:37]
	v_lshlrev_b32_e32 v4, 2, v4
	v_mov_b32_e32 v5, v37
	v_lshl_add_u64 v[30:31], v[2:3], 0, v[4:5]
	v_add_co_u32_e32 v6, vcc, s73, v30
	v_lshlrev_b32_e32 v32, 2, v20
	s_nop 0
	v_addc_co_u32_e32 v7, vcc, 0, v31, vcc
	v_add_co_u32_e32 v10, vcc, s74, v30
	global_load_dwordx4 v[2:5], v[30:31], off nt
	s_nop 0
	global_load_dwordx4 v[6:9], v[6:7], off nt
	v_addc_co_u32_e32 v11, vcc, 0, v31, vcc
	v_add_co_u32_e32 v14, vcc, s75, v30
	v_add_u32_e32 v85, v35, v61
	s_nop 0
	v_addc_co_u32_e32 v15, vcc, 0, v31, vcc
	v_add_co_u32_e32 v18, vcc, s76, v30
	global_load_dwordx4 v[10:13], v[10:11], off nt
	s_nop 0
	global_load_dwordx4 v[14:17], v[14:15], off nt
	v_addc_co_u32_e32 v19, vcc, 0, v31, vcc
	v_add_co_u32_e32 v22, vcc, s77, v30
	global_load_dword v56, v32, s[8:9]
	s_nop 0
	v_addc_co_u32_e32 v23, vcc, 0, v31, vcc
	v_add_co_u32_e32 v26, vcc, s78, v30
	global_load_dwordx4 v[18:21], v[18:19], off nt
	s_nop 0
	global_load_dwordx4 v[22:25], v[22:23], off nt
	s_nop 0
	global_load_dword v84, v32, s[8:9] offset:32
	global_load_dword v86, v32, s[8:9] offset:64
	global_load_dword v88, v32, s[8:9] offset:96
	global_load_dword v90, v32, s[8:9] offset:128
	v_addc_co_u32_e32 v27, vcc, 0, v31, vcc
	v_add_co_u32_e32 v30, vcc, s79, v30
	global_load_dword v92, v32, s[8:9] offset:160
	s_nop 0
	global_load_dwordx4 v[26:29], v[26:27], off nt
	s_nop 0
	global_load_dword v94, v32, s[8:9] offset:192
	v_addc_co_u32_e32 v31, vcc, 0, v31, vcc
	global_load_dword v96, v32, s[8:9] offset:224
	s_nop 0
	global_load_dwordx4 v[30:33], v[30:31], off nt
	v_add_u32_e32 v87, 0x420, v85
	v_add_u32_e32 v89, 0x428, v85
	v_add_u32_e32 v91, 0x840, v85
	s_waitcnt vmcnt(11)
	v_pk_mul_f32 v[2:3], v[2:3], v[56:57] op_sel_hi:[1,0]
	v_pk_mul_f32 v[4:5], v[4:5], v[56:57] op_sel_hi:[1,0]
	ds_write2_b32 v65, v2, v3 offset1:1
	ds_write2_b32 v65, v4, v5 offset0:2 offset1:3
	s_waitcnt vmcnt(8)
	v_pk_mul_f32 v[2:3], v[6:7], v[84:85] op_sel_hi:[1,0]
	v_pk_mul_f32 v[4:5], v[8:9], v[84:85] op_sel_hi:[1,0]
	s_waitcnt vmcnt(7)
	v_pk_mul_f32 v[6:7], v[10:11], v[86:87] op_sel_hi:[1,0]
	v_pk_mul_f32 v[8:9], v[12:13], v[86:87] op_sel_hi:[1,0]
	s_waitcnt vmcnt(6)
	v_pk_mul_f32 v[10:11], v[14:15], v[88:89] op_sel_hi:[1,0]
	v_pk_mul_f32 v[12:13], v[16:17], v[88:89] op_sel_hi:[1,0]
	s_waitcnt vmcnt(5)
	v_pk_mul_f32 v[14:15], v[18:19], v[90:91] op_sel_hi:[1,0]
	v_pk_mul_f32 v[16:17], v[20:21], v[90:91] op_sel_hi:[1,0]
	s_waitcnt vmcnt(4)
	v_pk_mul_f32 v[18:19], v[22:23], v[92:93] op_sel_hi:[1,0]
	v_pk_mul_f32 v[20:21], v[24:25], v[92:93] op_sel_hi:[1,0]
	s_waitcnt vmcnt(2)
	v_pk_mul_f32 v[22:23], v[26:27], v[94:95] op_sel_hi:[1,0]
	v_pk_mul_f32 v[24:25], v[28:29], v[94:95] op_sel_hi:[1,0]
	ds_write2_b32 v66, v2, v3 offset1:1
	ds_write2_b32 v67, v4, v5 offset1:1
	ds_write2_b32 v68, v6, v7 offset1:1
	ds_write2_b32 v69, v8, v9 offset1:1
	ds_write2_b32 v70, v10, v11 offset1:1
	ds_write2_b32 v71, v12, v13 offset1:1
	ds_write2_b32 v85, v14, v15 offset1:1
	ds_write2_b32 v85, v16, v17 offset0:2 offset1:3
	ds_write2_b32 v87, v18, v19 offset1:1
	ds_write2_b32 v89, v20, v21 offset1:1
	ds_write2_b32 v91, v22, v23 offset1:1
	v_add_u32_e32 v2, 0x848, v85
	ds_write2_b32 v2, v24, v25 offset1:1
	s_waitcnt vmcnt(0)
	v_pk_mul_f32 v[2:3], v[30:31], v[96:97] op_sel_hi:[1,0]
	v_add_u32_e32 v4, 0xc60, v85
	ds_write2_b32 v4, v2, v3 offset1:1
	v_pk_mul_f32 v[2:3], v[32:33], v[96:97] op_sel_hi:[1,0]
	v_add_u32_e32 v4, 0xc68, v85
	ds_write2_b32 v4, v2, v3 offset1:1
	s_waitcnt lgkmcnt(0)
	ds_read2_b32 v[6:7], v60 offset0:33 offset1:41
	ds_read2_b32 v[8:9], v60 offset1:8
	ds_read2_b32 v[10:11], v60 offset0:66 offset1:74
	ds_read2_b32 v[12:13], v60 offset0:99 offset1:107
	ds_read2_b32 v[14:15], v60 offset0:132 offset1:140
	ds_read2_b32 v[16:17], v60 offset0:165 offset1:173
	ds_read2_b32 v[18:19], v60 offset0:198 offset1:206
	ds_read2_b32 v[20:21], v60 offset0:231 offset1:239
	v_lshlrev_b32_e32 v2, 1, v55
	v_mov_b32_e32 v3, v37
	v_lshl_add_u64 v[22:23], v[40:41], 0, v[2:3]
	s_waitcnt lgkmcnt(6)
	v_cvt_pk_bf16_f32 v2, v8, v6
	v_or_b32_e32 v6, v34, v57
	v_lshlrev_b32_e32 v24, 13, v6
	v_mov_b32_e32 v25, v37
	s_waitcnt lgkmcnt(4)
	v_cvt_pk_bf16_f32 v3, v10, v12
	s_waitcnt lgkmcnt(2)
	v_cvt_pk_bf16_f32 v4, v14, v16
	s_waitcnt lgkmcnt(0)
	v_cvt_pk_bf16_f32 v5, v18, v20
	v_lshl_add_u64 v[24:25], v[22:23], 0, v[24:25]
	global_store_dwordx4 v[24:25], v[2:5], off sc1
	v_or_b32_e32 v6, v53, v57
	v_lshlrev_b32_e32 v6, 13, v6
	v_cvt_pk_bf16_f32 v2, v9, v7
	v_cvt_pk_bf16_f32 v3, v11, v13
	v_cvt_pk_bf16_f32 v4, v15, v17
	v_cvt_pk_bf16_f32 v5, v19, v21
	ds_read2_b32 v[8:9], v60 offset0:49 offset1:57
	ds_read2_b32 v[10:11], v60 offset0:16 offset1:24
	ds_read2_b32 v[12:13], v60 offset0:82 offset1:90
	ds_read2_b32 v[14:15], v60 offset0:115 offset1:123
	ds_read2_b32 v[16:17], v60 offset0:148 offset1:156
	ds_read2_b32 v[18:19], v60 offset0:181 offset1:189
	ds_read2_b32 v[20:21], v60 offset0:214 offset1:222
	ds_read2_b32 v[24:25], v60 offset0:247 offset1:255
	v_mov_b32_e32 v7, v37
	v_lshl_add_u64 v[6:7], v[22:23], 0, v[6:7]
	global_store_dwordx4 v[6:7], v[2:5], off sc1
	v_or_b32_e32 v6, v58, v57
	v_lshlrev_b32_e32 v6, 13, v6
	v_mov_b32_e32 v7, v37
	s_waitcnt lgkmcnt(6)
	v_cvt_pk_bf16_f32 v2, v10, v8
	s_waitcnt lgkmcnt(4)
	v_cvt_pk_bf16_f32 v3, v12, v14
	s_waitcnt lgkmcnt(2)
	v_cvt_pk_bf16_f32 v4, v16, v18
	s_waitcnt lgkmcnt(0)
	v_cvt_pk_bf16_f32 v5, v20, v24
	v_lshl_add_u64 v[6:7], v[22:23], 0, v[6:7]
	global_store_dwordx4 v[6:7], v[2:5], off sc1
	v_or_b32_e32 v6, v59, v57
	v_lshlrev_b32_e32 v6, 13, v6
	v_mov_b32_e32 v7, v37
	v_cvt_pk_bf16_f32 v2, v11, v9
	v_cvt_pk_bf16_f32 v3, v13, v15
	v_cvt_pk_bf16_f32 v4, v17, v19
	v_cvt_pk_bf16_f32 v5, v21, v25
	v_lshl_add_u64 v[6:7], v[22:23], 0, v[6:7]
	global_store_dwordx4 v[6:7], v[2:5], off sc1
	s_waitcnt lgkmcnt(0)

; #define LAS __attribute__((address_space(3)))
; DI unsigned cvtpk(float lo, float hi) { f32x2 v = {lo, hi}; bf16x2_t b = __builtin_convertvector(v, bf16x2_t); return __builtin_bit_cast(unsigned, b); }
; template <int KIND>
; DI void transpose_item(const float* W, int K, int N, bf16_t* WT, int ldk, const float* g0, const float* g1, const float* g2, LAS float* scr, int item, int lane) {
;     ...
;         if (KIND == 0 || KIND == 1 || KIND == 2 || KIND == 5 || KIND == 6) gn = g0[k];
;         if (KIND == 4) gn = k < 1024 ? g0[k] : (k < 1536 ? g1[k - 1024] : g2[k - 1536]);
;         LAS float* d = scr + kk * 33 + 4 * (lane & 7);
;         d[0] = tv[i][0] * gn; d[1] = tv[i][1] * gn; d[2] = tv[i][2] * gn; d[3] = tv[i][3] * gn;
;     }
;     asm volatile("s_waitcnt lgkmcnt(0)" ::: "memory");
;     int kd0 = k0;
;     if (KIND == 4) kd0 = k0 < 1024 ? k0 + 512 : (k0 < 1536 ? k0 - 1024 : k0);
;     const int c = lane & 7;
; #pragma unroll
;     for (int j = 0; j < 4; ++j) { const int n = (lane >> 3) + 8 * j; const LAS float* s = scr + (8 * c) * 33 + n;
;         u32x4 o; o.x = cvtpk(s[0 * 33], s[1 * 33]); o.y = cvtpk(s[2 * 33], s[3 * 33]); o.z = cvtpk(s[4 * 33], s[5 * 33]); o.w = cvtpk(s[6 * 33], s[7 * 33]);
;         *(u32x4*)(WT + (size_t)map_n<KIND>(n0 + n) * ldk + kd0 + 8 * c) = o; }
;     asm volatile("s_waitcnt lgkmcnt(0)" ::: "memory");
.LBB0_130:
	s_andn2_saveexec_b64 s[6:7], s[8:9]
	v_mov_b32_e32 v31, v37
	v_lshl_add_u64 v[6:7], s[12:13], 0, v[30:31]
	v_lshl_add_u64 v[6:7], v[6:7], 0, s[54:55]
	s_or_b64 exec, exec, s[6:7]
	global_load_dword v6, v[6:7], off
	s_movk_i32 s6, 0x600
	v_add_u32_e32 v7, 0xc60, v18
	v_add_u32_e32 v10, 0xfffffc00, v84
	v_cmp_gt_u32_e64 s[6:7], s6, v55
	v_add_u32_e32 v8, 0x200, v84
	v_add_u32_e32 v26, 0xc68, v18
	v_cndmask_b32_e64 v19, v84, v10, s[6:7]
	v_mov_b32_e32 v9, v37
	v_or_b32_e32 v12, v85, v34
	v_or_b32_e32 v14, v85, v53
	v_or_b32_e32 v16, v85, v58
	v_or_b32_e32 v18, v85, v59
	v_cndmask_b32_e32 v8, v19, v8, vcc
	v_mov_b32_e32 v11, v37
	v_mov_b32_e32 v13, v37
	v_mov_b32_e32 v15, v37
	v_mov_b32_e32 v17, v37
	v_lshlrev_b32_e32 v10, 12, v12
	v_lshlrev_b32_e32 v12, 12, v14
	v_lshlrev_b32_e32 v14, 12, v16
	v_lshlrev_b32_e32 v16, 12, v18
	v_lshl_add_u64 v[8:9], v[8:9], 1, v[42:43]
	v_lshl_add_u64 v[18:19], v[8:9], 0, v[10:11]
	v_lshl_add_u64 v[20:21], v[8:9], 0, v[12:13]
	v_lshl_add_u64 v[22:23], v[8:9], 0, v[14:15]
	v_lshl_add_u64 v[24:25], v[8:9], 0, v[16:17]
	s_waitcnt vmcnt(0)
	v_pk_mul_f32 v[2:3], v[2:3], v[6:7] op_sel_hi:[1,0]
	v_pk_mul_f32 v[4:5], v[4:5], v[6:7] op_sel_hi:[1,0]
	ds_write2_b32 v7, v2, v3 offset1:1
	ds_write2_b32 v26, v4, v5 offset1:1
	s_waitcnt lgkmcnt(0)
	ds_read2_b32 v[6:7], v60 offset0:33 offset1:41
	ds_read2_b32 v[8:9], v60 offset1:8
	ds_read2_b32 v[10:11], v60 offset0:66 offset1:74
	ds_read2_b32 v[12:13], v60 offset0:99 offset1:107
	ds_read2_b32 v[14:15], v60 offset0:132 offset1:140
	ds_read2_b32 v[16:17], v60 offset0:165 offset1:173
	ds_read2_b32 v[26:27], v60 offset0:198 offset1:206
	ds_read2_b32 v[28:29], v60 offset0:231 offset1:239
	ds_read2_b32 v[30:31], v60 offset0:49 offset1:57
	ds_read2_b32 v[32:33], v60 offset0:16 offset1:24
	ds_read2_b32 v[56:57], v60 offset0:82 offset1:90
	ds_read2_b32 v[84:85], v60 offset0:115 offset1:123
	ds_read2_b32 v[86:87], v60 offset0:148 offset1:156
	ds_read2_b32 v[88:89], v60 offset0:181 offset1:189
	ds_read2_b32 v[90:91], v60 offset0:214 offset1:222
	ds_read2_b32 v[92:93], v60 offset0:247 offset1:255
	s_waitcnt lgkmcnt(14)
	v_cvt_pk_bf16_f32 v2, v8, v6
	s_waitcnt lgkmcnt(12)
	v_cvt_pk_bf16_f32 v3, v10, v12
	s_waitcnt lgkmcnt(10)
	v_cvt_pk_bf16_f32 v4, v14, v16
	s_waitcnt lgkmcnt(8)
	v_cvt_pk_bf16_f32 v5, v26, v28
	v_cvt_pk_bf16_f32 v6, v9, v7
	v_cvt_pk_bf16_f32 v7, v11, v13
	v_cvt_pk_bf16_f32 v8, v15, v17
	v_cvt_pk_bf16_f32 v9, v27, v29
	s_waitcnt lgkmcnt(6)
	v_cvt_pk_bf16_f32 v10, v32, v30
	s_waitcnt lgkmcnt(4)
	v_cvt_pk_bf16_f32 v11, v56, v84
	s_waitcnt lgkmcnt(2)
	v_cvt_pk_bf16_f32 v12, v86, v88
	s_waitcnt lgkmcnt(0)
	v_cvt_pk_bf16_f32 v13, v90, v92
	v_cvt_pk_bf16_f32 v14, v33, v31
	v_cvt_pk_bf16_f32 v15, v57, v85
	v_cvt_pk_bf16_f32 v16, v87, v89
	v_cvt_pk_bf16_f32 v17, v91, v93
	global_store_dwordx4 v[18:19], v[2:5], off sc1
	global_store_dwordx4 v[20:21], v[6:9], off sc1
	global_store_dwordx4 v[22:23], v[10:13], off sc1
	global_store_dwordx4 v[24:25], v[14:17], off sc1
	s_waitcnt lgkmcnt(0)

; #define LAS __attribute__((address_space(3)))
; DI unsigned cvtpk(float lo, float hi) { f32x2 v = {lo, hi}; bf16x2_t b = __builtin_convertvector(v, bf16x2_t); return __builtin_bit_cast(unsigned, b); }
; template <int KIND>
; DI void transpose_item(const float* W, int K, int N, bf16_t* WT, int ldk, const float* g0, const float* g1, const float* g2, LAS float* scr, int item, int lane) {
;     const int nblk = N / 32, kb = item / nblk, nb = item % nblk, k0 = 64 * kb, n0 = 32 * nb;
;     f32x4 tv[8];
; #pragma unroll
;     for (int i = 0; i < 8; ++i) tv[i] = *(const f32x4*)(W + (size_t)(k0 + 8 * i + (lane >> 3)) * N + n0 + 4 * (lane & 7));
; #pragma unroll
;     for (int i = 0; i < 8; ++i) {
;         const int kk = 8 * i + (lane >> 3), k = k0 + kk;
;         float gn = 1.f;
;         if (KIND == 0 || KIND == 1 || KIND == 2 || KIND == 5 || KIND == 6) gn = g0[k];
;         if (KIND == 4) gn = k < 1024 ? g0[k] : (k < 1536 ? g1[k - 1024] : g2[k - 1536]);
;         LAS float* d = scr + kk * 33 + 4 * (lane & 7);
;         d[0] = tv[i][0] * gn; d[1] = tv[i][1] * gn; d[2] = tv[i][2] * gn; d[3] = tv[i][3] * gn;
;     }
;     asm volatile("s_waitcnt lgkmcnt(0)" ::: "memory");
;     int kd0 = k0;
;     if (KIND == 4) kd0 = k0 < 1024 ? k0 + 512 : (k0 < 1536 ? k0 - 1024 : k0);
;     const int c = lane & 7;
; #pragma unroll
;     for (int j = 0; j < 4; ++j) { const int n = (lane >> 3) + 8 * j; const LAS float* s = scr + (8 * c) * 33 + n;
;         u32x4 o; o.x = cvtpk(s[0 * 33], s[1 * 33]); o.y = cvtpk(s[2 * 33], s[3 * 33]); o.z = cvtpk(s[4 * 33], s[5 * 33]); o.w = cvtpk(s[6 * 33], s[7 * 33]);
;         *(u32x4*)(WT + (size_t)map_n<KIND>(n0 + n) * ldk + kd0 + 8 * c) = o; }
;     asm volatile("s_waitcnt lgkmcnt(0)" ::: "memory");
.LBB0_134:
	s_andn2_saveexec_b64 s[8:9], s[62:63]
	s_cbranch_execz .LBB0_136
	s_load_dwordx2 s[6:7], s[4:5], 0x78
	v_add_u32_e32 v2, 0xfffe4800, v52
	v_and_b32_e32 v88, 0x3e0, v2
	v_and_b32_e32 v55, 0x1c0, v64
	v_lshlrev_b32_e32 v2, 2, v88
	v_mov_b32_e32 v3, v37
	v_or_b32_e32 v4, v55, v34
	s_waitcnt lgkmcnt(0)
	v_lshl_add_u64 v[2:3], s[6:7], 0, v[2:3]
	v_lshl_add_u64 v[2:3], v[2:3], 0, v[36:37]
	v_lshlrev_b32_e32 v4, 12, v4
	v_mov_b32_e32 v5, v37
	v_lshl_add_u64 v[30:31], v[2:3], 0, v[4:5]
	s_mov_b32 s6, 0x8000
	v_add_co_u32_e32 v6, vcc, s6, v30
	s_mov_b32 s6, 0x28000
	s_nop 0
	v_addc_co_u32_e32 v7, vcc, 0, v31, vcc
	v_add_co_u32_e32 v10, vcc, s66, v30
	global_load_dwordx4 v[2:5], v[30:31], off nt
	s_nop 0
	global_load_dwordx4 v[6:9], v[6:7], off nt
	v_addc_co_u32_e32 v11, vcc, 0, v31, vcc
	v_add_co_u32_e32 v14, vcc, s82, v30
	v_lshlrev_b32_e32 v56, 1, v55
	s_nop 0
	v_addc_co_u32_e32 v15, vcc, 0, v31, vcc
	global_load_dwordx4 v[10:13], v[10:11], off nt
	s_nop 0
	global_load_dwordx4 v[14:17], v[14:15], off nt
	v_add_co_u32_e32 v18, vcc, s67, v30
	v_or_b32_e32 v55, v88, v34
	s_nop 0
	v_addc_co_u32_e32 v19, vcc, 0, v31, vcc
	global_load_dwordx4 v[18:21], v[18:19], off nt
	v_add_co_u32_e32 v26, vcc, s6, v30
	v_add_co_u32_e64 v22, s[6:7], s68, v30
	s_nop 0
	v_addc_co_u32_e32 v27, vcc, 0, v31, vcc
	v_addc_co_u32_e64 v23, s[6:7], 0, v31, s[6:7]
	global_load_dwordx4 v[22:25], v[22:23], off nt
	s_mov_b32 s6, 0x38000
	global_load_dwordx4 v[26:29], v[26:27], off nt
	v_add_co_u32_e32 v30, vcc, s6, v30
	s_movk_i32 s6, 0x200
	s_nop 0
	v_addc_co_u32_e32 v31, vcc, 0, v31, vcc
	global_load_dwordx4 v[30:33], v[30:31], off nt
	v_or_b32_e32 v84, v88, v53
	v_lshlrev_b32_e32 v55, 1, v55
	v_lshlrev_b32_e32 v85, 1, v84
	v_add_u32_e32 v84, 0xfffffc01, v55
	v_cmp_gt_u32_e32 vcc, s6, v88
	v_add_u32_e32 v86, 0xfffffc01, v85
	v_mov_b32_e32 v57, v37
	v_cndmask_b32_e32 v84, v84, v55, vcc
	v_cndmask_b32_e32 v86, v86, v85, vcc
	v_ashrrev_i32_e32 v85, 31, v84
	v_lshl_add_u64 v[56:57], v[44:45], 0, v[56:57]
	v_lshlrev_b64 v[84:85], 10, v[84:85]
	v_ashrrev_i32_e32 v87, 31, v86
	s_waitcnt vmcnt(7)
	ds_write2_b32 v65, v2, v3 offset1:1
	ds_write2_b32 v65, v4, v5 offset0:2 offset1:3
	s_waitcnt vmcnt(5)
	ds_write2_b32 v68, v10, v11 offset1:1
	ds_write2_b32 v69, v12, v13 offset1:1
	s_waitcnt vmcnt(3)
	ds_write2_b32 v72, v18, v19 offset1:1
	ds_write2_b32 v73, v20, v21 offset1:1
	s_waitcnt vmcnt(2)
	ds_write2_b32 v76, v22, v23 offset1:1
	ds_write2_b32 v77, v24, v25 offset1:1
	ds_write2_b32 v66, v6, v7 offset1:1
	ds_write2_b32 v67, v8, v9 offset1:1
	ds_write2_b32 v70, v14, v15 offset1:1
	ds_write2_b32 v71, v16, v17 offset1:1
	s_waitcnt vmcnt(1)
	ds_write2_b32 v74, v26, v27 offset1:1
	ds_write2_b32 v75, v28, v29 offset1:1
	s_waitcnt vmcnt(0)
	ds_write2_b32 v78, v30, v31 offset1:1
	ds_write2_b32 v79, v32, v33 offset1:1
	s_waitcnt lgkmcnt(0)
	ds_read2_b32 v[6:7], v60 offset0:33 offset1:41
	ds_read2_b32 v[8:9], v60 offset1:8
	ds_read2_b32 v[10:11], v60 offset0:66 offset1:74
	ds_read2_b32 v[12:13], v60 offset0:99 offset1:107
	ds_read2_b32 v[14:15], v60 offset0:132 offset1:140
	ds_read2_b32 v[16:17], v60 offset0:165 offset1:173
	ds_read2_b32 v[18:19], v60 offset0:198 offset1:206
	ds_read2_b32 v[20:21], v60 offset0:231 offset1:239
	v_lshl_add_u64 v[22:23], v[56:57], 0, v[84:85]
	s_waitcnt lgkmcnt(6)
	v_cvt_pk_bf16_f32 v2, v8, v6
	s_waitcnt lgkmcnt(4)
	v_cvt_pk_bf16_f32 v3, v10, v12
	s_waitcnt lgkmcnt(2)
	v_cvt_pk_bf16_f32 v4, v14, v16
	s_waitcnt lgkmcnt(0)
	v_cvt_pk_bf16_f32 v5, v18, v20
	global_store_dwordx4 v[22:23], v[2:5], off sc1
	v_cvt_pk_bf16_f32 v6, v9, v7
	v_cvt_pk_bf16_f32 v7, v11, v13
	v_lshlrev_b64 v[2:3], 10, v[86:87]
	v_cvt_pk_bf16_f32 v8, v15, v17
	v_cvt_pk_bf16_f32 v9, v19, v21
	v_lshl_add_u64 v[2:3], v[56:57], 0, v[2:3]
	ds_read2_b32 v[10:11], v60 offset0:49 offset1:57
	ds_read2_b32 v[12:13], v60 offset0:16 offset1:24
	ds_read2_b32 v[14:15], v60 offset0:82 offset1:90
	ds_read2_b32 v[16:17], v60 offset0:115 offset1:123
	ds_read2_b32 v[18:19], v60 offset0:148 offset1:156
	ds_read2_b32 v[20:21], v60 offset0:181 offset1:189
	ds_read2_b32 v[22:23], v60 offset0:214 offset1:222
	ds_read2_b32 v[24:25], v60 offset0:247 offset1:255
	global_store_dwordx4 v[2:3], v[6:9], off sc1
	s_waitcnt lgkmcnt(6)
	v_cvt_pk_bf16_f32 v2, v12, v10
	s_waitcnt lgkmcnt(4)
	v_cvt_pk_bf16_f32 v3, v14, v16
	v_or_b32_e32 v6, v88, v58
	v_lshlrev_b32_e32 v6, 1, v6
	v_add_u32_e32 v7, 0xfffffc01, v6
	v_cndmask_b32_e32 v6, v7, v6, vcc
	v_ashrrev_i32_e32 v7, 31, v6
	v_lshlrev_b64 v[6:7], 10, v[6:7]
	s_waitcnt lgkmcnt(2)
	v_cvt_pk_bf16_f32 v4, v18, v20
	s_waitcnt lgkmcnt(0)
	v_cvt_pk_bf16_f32 v5, v22, v24
	v_lshl_add_u64 v[6:7], v[56:57], 0, v[6:7]
	global_store_dwordx4 v[6:7], v[2:5], off sc1
	v_or_b32_e32 v6, v88, v59
	v_lshlrev_b32_e32 v6, 1, v6
	v_add_u32_e32 v7, 0xfffffc01, v6
	v_cndmask_b32_e32 v6, v7, v6, vcc
	v_ashrrev_i32_e32 v7, 31, v6
	v_lshlrev_b64 v[6:7], 10, v[6:7]
	v_cvt_pk_bf16_f32 v2, v13, v11
	v_cvt_pk_bf16_f32 v3, v15, v17
	v_cvt_pk_bf16_f32 v4, v19, v21
	v_cvt_pk_bf16_f32 v5, v23, v25
	v_lshl_add_u64 v[6:7], v[56:57], 0, v[6:7]
	global_store_dwordx4 v[6:7], v[2:5], off sc1
	s_waitcnt lgkmcnt(0)

; #define LAS __attribute__((address_space(3)))
; DI unsigned cvtpk(float lo, float hi) { f32x2 v = {lo, hi}; bf16x2_t b = __builtin_convertvector(v, bf16x2_t); return __builtin_bit_cast(unsigned, b); }
; template <int KIND>
; DI void transpose_item(const float* W, int K, int N, bf16_t* WT, int ldk, const float* g0, const float* g1, const float* g2, LAS float* scr, int item, int lane) {
;     const int nblk = N / 32, kb = item / nblk, nb = item % nblk, k0 = 64 * kb, n0 = 32 * nb;
;     f32x4 tv[8];
; #pragma unroll
;     for (int i = 0; i < 8; ++i) tv[i] = *(const f32x4*)(W + (size_t)(k0 + 8 * i + (lane >> 3)) * N + n0 + 4 * (lane & 7));
; #pragma unroll
;     for (int i = 0; i < 8; ++i) {
;         const int kk = 8 * i + (lane >> 3), k = k0 + kk;
;         float gn = 1.f;
;         if (KIND == 0 || KIND == 1 || KIND == 2 || KIND == 5 || KIND == 6) gn = g0[k];
;         if (KIND == 4) gn = k < 1024 ? g0[k] : (k < 1536 ? g1[k - 1024] : g2[k - 1536]);
;         LAS float* d = scr + kk * 33 + 4 * (lane & 7);
;         d[0] = tv[i][0] * gn; d[1] = tv[i][1] * gn; d[2] = tv[i][2] * gn; d[3] = tv[i][3] * gn;
;     }
;     asm volatile("s_waitcnt lgkmcnt(0)" ::: "memory");
;     int kd0 = k0;
;     if (KIND == 4) kd0 = k0 < 1024 ? k0 + 512 : (k0 < 1536 ? k0 - 1024 : k0);
;     const int c = lane & 7;
; #pragma unroll
;     for (int j = 0; j < 4; ++j) { const int n = (lane >> 3) + 8 * j; const LAS float* s = scr + (8 * c) * 33 + n;
;         u32x4 o; o.x = cvtpk(s[0 * 33], s[1 * 33]); o.y = cvtpk(s[2 * 33], s[3 * 33]); o.z = cvtpk(s[4 * 33], s[5 * 33]); o.w = cvtpk(s[6 * 33], s[7 * 33]);
;         *(u32x4*)(WT + (size_t)map_n<KIND>(n0 + n) * ldk + kd0 + 8 * c) = o; }
;     asm volatile("s_waitcnt lgkmcnt(0)" ::: "memory");
.LBB0_137:
	s_andn2_saveexec_b64 s[6:7], s[60:61]
	s_cbranch_execz .LBB0_139
	s_load_dwordx4 s[8:11], s[4:5], 0x28
	v_add_u32_e32 v2, 0xfffff340, v1
	v_and_b32_e32 v55, 0xc0, v2
	v_add_u32_e32 v2, 0xfffe6800, v52
	v_and_b32_e32 v57, 0x7e0, v2
	v_lshlrev_b32_e32 v2, 2, v57
	v_mov_b32_e32 v3, v37
	v_or_b32_e32 v20, v55, v34
	s_waitcnt lgkmcnt(0)
	v_lshl_add_u64 v[2:3], s[10:11], 0, v[2:3]
	v_lshl_add_u64 v[2:3], v[2:3], 0, v[36:37]
	v_lshlrev_b32_e32 v4, 13, v20
	v_mov_b32_e32 v5, v37
	v_lshl_add_u64 v[30:31], v[2:3], 0, v[4:5]
	v_add_co_u32_e32 v6, vcc, s66, v30
	v_lshlrev_b32_e32 v32, 2, v20
	s_nop 0
	v_addc_co_u32_e32 v7, vcc, 0, v31, vcc
	v_add_co_u32_e32 v10, vcc, s67, v30
	global_load_dwordx4 v[2:5], v[30:31], off nt
	s_nop 0
	global_load_dwordx4 v[6:9], v[6:7], off nt
	v_addc_co_u32_e32 v11, vcc, 0, v31, vcc
	v_add_co_u32_e32 v14, vcc, s68, v30
	v_add_u32_e32 v85, v35, v61
	s_nop 0
	v_addc_co_u32_e32 v15, vcc, 0, v31, vcc
	v_add_co_u32_e32 v18, vcc, s69, v30
	global_load_dwordx4 v[10:13], v[10:11], off nt
	s_nop 0
	global_load_dwordx4 v[14:17], v[14:15], off nt
	v_addc_co_u32_e32 v19, vcc, 0, v31, vcc
	v_add_co_u32_e32 v22, vcc, s70, v30
	global_load_dword v56, v32, s[8:9]
	s_nop 0
	v_addc_co_u32_e32 v23, vcc, 0, v31, vcc
	v_add_co_u32_e32 v26, vcc, s71, v30
	global_load_dwordx4 v[18:21], v[18:19], off nt
	s_nop 0
	global_load_dwordx4 v[22:25], v[22:23], off nt
	s_nop 0
	global_load_dword v84, v32, s[8:9] offset:32
	global_load_dword v86, v32, s[8:9] offset:64
	global_load_dword v88, v32, s[8:9] offset:96
	global_load_dword v90, v32, s[8:9] offset:128
	v_addc_co_u32_e32 v27, vcc, 0, v31, vcc
	v_add_co_u32_e32 v30, vcc, s72, v30
	global_load_dword v92, v32, s[8:9] offset:160
	s_nop 0
	global_load_dwordx4 v[26:29], v[26:27], off nt
	s_nop 0
	global_load_dword v94, v32, s[8:9] offset:192
	v_addc_co_u32_e32 v31, vcc, 0, v31, vcc
	global_load_dword v96, v32, s[8:9] offset:224
	s_nop 0
	global_load_dwordx4 v[30:33], v[30:31], off nt
	v_add_u32_e32 v87, 0x420, v85
	v_add_u32_e32 v89, 0x428, v85
	v_add_u32_e32 v91, 0x840, v85
	v_add_u32_e32 v93, 0x848, v85
	s_waitcnt vmcnt(11)
	v_pk_mul_f32 v[2:3], v[2:3], v[56:57] op_sel_hi:[1,0]
	v_pk_mul_f32 v[4:5], v[4:5], v[56:57] op_sel_hi:[1,0]
	ds_write2_b32 v65, v2, v3 offset1:1
	ds_write2_b32 v65, v4, v5 offset0:2 offset1:3
	s_waitcnt vmcnt(8)
	v_pk_mul_f32 v[2:3], v[6:7], v[84:85] op_sel_hi:[1,0]
	v_pk_mul_f32 v[4:5], v[8:9], v[84:85] op_sel_hi:[1,0]
	s_waitcnt vmcnt(7)
	v_pk_mul_f32 v[6:7], v[10:11], v[86:87] op_sel_hi:[1,0]
	v_pk_mul_f32 v[8:9], v[12:13], v[86:87] op_sel_hi:[1,0]
	s_waitcnt vmcnt(6)
	v_pk_mul_f32 v[10:11], v[14:15], v[88:89] op_sel_hi:[1,0]
	v_pk_mul_f32 v[12:13], v[16:17], v[88:89] op_sel_hi:[1,0]
	s_waitcnt vmcnt(5)
	v_pk_mul_f32 v[14:15], v[18:19], v[90:91] op_sel_hi:[1,0]
	v_pk_mul_f32 v[16:17], v[20:21], v[90:91] op_sel_hi:[1,0]
	s_waitcnt vmcnt(4)
	v_pk_mul_f32 v[18:19], v[22:23], v[92:93] op_sel_hi:[1,0]
	v_pk_mul_f32 v[20:21], v[24:25], v[92:93] op_sel_hi:[1,0]
	s_waitcnt vmcnt(2)
	v_pk_mul_f32 v[22:23], v[26:27], v[94:95] op_sel_hi:[1,0]
	v_pk_mul_f32 v[24:25], v[28:29], v[94:95] op_sel_hi:[1,0]
	ds_write2_b32 v66, v2, v3 offset1:1
	ds_write2_b32 v67, v4, v5 offset1:1
	ds_write2_b32 v68, v6, v7 offset1:1
	ds_write2_b32 v69, v8, v9 offset1:1
	ds_write2_b32 v70, v10, v11 offset1:1
	ds_write2_b32 v71, v12, v13 offset1:1
	ds_write2_b32 v85, v14, v15 offset1:1
	ds_write2_b32 v85, v16, v17 offset0:2 offset1:3
	ds_write2_b32 v87, v18, v19 offset1:1
	ds_write2_b32 v89, v20, v21 offset1:1
	ds_write2_b32 v91, v22, v23 offset1:1
	ds_write2_b32 v93, v24, v25 offset1:1
	s_waitcnt vmcnt(0)
	v_pk_mul_f32 v[2:3], v[30:31], v[96:97] op_sel_hi:[1,0]
	v_add_u32_e32 v4, 0xc60, v85
	ds_write2_b32 v4, v2, v3 offset1:1
	v_pk_mul_f32 v[2:3], v[32:33], v[96:97] op_sel_hi:[1,0]
	v_add_u32_e32 v4, 0xc68, v85
	ds_write2_b32 v4, v2, v3 offset1:1
	s_waitcnt lgkmcnt(0)
	ds_read2_b32 v[6:7], v60 offset0:33 offset1:41
	ds_read2_b32 v[8:9], v60 offset1:8
	ds_read2_b32 v[10:11], v60 offset0:66 offset1:74
	ds_read2_b32 v[12:13], v60 offset0:99 offset1:107
	ds_read2_b32 v[14:15], v60 offset0:132 offset1:140
	ds_read2_b32 v[16:17], v60 offset0:165 offset1:173
	ds_read2_b32 v[18:19], v60 offset0:198 offset1:206
	ds_read2_b32 v[20:21], v60 offset0:231 offset1:239
	v_lshlrev_b32_e32 v2, 1, v55
	v_mov_b32_e32 v3, v37
	v_lshl_add_u64 v[22:23], v[46:47], 0, v[2:3]
	s_waitcnt lgkmcnt(6)
	v_cvt_pk_bf16_f32 v2, v8, v6
	v_or_b32_e32 v6, v57, v34
	v_lshlrev_b32_e32 v24, 9, v6
	v_mov_b32_e32 v25, v37
	s_waitcnt lgkmcnt(4)
	v_cvt_pk_bf16_f32 v3, v10, v12
	s_waitcnt lgkmcnt(2)
	v_cvt_pk_bf16_f32 v4, v14, v16
	s_waitcnt lgkmcnt(0)
	v_cvt_pk_bf16_f32 v5, v18, v20
	v_lshl_add_u64 v[24:25], v[22:23], 0, v[24:25]
	global_store_dwordx4 v[24:25], v[2:5], off sc1
	v_or_b32_e32 v6, v57, v53
	v_lshlrev_b32_e32 v6, 9, v6
	v_cvt_pk_bf16_f32 v2, v9, v7
	v_cvt_pk_bf16_f32 v3, v11, v13
	v_cvt_pk_bf16_f32 v4, v15, v17
	v_cvt_pk_bf16_f32 v5, v19, v21
	ds_read2_b32 v[8:9], v60 offset0:49 offset1:57
	ds_read2_b32 v[10:11], v60 offset0:16 offset1:24
	ds_read2_b32 v[12:13], v60 offset0:82 offset1:90
	ds_read2_b32 v[14:15], v60 offset0:115 offset1:123
	ds_read2_b32 v[16:17], v60 offset0:148 offset1:156
	ds_read2_b32 v[18:19], v60 offset0:181 offset1:189
	ds_read2_b32 v[20:21], v60 offset0:214 offset1:222
	ds_read2_b32 v[24:25], v60 offset0:247 offset1:255
	v_mov_b32_e32 v7, v37
	v_lshl_add_u64 v[6:7], v[22:23], 0, v[6:7]
	global_store_dwordx4 v[6:7], v[2:5], off sc1
	v_or_b32_e32 v6, v57, v58
	v_lshlrev_b32_e32 v6, 9, v6
	v_mov_b32_e32 v7, v37
	s_waitcnt lgkmcnt(6)
	v_cvt_pk_bf16_f32 v2, v10, v8
	s_waitcnt lgkmcnt(4)
	v_cvt_pk_bf16_f32 v3, v12, v14
	s_waitcnt lgkmcnt(2)
	v_cvt_pk_bf16_f32 v4, v16, v18
	s_waitcnt lgkmcnt(0)
	v_cvt_pk_bf16_f32 v5, v20, v24
	v_lshl_add_u64 v[6:7], v[22:23], 0, v[6:7]
	global_store_dwordx4 v[6:7], v[2:5], off sc1
	v_or_b32_e32 v6, v57, v59
	v_lshlrev_b32_e32 v6, 9, v6
	v_mov_b32_e32 v7, v37
	v_cvt_pk_bf16_f32 v2, v11, v9
	v_cvt_pk_bf16_f32 v3, v13, v15
	v_cvt_pk_bf16_f32 v4, v17, v19
	v_cvt_pk_bf16_f32 v5, v21, v25
	v_lshl_add_u64 v[6:7], v[22:23], 0, v[6:7]
	global_store_dwordx4 v[6:7], v[2:5], off sc1
	s_waitcnt lgkmcnt(0)

; #define LAS __attribute__((address_space(3)))
; template <int KIND>
; DI void transpose_item(const float* W, int K, int N, bf16_t* WT, int ldk, const float* g0, const float* g1, const float* g2, LAS float* scr, int item, int lane) {
;     const int nblk = N / 32, kb = item / nblk, nb = item % nblk, k0 = 64 * kb, n0 = 32 * nb;
;     f32x4 tv[8];
; #pragma unroll
;     for (int i = 0; i < 8; ++i) tv[i] = *(const f32x4*)(W + (size_t)(k0 + 8 * i + (lane >> 3)) * N + n0 + 4 * (lane & 7));
; #pragma unroll
;     for (int i = 0; i < 8; ++i) {
;         const int kk = 8 * i + (lane >> 3), k = k0 + kk;
;         float gn = 1.f;
;         if (KIND == 0 || KIND == 1 || KIND == 2 || KIND == 5 || KIND == 6) gn = g0[k];
;         if (KIND == 4) gn = k < 1024 ? g0[k] : (k < 1536 ? g1[k - 1024] : g2[k - 1536]);
;         LAS float* d = scr + kk * 33 + 4 * (lane & 7);
;         d[0] = tv[i][0] * gn; d[1] = tv[i][1] * gn; d[2] = tv[i][2] * gn; d[3] = tv[i][3] * gn;
;     }
;     asm volatile("s_waitcnt lgkmcnt(0)" ::: "memory");
.LBB0_140:
	s_andn2_saveexec_b64 s[6:7], s[58:59]
	s_cbranch_execz .LBB0_142
	v_add_u16_e32 v2, 0xf4c0, v1
	v_mul_u32_u24_e32 v3, 0xaaab, v2
	s_load_dwordx4 s[8:11], s[4:5], 0x18
	v_lshrrev_b32_e32 v3, 21, v3
	v_mul_lo_u16_e32 v4, 48, v3
	v_sub_u16_e32 v2, v2, v4
	v_lshlrev_b16_e32 v55, 6, v3
	v_lshlrev_b16_e32 v57, 5, v2
	v_or_b32_e32 v20, v34, v55
	v_lshlrev_b32_e32 v2, 2, v57
	v_mov_b32_e32 v3, v37
	s_waitcnt lgkmcnt(0)
	v_lshl_add_u64 v[2:3], s[10:11], 0, v[2:3]
	v_mul_u32_u24_e32 v4, 0x600, v20
	v_lshl_add_u64 v[2:3], v[2:3], 0, v[36:37]
	v_lshlrev_b32_e32 v4, 2, v4
	v_mov_b32_e32 v5, v37
	v_lshl_add_u64 v[30:31], v[2:3], 0, v[4:5]
	s_mov_b32 s10, 0xc000
	v_add_co_u32_e32 v6, vcc, s10, v30
	s_mov_b32 s10, 0x24000
	s_nop 0
	v_addc_co_u32_e32 v7, vcc, 0, v31, vcc
	v_add_co_u32_e32 v10, vcc, s82, v30
	v_lshlrev_b32_e32 v32, 2, v20
	s_nop 0
	v_addc_co_u32_e32 v11, vcc, 0, v31, vcc
	v_add_co_u32_e32 v14, vcc, s10, v30
	s_mov_b32 s10, 0x3c000
	s_nop 0
	v_addc_co_u32_e32 v15, vcc, 0, v31, vcc
	v_add_co_u32_e32 v18, vcc, s68, v30
	global_load_dwordx4 v[2:5], v[30:31], off nt
	s_nop 0
	global_load_dwordx4 v[6:9], v[6:7], off nt
	v_addc_co_u32_e32 v19, vcc, 0, v31, vcc
	v_add_co_u32_e32 v22, vcc, s10, v30
	s_mov_b32 s10, 0x48000
	s_nop 0
	v_addc_co_u32_e32 v23, vcc, 0, v31, vcc
	v_add_co_u32_e32 v26, vcc, s10, v30
	global_load_dwordx4 v[10:13], v[10:11], off nt
	s_nop 0
	global_load_dwordx4 v[14:17], v[14:15], off nt
	v_addc_co_u32_e32 v27, vcc, 0, v31, vcc
	global_load_dword v56, v32, s[8:9]
	s_mov_b32 s10, 0x54000
	v_add_co_u32_e32 v30, vcc, s10, v30
	global_load_dwordx4 v[18:21], v[18:19], off nt
	s_nop 0
	global_load_dwordx4 v[22:25], v[22:23], off nt
	s_nop 0
	global_load_dword v84, v32, s[8:9] offset:32
	global_load_dword v86, v32, s[8:9] offset:64
	global_load_dword v88, v32, s[8:9] offset:96
	global_load_dword v90, v32, s[8:9] offset:128
	global_load_dword v92, v32, s[8:9] offset:160
	s_nop 0
	global_load_dwordx4 v[26:29], v[26:27], off nt
	s_nop 0
	global_load_dword v94, v32, s[8:9] offset:192
	v_addc_co_u32_e32 v31, vcc, 0, v31, vcc
	global_load_dword v96, v32, s[8:9] offset:224
	s_nop 0
	global_load_dwordx4 v[30:33], v[30:31], off nt
	v_add_u32_e32 v85, v35, v61
	v_add_u32_e32 v87, 0x420, v85
	v_add_u32_e32 v89, 0x428, v85
	v_add_u32_e32 v91, 0x840, v85
	s_waitcnt vmcnt(11)
	v_pk_mul_f32 v[2:3], v[2:3], v[56:57] op_sel_hi:[1,0]
	v_pk_mul_f32 v[4:5], v[4:5], v[56:57] op_sel_hi:[1,0]
	ds_write2_b32 v65, v2, v3 offset1:1
	ds_write2_b32 v65, v4, v5 offset0:2 offset1:3
	s_waitcnt vmcnt(8)
	v_pk_mul_f32 v[2:3], v[6:7], v[84:85] op_sel_hi:[1,0]
	v_pk_mul_f32 v[4:5], v[8:9], v[84:85] op_sel_hi:[1,0]
	s_waitcnt vmcnt(7)
	v_pk_mul_f32 v[6:7], v[10:11], v[86:87] op_sel_hi:[1,0]
	v_pk_mul_f32 v[8:9], v[12:13], v[86:87] op_sel_hi:[1,0]
	s_waitcnt vmcnt(6)
	v_pk_mul_f32 v[10:11], v[14:15], v[88:89] op_sel_hi:[1,0]
	v_pk_mul_f32 v[12:13], v[16:17], v[88:89] op_sel_hi:[1,0]
	s_waitcnt vmcnt(5)
	v_pk_mul_f32 v[14:15], v[18:19], v[90:91] op_sel_hi:[1,0]
	v_pk_mul_f32 v[16:17], v[20:21], v[90:91] op_sel_hi:[1,0]
	s_waitcnt vmcnt(4)
	v_pk_mul_f32 v[18:19], v[22:23], v[92:93] op_sel_hi:[1,0]
	v_pk_mul_f32 v[20:21], v[24:25], v[92:93] op_sel_hi:[1,0]
	s_waitcnt vmcnt(2)
	v_pk_mul_f32 v[22:23], v[26:27], v[94:95] op_sel_hi:[1,0]
	v_pk_mul_f32 v[24:25], v[28:29], v[94:95] op_sel_hi:[1,0]
	ds_write2_b32 v66, v2, v3 offset1:1
	ds_write2_b32 v67, v4, v5 offset1:1
	ds_write2_b32 v68, v6, v7 offset1:1
	ds_write2_b32 v69, v8, v9 offset1:1
	ds_write2_b32 v70, v10, v11 offset1:1
	ds_write2_b32 v71, v12, v13 offset1:1
	ds_write2_b32 v85, v14, v15 offset1:1
	ds_write2_b32 v85, v16, v17 offset0:2 offset1:3
	ds_write2_b32 v87, v18, v19 offset1:1
	ds_write2_b32 v89, v20, v21 offset1:1
	ds_write2_b32 v91, v22, v23 offset1:1
	v_add_u32_e32 v2, 0x848, v85
	ds_write2_b32 v2, v24, v25 offset1:1
	s_waitcnt vmcnt(0)
; #define LAS __attribute__((address_space(3)))
; DI unsigned cvtpk(float lo, float hi) { f32x2 v = {lo, hi}; bf16x2_t b = __builtin_convertvector(v, bf16x2_t); return __builtin_bit_cast(unsigned, b); }
; template <int KIND> DI int map_n(int n) {
;     ...
;         const int hd = n / 192, w = n % 192;
;         if (w < 128) return n;
;         const int j = w - 128; return hd * 192 + 128 + (j < 32 ? 2 * j : 2 * (j - 32) + 1);
;     }
; template <int KIND>
; DI void transpose_item(const float* W, int K, int N, bf16_t* WT, int ldk, const float* g0, const float* g1, const float* g2, LAS float* scr, int item, int lane) {
;     ...
;     asm volatile("s_waitcnt lgkmcnt(0)" ::: "memory");
;     int kd0 = k0;
;     if (KIND == 4) kd0 = k0 < 1024 ? k0 + 512 : (k0 < 1536 ? k0 - 1024 : k0);
;     const int c = lane & 7;
; #pragma unroll
;     for (int j = 0; j < 4; ++j) { const int n = (lane >> 3) + 8 * j; const LAS float* s = scr + (8 * c) * 33 + n;
;         u32x4 o; o.x = cvtpk(s[0 * 33], s[1 * 33]); o.y = cvtpk(s[2 * 33], s[3 * 33]); o.z = cvtpk(s[4 * 33], s[5 * 33]); o.w = cvtpk(s[6 * 33], s[7 * 33]);
;         *(u32x4*)(WT + (size_t)map_n<KIND>(n0 + n) * ldk + kd0 + 8 * c) = o; }
;     asm volatile("s_waitcnt lgkmcnt(0)" ::: "memory");
; }
	v_pk_mul_f32 v[2:3], v[30:31], v[96:97] op_sel_hi:[1,0]
	v_add_u32_e32 v4, 0xc60, v85
	ds_write2_b32 v4, v2, v3 offset1:1
	v_pk_mul_f32 v[2:3], v[32:33], v[96:97] op_sel_hi:[1,0]
	v_add_u32_e32 v4, 0xc68, v85
	ds_write2_b32 v4, v2, v3 offset1:1
	s_waitcnt lgkmcnt(0)
	v_lshlrev_b32_e32 v2, 1, v55
	v_mov_b32_e32 v3, v37
	ds_read2_b32 v[6:7], v60 offset0:33 offset1:41
	ds_read2_b32 v[8:9], v60 offset1:8
	ds_read2_b32 v[10:11], v60 offset0:66 offset1:74
	ds_read2_b32 v[12:13], v60 offset0:99 offset1:107
	ds_read2_b32 v[14:15], v60 offset0:132 offset1:140
	ds_read2_b32 v[16:17], v60 offset0:165 offset1:173
	ds_read2_b32 v[18:19], v60 offset0:198 offset1:206
	ds_read2_b32 v[20:21], v60 offset0:231 offset1:239
	v_lshl_add_u64 v[22:23], v[48:49], 0, v[2:3]
	s_waitcnt lgkmcnt(6)
	v_cvt_pk_bf16_f32 v2, v8, v6
	v_or_b32_e32 v6, v34, v57
	v_mul_u32_u24_e32 v8, 0x2aab, v6
	v_lshrrev_b32_e32 v8, 21, v8
	v_mul_lo_u16_e32 v8, 0xc0, v8
	v_sub_u16_e32 v8, v6, v8
	s_waitcnt lgkmcnt(4)
	v_cvt_pk_bf16_f32 v3, v10, v12
	v_cmp_gt_u16_e32 vcc, s84, v8
	v_sub_u32_e32 v12, v6, v8
	v_lshl_add_u32 v12, v8, 1, v12
	v_cndmask_b32_e32 v10, v80, v81, vcc
	v_add3_u32 v10, v12, v10, s83
	v_cmp_gt_u16_e32 vcc, s83, v8
	s_waitcnt lgkmcnt(2)
	v_cvt_pk_bf16_f32 v4, v14, v16
	s_waitcnt lgkmcnt(0)
	v_cvt_pk_bf16_f32 v5, v18, v20
	v_cndmask_b32_e32 v24, v10, v6, vcc
	v_ashrrev_i32_e32 v25, 31, v24
	v_lshlrev_b64 v[24:25], 10, v[24:25]
	v_lshl_add_u64 v[24:25], v[22:23], 0, v[24:25]
	v_or_b32_e32 v6, v53, v57
	global_store_dwordx4 v[24:25], v[2:5], off sc1
	s_nop 1
	v_cvt_pk_bf16_f32 v2, v9, v7
	v_mul_u32_u24_e32 v7, 0x2aab, v6
	v_lshrrev_b32_e32 v7, 21, v7
	v_mul_lo_u16_e32 v7, 0xc0, v7
	v_sub_u16_e32 v7, v6, v7
	v_cmp_gt_u16_e32 vcc, s84, v7
	v_sub_u32_e32 v9, v6, v7
	v_lshl_add_u32 v9, v7, 1, v9
	v_cndmask_b32_e32 v8, v80, v81, vcc
	v_add3_u32 v8, v9, v8, s83
	v_cmp_gt_u16_e32 vcc, s83, v7
	v_cvt_pk_bf16_f32 v3, v11, v13
	v_cvt_pk_bf16_f32 v4, v15, v17
	v_cndmask_b32_e32 v6, v8, v6, vcc
	v_ashrrev_i32_e32 v7, 31, v6
	v_lshlrev_b64 v[6:7], 10, v[6:7]
	v_cvt_pk_bf16_f32 v5, v19, v21
	v_lshl_add_u64 v[6:7], v[22:23], 0, v[6:7]
	ds_read2_b32 v[8:9], v60 offset0:16 offset1:24
	ds_read2_b32 v[10:11], v60 offset0:49 offset1:57
	ds_read2_b32 v[12:13], v60 offset0:82 offset1:90
	ds_read2_b32 v[14:15], v60 offset0:115 offset1:123
	ds_read2_b32 v[16:17], v60 offset0:148 offset1:156
	ds_read2_b32 v[18:19], v60 offset0:181 offset1:189
	ds_read2_b32 v[20:21], v60 offset0:214 offset1:222
	ds_read2_b32 v[24:25], v60 offset0:247 offset1:255
	global_store_dwordx4 v[6:7], v[2:5], off sc1
	v_or_b32_e32 v6, v58, v57
	v_mul_u32_u24_e32 v7, 0x2aab, v6
	v_lshrrev_b32_e32 v7, 21, v7
	v_mul_lo_u16_e32 v7, 0xc0, v7
	v_sub_u16_e32 v7, v6, v7
	s_waitcnt lgkmcnt(6)
	v_cvt_pk_bf16_f32 v2, v8, v10
	v_cmp_gt_u16_e32 vcc, s84, v7
	v_sub_u32_e32 v10, v6, v7
	v_lshl_add_u32 v10, v7, 1, v10
	v_cndmask_b32_e32 v8, v80, v81, vcc
	v_add3_u32 v8, v10, v8, s83
	v_cmp_gt_u16_e32 vcc, s83, v7
	s_waitcnt lgkmcnt(4)
	v_cvt_pk_bf16_f32 v3, v12, v14
	s_waitcnt lgkmcnt(2)
	v_cvt_pk_bf16_f32 v4, v16, v18
	v_cndmask_b32_e32 v6, v8, v6, vcc
	v_ashrrev_i32_e32 v7, 31, v6
	v_lshlrev_b64 v[6:7], 10, v[6:7]
	s_waitcnt lgkmcnt(0)
	v_cvt_pk_bf16_f32 v5, v20, v24
	v_lshl_add_u64 v[6:7], v[22:23], 0, v[6:7]
	global_store_dwordx4 v[6:7], v[2:5], off sc1
	v_or_b32_e32 v6, v59, v57
	v_mul_u32_u24_e32 v7, 0x2aab, v6
	v_lshrrev_b32_e32 v7, 21, v7
	v_mul_lo_u16_e32 v7, 0xc0, v7
	v_sub_u16_e32 v7, v6, v7
	v_cvt_pk_bf16_f32 v2, v9, v11
	v_cmp_gt_u16_e32 vcc, s84, v7
	v_sub_u32_e32 v9, v6, v7
	v_lshl_add_u32 v9, v7, 1, v9
	v_cndmask_b32_e32 v8, v80, v81, vcc
	v_add3_u32 v8, v9, v8, s83
	v_cmp_gt_u16_e32 vcc, s83, v7
	v_cvt_pk_bf16_f32 v3, v13, v15
	v_cvt_pk_bf16_f32 v4, v17, v19
	v_cndmask_b32_e32 v6, v8, v6, vcc
	v_ashrrev_i32_e32 v7, 31, v6
	v_lshlrev_b64 v[6:7], 10, v[6:7]
	v_cvt_pk_bf16_f32 v5, v21, v25
	v_lshl_add_u64 v[6:7], v[22:23], 0, v[6:7]
	global_store_dwordx4 v[6:7], v[2:5], off sc1
	s_waitcnt lgkmcnt(0)

; #define LAS __attribute__((address_space(3)))
; DI unsigned cvtpk(float lo, float hi) { f32x2 v = {lo, hi}; bf16x2_t b = __builtin_convertvector(v, bf16x2_t); return __builtin_bit_cast(unsigned, b); }
; template <int KIND> DI int map_n(int n) {
;     if (KIND == 0) {
;         if (n < 768) return n;
;         if (n < 832) { const int j = n - 768; return 2816 + (j < 32 ? 2 * j : 2 * (j - 32) + 1); }
;         return n - 64;
;     }
; template <int KIND>
; DI void transpose_item(const float* W, int K, int N, bf16_t* WT, int ldk, const float* g0, const float* g1, const float* g2, LAS float* scr, int item, int lane) {
;     ...
;     for (int j = 0; j < 4; ++j) { const int n = (lane >> 3) + 8 * j; const LAS float* s = scr + (8 * c) * 33 + n;
;         u32x4 o; o.x = cvtpk(s[0 * 33], s[1 * 33]); o.y = cvtpk(s[2 * 33], s[3 * 33]); o.z = cvtpk(s[4 * 33], s[5 * 33]); o.w = cvtpk(s[6 * 33], s[7 * 33]);
;         *(u32x4*)(WT + (size_t)map_n<KIND>(n0 + n) * ldk + kd0 + 8 * c) = o; }
.LBB0_150:
	s_or_b64 exec, exec, s[8:9]
	v_ashrrev_i32_e32 v15, 31, v14
	v_lshl_add_u64 v[4:5], v[4:5], 1, v[50:51]
	s_waitcnt lgkmcnt(3)
	v_cvt_pk_bf16_f32 v18, v6, v7
	v_lshlrev_b64 v[6:7], 12, v[14:15]
	s_waitcnt lgkmcnt(2)
	v_cvt_pk_bf16_f32 v19, v8, v9
	s_waitcnt lgkmcnt(1)
	v_cvt_pk_bf16_f32 v20, v10, v11
	s_waitcnt lgkmcnt(0)
	v_cvt_pk_bf16_f32 v21, v12, v13
	v_lshl_add_u64 v[14:15], v[4:5], 0, v[6:7]
	ds_read2_b32 v[6:7], v60 offset0:8 offset1:41
	ds_read2_b32 v[8:9], v60 offset0:74 offset1:107
	ds_read2_b32 v[10:11], v60 offset0:140 offset1:173
	ds_read2_b32 v[12:13], v60 offset0:206 offset1:239
	global_store_dwordx4 v[14:15], v[18:21], off sc1
	v_add_u32_e32 v15, 8, v17
	v_or_b32_e32 v14, v3, v53
	v_cmp_lt_i32_e32 vcc, s86, v15
	s_and_saveexec_b64 s[8:9], vcc
	s_cbranch_execz .LBB0_156
	v_cmp_lt_u32_e32 vcc, s87, v2
	s_and_saveexec_b64 s[10:11], vcc
	s_xor_b64 s[10:11], exec, s[10:11]
	v_subrev_u32_e32 v14, 64, v14
	s_andn2_saveexec_b64 s[10:11], s[10:11]
	v_cmp_gt_u32_e32 vcc, s88, v2
	v_mul_lo_u32 v15, v16, s89
	s_movk_i32 s12, 0xb10
	v_cndmask_b32_e32 v14, v82, v83, vcc
	v_sub_u32_e32 v14, v14, v15
	v_add_u32_e32 v15, v62, v63
	v_add3_u32 v14, v15, v14, s12
	s_or_b64 exec, exec, s[10:11]
.LBB0_156:
	s_or_b64 exec, exec, s[8:9]
	v_ashrrev_i32_e32 v15, 31, v14
	s_waitcnt lgkmcnt(3)
	v_cvt_pk_bf16_f32 v18, v6, v7
	v_lshlrev_b64 v[6:7], 12, v[14:15]
	s_waitcnt lgkmcnt(2)
	v_cvt_pk_bf16_f32 v19, v8, v9
	s_waitcnt lgkmcnt(1)
	v_cvt_pk_bf16_f32 v20, v10, v11
	s_waitcnt lgkmcnt(0)
	v_cvt_pk_bf16_f32 v21, v12, v13
	v_lshl_add_u64 v[14:15], v[4:5], 0, v[6:7]
	ds_read2_b32 v[6:7], v60 offset0:16 offset1:49
	ds_read2_b32 v[8:9], v60 offset0:82 offset1:115
	ds_read2_b32 v[10:11], v60 offset0:148 offset1:181
	ds_read2_b32 v[12:13], v60 offset0:214 offset1:247
	global_store_dwordx4 v[14:15], v[18:21], off sc1
	v_add_u32_e32 v15, 16, v17
	v_or_b32_e32 v14, v3, v58
	v_cmp_lt_i32_e32 vcc, s86, v15
	s_and_saveexec_b64 s[8:9], vcc
	s_cbranch_execz .LBB0_162
	v_cmp_lt_u32_e32 vcc, s87, v2
	s_and_saveexec_b64 s[10:11], vcc
	s_xor_b64 s[10:11], exec, s[10:11]
	v_subrev_u32_e32 v14, 64, v14
	s_andn2_saveexec_b64 s[10:11], s[10:11]
	v_cmp_gt_u32_e32 vcc, s88, v2
	v_mul_lo_u32 v15, v16, s89
	s_movk_i32 s12, 0xb20
	v_cndmask_b32_e32 v14, v82, v83, vcc
	v_sub_u32_e32 v14, v14, v15
	v_add_u32_e32 v15, v62, v63
	v_add3_u32 v14, v15, v14, s12
	s_or_b64 exec, exec, s[10:11]
.LBB0_162:
	s_or_b64 exec, exec, s[8:9]
	v_ashrrev_i32_e32 v15, 31, v14
	s_waitcnt lgkmcnt(3)
	v_cvt_pk_bf16_f32 v18, v6, v7
	v_lshlrev_b64 v[6:7], 12, v[14:15]
	s_waitcnt lgkmcnt(2)
	v_cvt_pk_bf16_f32 v19, v8, v9
	s_waitcnt lgkmcnt(1)
	v_cvt_pk_bf16_f32 v20, v10, v11
	s_waitcnt lgkmcnt(0)
	v_cvt_pk_bf16_f32 v21, v12, v13
	v_lshl_add_u64 v[14:15], v[4:5], 0, v[6:7]
	ds_read2_b32 v[6:7], v60 offset0:24 offset1:57
	ds_read2_b32 v[8:9], v60 offset0:90 offset1:123
	ds_read2_b32 v[10:11], v60 offset0:156 offset1:189
	ds_read2_b32 v[12:13], v60 offset0:222 offset1:255
	global_store_dwordx4 v[14:15], v[18:21], off sc1
	v_or_b32_e32 v14, v3, v59
	v_add_u32_e32 v3, 24, v17
	v_cmp_lt_i32_e32 vcc, s86, v3
	s_and_saveexec_b64 s[8:9], vcc
	s_cbranch_execz .LBB0_51
	v_cmp_lt_u32_e32 vcc, s87, v2
	s_and_saveexec_b64 s[10:11], vcc
	s_xor_b64 s[10:11], exec, s[10:11]
	v_subrev_u32_e32 v14, 64, v14
	s_andn2_saveexec_b64 s[10:11], s[10:11]
	s_cbranch_execz .LBB0_50
	v_cmp_gt_u32_e32 vcc, s88, v2
	v_mul_lo_u32 v3, v16, s89
	s_movk_i32 s12, 0xb30
	v_cndmask_b32_e32 v2, v82, v83, vcc
	v_sub_u32_e32 v2, v2, v3
	v_add_u32_e32 v3, v62, v63
	v_add3_u32 v14, v3, v2, s12
	s_branch .LBB0_50

; #define LAS __attribute__((address_space(3)))
; DI unsigned cvtpk(float lo, float hi) { f32x2 v = {lo, hi}; bf16x2_t b = __builtin_convertvector(v, bf16x2_t); return __builtin_bit_cast(unsigned, b); }
; template <int KIND>
; DI void transpose_item(const float* W, int K, int N, bf16_t* WT, int ldk, const float* g0, const float* g1, const float* g2, LAS float* scr, int item, int lane) {
;     ...
;     for (int j = 0; j < 4; ++j) { const int n = (lane >> 3) + 8 * j; const LAS float* s = scr + (8 * c) * 33 + n;
;         u32x4 o; o.x = cvtpk(s[0 * 33], s[1 * 33]); o.y = cvtpk(s[2 * 33], s[3 * 33]); o.z = cvtpk(s[4 * 33], s[5 * 33]); o.w = cvtpk(s[6 * 33], s[7 * 33]);
;         *(u32x4*)(WT + (size_t)map_n<KIND>(n0 + n) * ldk + kd0 + 8 * c) = o; }
.LBB0_622:
	s_or_b64 exec, exec, s[14:15]
	v_ashrrev_i32_e32 v13, 31, v12
	s_waitcnt lgkmcnt(3)
	v_cvt_pk_bf16_f32 v2, v2, v3
	s_waitcnt lgkmcnt(2)
	v_cvt_pk_bf16_f32 v3, v4, v5
	s_waitcnt lgkmcnt(1)
	v_cvt_pk_bf16_f32 v4, v6, v7
	v_lshlrev_b64 v[6:7], 12, v[12:13]
	s_waitcnt lgkmcnt(0)
	v_cvt_pk_bf16_f32 v5, v10, v11
	v_lshl_add_u64 v[0:1], v[0:1], 0, v[6:7]
	global_store_dwordx4 v[0:1], v[2:5], off sc1
	s_waitcnt lgkmcnt(0)

; template <int KIND>
; DI void transpose_item(const float* W, int K, int N, bf16_t* WT, int ldk, const float* g0, const float* g1, const float* g2, LAS float* scr, int item, int lane) {
;     const int nblk = N / 32, kb = item / nblk, nb = item % nblk, k0 = 64 * kb, n0 = 32 * nb;
;     f32x4 tv[8];
; #pragma unroll
;     for (int i = 0; i < 8; ++i) tv[i] = *(const f32x4*)(W + (size_t)(k0 + 8 * i + (lane >> 3)) * N + n0 + 4 * (lane & 7));
; #pragma unroll
;     for (int i = 0; i < 8; ++i) {
;         const int kk = 8 * i + (lane >> 3), k = k0 + kk;
;         float gn = 1.f;
;         if (KIND == 0 || KIND == 1 || KIND == 2 || KIND == 5 || KIND == 6) gn = g0[k];
; DI void convert_weights(PP p, LAS unsigned char* lds, int l, int worker, int nworkers) {
;     ...
;     for (int it = worker; it < I_LAYER; it += nworkers) {
;         int r = it;
;         if (r < I_IN) { transpose_item<0>(p->in[2] + (size_t)l * 2048 * 2880, 2048, 2880, (bf16_t*)(wl + W_IN), 2048, p->in[1] + l * 2048, nullptr, nullptr, scr, r, lane); continue; } r -= I_IN;
;         if (r < I_UQ) { transpose_item<1>(p->in[4] + (size_t)l * 512 * 1536, 512, 1536, (bf16_t*)(wl + W_UQ), 512, p->in[3] + l * 512, nullptr, nullptr, scr, r, lane); continue; } r -= I_UQ;
;         if (r < I_UKV) { transpose_item<2>(p->in[6] + (size_t)l * 256 * 2048, 256, 2048, (bf16_t*)(wl + W_UKV), 256, p->in[5] + l * 256, nullptr, nullptr, scr, r, lane); continue; } r -= I_UKV;
;         if (r < I_GLU) { transpose_item<3>(p->in[15] + (size_t)l * 512 * 1024, 512, 1024, (bf16_t*)(wl + W_GLU), 512, nullptr, nullptr, nullptr, scr, r, lane); continue; } r -= I_GLU;
;         if (r < I_O) { transpose_item<4>(p->in[20] + (size_t)l * 2048 * 2048, 2048, 2048, (bf16_t*)(wl + W_O), 2048, p->in[17] + l * 1024, p->in[18] + l * 512, p->in[19] + l * 512, scr, r, lane); continue; } r -= I_O;
;         if (r < I_G) { transpose_item<5>(p->in[22] + (size_t)l * 2048 * DFF_, 2048, DFF_, (bf16_t*)(wl + W_GU), 2048, p->in[21] + l * 2048, nullptr, nullptr, scr, r, lane); continue; } r -= I_G;
;         if (r < I_G) { transpose_item<6>(p->in[23] + (size_t)l * 2048 * DFF_, 2048, DFF_, (bf16_t*)(wl + W_GU), 2048, p->in[21] + l * 2048, nullptr, nullptr, scr, r, lane); continue; } r -= I_G;
;         transpose_item<7>(p->in[24] + (size_t)l * DFF_ * 2048, DFF_, 2048, (bf16_t*)(wl + W_DN), DFF_, nullptr, nullptr, nullptr, scr, r, lane);
.LBB0_624:
	s_movk_i32 s4, 0xb3f
	v_cmp_lt_i32_e32 vcc, s4, v62
	s_and_saveexec_b64 s[6:7], vcc
	s_xor_b64 s[62:63], exec, s[6:7]
	s_cbranch_execz .LBB0_714
	s_movk_i32 s4, 0xcbf
	v_cmp_lt_u32_e32 vcc, s4, v62
	s_and_saveexec_b64 s[6:7], vcc
	s_xor_b64 s[64:65], exec, s[6:7]
	s_cbranch_execz .LBB0_711
	s_movk_i32 s4, 0xdbf
	v_cmp_lt_u32_e32 vcc, s4, v62
	s_and_saveexec_b64 s[6:7], vcc
	s_xor_b64 s[66:67], exec, s[6:7]
	s_cbranch_execz .LBB0_708
	s_movk_i32 s4, 0xebf
	v_cmp_lt_u32_e32 vcc, s4, v62
	s_and_saveexec_b64 s[6:7], vcc
	s_xor_b64 s[68:69], exec, s[6:7]
	s_cbranch_execz .LBB0_705
	s_movk_i32 s4, 0x16bf
	v_cmp_lt_u32_e32 vcc, s4, v62
	s_and_saveexec_b64 s[6:7], vcc
	s_xor_b64 s[6:7], exec, s[6:7]
	s_cbranch_execz .LBB0_638
	s_movk_i32 s4, 0x2cbf
	v_cmp_lt_u32_e32 vcc, s4, v62
	s_and_saveexec_b64 s[14:15], vcc
	s_xor_b64 s[14:15], exec, s[14:15]
	s_cbranch_execz .LBB0_635
	s_movk_i32 s4, 0x42bf
	v_cmp_lt_u32_e32 vcc, s4, v62
	s_and_saveexec_b64 s[16:17], vcc
	s_xor_b64 s[16:17], exec, s[16:17]
	s_cbranch_execz .LBB0_632
	s_load_dwordx2 s[18:19], s[8:9], 0xc0
	v_add_u32_e32 v0, 0xffffbd40, v62
	v_and_b32_e32 v53, 0x1fc0, v0
	v_add_u32_e32 v0, 0xfff7a800, v50
	v_and_b32_e32 v54, 0x7c0, v0
	s_waitcnt lgkmcnt(0)
	s_add_u32 s18, s18, s1
	s_addc_u32 s19, s19, s0
	v_lshlrev_b32_e32 v128, 2, v54
	v_or_b32_e32 v2, v53, v32
	v_lshl_add_u64 v[0:1], s[18:19], 0, v[128:129]
	v_lshlrev_b32_e32 v128, 2, v34
	v_lshl_add_u64 v[0:1], v[0:1], 0, v[128:129]
	v_lshlrev_b32_e32 v128, 13, v2
	v_lshl_add_u64 v[28:29], v[0:1], 0, v[128:129]
	s_mov_b32 s4, 0x10000
	v_add_co_u32_e32 v4, vcc, s4, v28
	global_load_dwordx4 v[0:3], v[28:29], off nt
	s_nop 0
	v_addc_co_u32_e32 v5, vcc, 0, v29, vcc
	s_mov_b32 s4, 0x20000
	global_load_dwordx4 v[4:7], v[4:5], off nt
	v_add_co_u32_e32 v8, vcc, s4, v28
	s_mov_b32 s4, 0x30000
	s_nop 0
	v_addc_co_u32_e32 v9, vcc, 0, v29, vcc
	global_load_dwordx4 v[8:11], v[8:9], off nt
	v_add_co_u32_e32 v12, vcc, s4, v28
	s_mov_b32 s4, 0x50000
	s_nop 0
	v_addc_co_u32_e32 v13, vcc, 0, v29, vcc
	global_load_dwordx4 v[12:15], v[12:13], off nt
	v_add_co_u32_e32 v16, vcc, s89, v28
	v_add_u32_e32 v55, v33, v35
	s_nop 0
	v_addc_co_u32_e32 v17, vcc, 0, v29, vcc
	global_load_dwordx4 v[16:19], v[16:17], off nt
	v_add_co_u32_e32 v20, vcc, s4, v28
	s_mov_b32 s4, 0x60000
	s_nop 0
	v_addc_co_u32_e32 v21, vcc, 0, v29, vcc
	global_load_dwordx4 v[20:23], v[20:21], off nt
	v_add_co_u32_e32 v24, vcc, s4, v28
	s_mov_b32 s4, 0x70000
	s_nop 0
	v_addc_co_u32_e32 v25, vcc, 0, v29, vcc
	global_load_dwordx4 v[24:27], v[24:25], off nt
	v_add_co_u32_e32 v28, vcc, s4, v28
	v_lshlrev_b32_e32 v128, 1, v53
	s_nop 0
	v_addc_co_u32_e32 v29, vcc, 0, v29, vcc
	global_load_dwordx4 v[28:31], v[28:29], off nt
	s_waitcnt vmcnt(7)
	ds_write2_b32 v55, v0, v1 offset1:1
	ds_write2_b32 v55, v2, v3 offset0:2 offset1:3
	v_add_u32_e32 v0, 0x420, v55
	s_waitcnt vmcnt(6)
	ds_write2_b32 v0, v4, v5 offset1:1
	v_add_u32_e32 v0, 0x428, v55
	ds_write2_b32 v0, v6, v7 offset1:1
	v_add_u32_e32 v0, 0x840, v55
	s_waitcnt vmcnt(5)
	ds_write2_b32 v0, v8, v9 offset1:1
	v_add_u32_e32 v0, 0x848, v55
	ds_write2_b32 v0, v10, v11 offset1:1
	v_add_u32_e32 v0, 0xc60, v55
	s_waitcnt vmcnt(4)
	ds_write2_b32 v0, v12, v13 offset1:1
	v_add_u32_e32 v0, 0xc68, v55
	ds_write2_b32 v0, v14, v15 offset1:1
	v_add_u32_e32 v0, 0x1080, v55
	s_waitcnt vmcnt(3)
	ds_write2_b32 v0, v16, v17 offset1:1
	v_add_u32_e32 v0, 0x1088, v55
	ds_write2_b32 v0, v18, v19 offset1:1
	v_add_u32_e32 v0, 0x14a0, v55
	s_waitcnt vmcnt(2)
	ds_write2_b32 v0, v20, v21 offset1:1
	v_add_u32_e32 v0, 0x14a8, v55
	ds_write2_b32 v0, v22, v23 offset1:1
	v_add_u32_e32 v0, 0x18c0, v55
	s_waitcnt vmcnt(1)
	ds_write2_b32 v0, v24, v25 offset1:1
	v_add_u32_e32 v0, 0x18c8, v55
	ds_write2_b32 v0, v26, v27 offset1:1
	v_add_u32_e32 v0, 0x1ce0, v55
	s_waitcnt vmcnt(0)
	ds_write2_b32 v0, v28, v29 offset1:1
	v_add_u32_e32 v0, 0x1ce8, v55
	ds_write2_b32 v0, v30, v31 offset1:1
	s_waitcnt lgkmcnt(0)
	ds_read2_b32 v[6:7], v58 offset0:33 offset1:41
	ds_read2_b32 v[8:9], v58 offset1:8
	ds_read2_b32 v[10:11], v58 offset0:66 offset1:74
	ds_read2_b32 v[12:13], v58 offset0:99 offset1:107
	ds_read2_b32 v[14:15], v58 offset0:132 offset1:140
	ds_read2_b32 v[16:17], v58 offset0:165 offset1:173
	ds_read2_b32 v[18:19], v58 offset0:198 offset1:206
	ds_read2_b32 v[20:21], v58 offset0:231 offset1:239
	v_lshl_add_u64 v[0:1], v[36:37], 0, v[128:129]
	s_waitcnt lgkmcnt(6)
	v_cvt_pk_bf16_f32 v2, v8, v6
	v_or_b32_e32 v6, v54, v32
	v_mul_u32_u24_e32 v128, 0x2c00, v6
	v_or_b32_e32 v6, v54, v51
	s_waitcnt lgkmcnt(4)
	v_cvt_pk_bf16_f32 v3, v10, v12
	s_waitcnt lgkmcnt(2)
	v_cvt_pk_bf16_f32 v4, v14, v16
	s_waitcnt lgkmcnt(0)
	v_cvt_pk_bf16_f32 v5, v18, v20
	v_lshl_add_u64 v[22:23], v[0:1], 0, v[128:129]
	v_mul_u32_u24_e32 v128, 0x2c00, v6
	global_store_dwordx4 v[22:23], v[2:5], off sc1
	s_nop 1
	v_cvt_pk_bf16_f32 v2, v9, v7
	v_cvt_pk_bf16_f32 v3, v11, v13
	v_cvt_pk_bf16_f32 v4, v15, v17
	v_cvt_pk_bf16_f32 v5, v19, v21
	v_lshl_add_u64 v[6:7], v[0:1], 0, v[128:129]
	global_store_dwordx4 v[6:7], v[2:5], off sc1
	ds_read2_b32 v[6:7], v58 offset0:16 offset1:24
	ds_read2_b32 v[8:9], v58 offset0:49 offset1:57
	ds_read2_b32 v[10:11], v58 offset0:82 offset1:90
	ds_read2_b32 v[12:13], v58 offset0:115 offset1:123
	ds_read2_b32 v[14:15], v58 offset0:148 offset1:156
	ds_read2_b32 v[16:17], v58 offset0:181 offset1:189
	ds_read2_b32 v[18:19], v58 offset0:214 offset1:222
	ds_read2_b32 v[20:21], v58 offset0:247 offset1:255
	s_waitcnt lgkmcnt(6)
	v_cvt_pk_bf16_f32 v2, v6, v8
	v_or_b32_e32 v6, v54, v56
	v_mul_u32_u24_e32 v128, 0x2c00, v6
	v_or_b32_e32 v6, v54, v57
	s_waitcnt lgkmcnt(4)
	v_cvt_pk_bf16_f32 v3, v10, v12
	s_waitcnt lgkmcnt(2)
	v_cvt_pk_bf16_f32 v4, v14, v16
	s_waitcnt lgkmcnt(0)
	v_cvt_pk_bf16_f32 v5, v18, v20
	v_lshl_add_u64 v[22:23], v[0:1], 0, v[128:129]
	v_mul_u32_u24_e32 v128, 0x2c00, v6
	global_store_dwordx4 v[22:23], v[2:5], off sc1
	v_lshl_add_u64 v[0:1], v[0:1], 0, v[128:129]
	s_nop 0
	v_cvt_pk_bf16_f32 v2, v7, v9
	v_cvt_pk_bf16_f32 v3, v11, v13
	v_cvt_pk_bf16_f32 v4, v15, v17
	v_cvt_pk_bf16_f32 v5, v19, v21
	global_store_dwordx4 v[0:1], v[2:5], off sc1
	s_waitcnt lgkmcnt(0)
; #define LAS __attribute__((address_space(3)))
; template <int KIND>
; DI void transpose_item(const float* W, int K, int N, bf16_t* WT, int ldk, const float* g0, const float* g1, const float* g2, LAS float* scr, int item, int lane) {
;     const int nblk = N / 32, kb = item / nblk, nb = item % nblk, k0 = 64 * kb, n0 = 32 * nb;
;     f32x4 tv[8];
; #pragma unroll
;     for (int i = 0; i < 8; ++i) tv[i] = *(const f32x4*)(W + (size_t)(k0 + 8 * i + (lane >> 3)) * N + n0 + 4 * (lane & 7));
; #pragma unroll
;     for (int i = 0; i < 8; ++i) {
;         const int kk = 8 * i + (lane >> 3), k = k0 + kk;
;         float gn = 1.f;
;         if (KIND == 0 || KIND == 1 || KIND == 2 || KIND == 5 || KIND == 6) gn = g0[k];
;         if (KIND == 4) gn = k < 1024 ? g0[k] : (k < 1536 ? g1[k - 1024] : g2[k - 1536]);
;         LAS float* d = scr + kk * 33 + 4 * (lane & 7);
;         d[0] = tv[i][0] * gn; d[1] = tv[i][1] * gn; d[2] = tv[i][2] * gn; d[3] = tv[i][3] * gn;
;     }
;     asm volatile("s_waitcnt lgkmcnt(0)" ::: "memory");
.LBB0_632:
	s_andn2_saveexec_b64 s[16:17], s[16:17]
	s_cbranch_execz .LBB0_634
	s_load_dwordx2 s[18:19], s[8:9], 0xa8
	s_load_dwordx2 s[22:23], s[8:9], 0xb8
	v_add_u16_e32 v0, 0xd340, v62
	v_mul_u32_u24_e32 v1, 0xba2f, v0
	v_lshrrev_b32_e32 v1, 23, v1
	v_mul_lo_u16_e32 v2, 0xb0, v1
	v_sub_u16_e32 v0, v0, v2
	s_waitcnt lgkmcnt(0)
	s_add_u32 s22, s22, s1
	v_lshlrev_b16_e32 v13, 6, v1
	v_lshlrev_b16_e32 v12, 5, v0
	s_addc_u32 s23, s23, s0
	v_or_b32_e32 v30, v32, v13
	v_lshlrev_b32_e32 v128, 2, v12
	s_lshl_b64 s[34:35], s[38:39], 2
	v_lshl_add_u64 v[0:1], s[22:23], 0, v[128:129]
	v_lshlrev_b32_e32 v128, 2, v34
	v_mul_u32_u24_e32 v2, 0x1600, v30
	s_add_u32 s18, s18, s34
	v_lshl_add_u64 v[0:1], v[0:1], 0, v[128:129]
	v_lshlrev_b32_e32 v128, 2, v2
	s_addc_u32 s19, s19, s35
	v_lshl_add_u64 v[0:1], v[0:1], 0, v[128:129]
	v_lshlrev_b32_e32 v31, 2, v30
	global_load_dwordx4 v[14:17], v[0:1], off nt
	global_load_dword v30, v31, s[18:19]
	s_mov_b32 s4, 0x2c000
	v_add_co_u32_e32 v2, vcc, s4, v0
	v_add_u32_e32 v53, v33, v35
	s_nop 0
	v_addc_co_u32_e32 v3, vcc, 0, v1, vcc
	global_load_dwordx4 v[18:21], v[2:3], off nt
	s_mov_b32 s4, 0x58000
	v_add_co_u32_e32 v2, vcc, s4, v0
	s_mov_b32 s4, 0x84000
	s_nop 0
	v_addc_co_u32_e32 v3, vcc, 0, v1, vcc
	global_load_dwordx4 v[22:25], v[2:3], off nt
	v_add_co_u32_e32 v2, vcc, s4, v0
	s_mov_b32 s4, 0xb0000
	s_nop 0
	v_addc_co_u32_e32 v3, vcc, 0, v1, vcc
	global_load_dwordx4 v[26:29], v[2:3], off nt
	v_add_co_u32_e32 v2, vcc, s4, v0
	s_mov_b32 s4, 0xdc000
	s_nop 0
	v_addc_co_u32_e32 v3, vcc, 0, v1, vcc
	global_load_dwordx4 v[64:67], v[2:3], off nt
	v_add_co_u32_e32 v2, vcc, s4, v0
	s_mov_b32 s4, 0x108000
	s_nop 0
	v_addc_co_u32_e32 v3, vcc, 0, v1, vcc
	global_load_dwordx4 v[8:11], v[2:3], off nt
	v_add_co_u32_e32 v2, vcc, s4, v0
	s_mov_b32 s4, 0x134000
	s_nop 0
	v_addc_co_u32_e32 v3, vcc, 0, v1, vcc
	global_load_dwordx4 v[4:7], v[2:3], off nt
	v_add_co_u32_e32 v0, vcc, s4, v0
	s_movk_i32 s4, 0x1000
	s_nop 0
	v_addc_co_u32_e32 v1, vcc, 0, v1, vcc
	global_load_dwordx4 v[0:3], v[0:1], off nt
	s_waitcnt vmcnt(7)
	v_pk_mul_f32 v[14:15], v[14:15], v[30:31] op_sel_hi:[1,0]
	ds_write2_b32 v53, v14, v15 offset1:1
	v_pk_mul_f32 v[14:15], v[16:17], v[30:31] op_sel_hi:[1,0]
	ds_write2_b32 v53, v14, v15 offset0:2 offset1:3
	global_load_dword v14, v31, s[18:19] offset:32
	s_waitcnt vmcnt(0)
	v_pk_mul_f32 v[16:17], v[18:19], v[14:15] op_sel_hi:[1,0]
	v_add_u32_e32 v15, 0x420, v53
	ds_write2_b32 v15, v16, v17 offset1:1
	v_pk_mul_f32 v[14:15], v[20:21], v[14:15] op_sel_hi:[1,0]
	v_add_u32_e32 v16, 0x428, v53
	ds_write2_b32 v16, v14, v15 offset1:1
	global_load_dword v14, v31, s[18:19] offset:64
	v_add_u32_e32 v18, v33, v59
	s_waitcnt vmcnt(0)
	v_pk_mul_f32 v[16:17], v[22:23], v[14:15] op_sel_hi:[1,0]
	v_add_u32_e32 v15, 0x840, v53
	ds_write2_b32 v15, v16, v17 offset1:1
	v_pk_mul_f32 v[14:15], v[24:25], v[14:15] op_sel_hi:[1,0]
	v_add_u32_e32 v16, 0x848, v53
	ds_write2_b32 v16, v14, v15 offset1:1
	global_load_dword v14, v31, s[18:19] offset:96
	s_waitcnt vmcnt(0)
	v_pk_mul_f32 v[16:17], v[26:27], v[14:15] op_sel_hi:[1,0]
	v_add_u32_e32 v15, 0xc60, v53
	ds_write2_b32 v15, v16, v17 offset1:1
	v_pk_mul_f32 v[14:15], v[28:29], v[14:15] op_sel_hi:[1,0]
	v_add_u32_e32 v16, 0xc68, v53
	ds_write2_b32 v16, v14, v15 offset1:1
	global_load_dword v14, v31, s[18:19] offset:128
	v_mov_b32_e32 v53, v129
	s_waitcnt vmcnt(0)
	v_pk_mul_f32 v[16:17], v[64:65], v[14:15] op_sel_hi:[1,0]
	v_pk_mul_f32 v[14:15], v[66:67], v[14:15] op_sel_hi:[1,0]
	ds_write2_b32 v18, v14, v15 offset0:2 offset1:3
	global_load_dword v14, v31, s[18:19] offset:160
	ds_write2_b32 v18, v16, v17 offset1:1
	s_waitcnt vmcnt(0)
; #define LAS __attribute__((address_space(3)))
; DI unsigned cvtpk(float lo, float hi) { f32x2 v = {lo, hi}; bf16x2_t b = __builtin_convertvector(v, bf16x2_t); return __builtin_bit_cast(unsigned, b); }
; template <int KIND>
; DI void transpose_item(const float* W, int K, int N, bf16_t* WT, int ldk, const float* g0, const float* g1, const float* g2, LAS float* scr, int item, int lane) {
;     ...
;     asm volatile("s_waitcnt lgkmcnt(0)" ::: "memory");
;     int kd0 = k0;
;     if (KIND == 4) kd0 = k0 < 1024 ? k0 + 512 : (k0 < 1536 ? k0 - 1024 : k0);
;     const int c = lane & 7;
; #pragma unroll
;     for (int j = 0; j < 4; ++j) { const int n = (lane >> 3) + 8 * j; const LAS float* s = scr + (8 * c) * 33 + n;
;         u32x4 o; o.x = cvtpk(s[0 * 33], s[1 * 33]); o.y = cvtpk(s[2 * 33], s[3 * 33]); o.z = cvtpk(s[4 * 33], s[5 * 33]); o.w = cvtpk(s[6 * 33], s[7 * 33]);
;         *(u32x4*)(WT + (size_t)map_n<KIND>(n0 + n) * ldk + kd0 + 8 * c) = o; }
;     asm volatile("s_waitcnt lgkmcnt(0)" ::: "memory");
; }
	v_pk_mul_f32 v[8:9], v[8:9], v[14:15] op_sel_hi:[1,0]
	v_add_u32_e32 v15, 0x420, v18
	ds_write2_b32 v15, v8, v9 offset1:1
	v_pk_mul_f32 v[8:9], v[10:11], v[14:15] op_sel_hi:[1,0]
	v_add_u32_e32 v10, 0x428, v18
	ds_write2_b32 v10, v8, v9 offset1:1
	global_load_dword v8, v31, s[18:19] offset:192
	s_waitcnt vmcnt(0)
	v_pk_mul_f32 v[4:5], v[4:5], v[8:9] op_sel_hi:[1,0]
	v_add_u32_e32 v9, 0x840, v18
	ds_write2_b32 v9, v4, v5 offset1:1
	v_pk_mul_f32 v[4:5], v[6:7], v[8:9] op_sel_hi:[1,0]
	v_add_u32_e32 v6, 0x848, v18
	ds_write2_b32 v6, v4, v5 offset1:1
	global_load_dword v4, v31, s[18:19] offset:224
	s_waitcnt vmcnt(0)
	v_pk_mul_f32 v[0:1], v[0:1], v[4:5] op_sel_hi:[1,0]
	v_add_u32_e32 v5, 0xc60, v18
	ds_write2_b32 v5, v0, v1 offset1:1
	v_pk_mul_f32 v[0:1], v[2:3], v[4:5] op_sel_hi:[1,0]
	v_add_u32_e32 v2, 0xc68, v18
	ds_write2_b32 v2, v0, v1 offset1:1
	s_waitcnt lgkmcnt(0)
	ds_read2_b32 v[4:5], v58 offset0:33 offset1:41
	ds_read2_b32 v[6:7], v58 offset1:8
	ds_read2_b32 v[8:9], v58 offset0:66 offset1:74
	ds_read2_b32 v[10:11], v58 offset0:99 offset1:107
	ds_read2_b32 v[14:15], v58 offset0:132 offset1:140
	ds_read2_b32 v[16:17], v58 offset0:165 offset1:173
	ds_read2_b32 v[18:19], v58 offset0:198 offset1:206
	ds_read2_b32 v[20:21], v58 offset0:231 offset1:239
	s_waitcnt lgkmcnt(6)
	v_cvt_pk_bf16_f32 v0, v6, v4
	v_or_b32_e32 v4, v32, v12
	v_lshlrev_b32_e32 v128, 13, v4
	v_lshl_add_u64 v[22:23], s[12:13], 0, v[128:129]
	v_lshlrev_b32_e32 v128, 1, v13
	v_lshl_add_u64 v[22:23], v[22:23], 0, v[128:129]
	v_lshl_add_u64 v[22:23], v[22:23], 0, v[52:53]
	v_add_co_u32_e32 v22, vcc, s4, v22
	s_waitcnt lgkmcnt(4)
	v_cvt_pk_bf16_f32 v1, v8, v10
	s_waitcnt lgkmcnt(2)
	v_cvt_pk_bf16_f32 v2, v14, v16
	s_waitcnt lgkmcnt(0)
	v_cvt_pk_bf16_f32 v3, v18, v20
	v_addc_co_u32_e32 v23, vcc, 0, v23, vcc
	v_or_b32_e32 v4, v51, v12
	global_store_dwordx4 v[22:23], v[0:3], off sc1
	v_lshlrev_b32_e32 v4, 13, v4
	v_mov_b32_e32 v23, v129
	v_cvt_pk_bf16_f32 v0, v7, v5
	v_mov_b32_e32 v5, v129
	v_lshl_add_u64 v[4:5], s[12:13], 0, v[4:5]
	v_lshl_add_u64 v[4:5], v[4:5], 0, v[128:129]
	v_lshl_add_u64 v[4:5], v[4:5], 0, v[52:53]
	v_add_co_u32_e32 v4, vcc, s4, v4
	v_cvt_pk_bf16_f32 v1, v9, v11
	v_cvt_pk_bf16_f32 v2, v15, v17
	v_cvt_pk_bf16_f32 v3, v19, v21
	v_addc_co_u32_e32 v5, vcc, 0, v5, vcc
	global_store_dwordx4 v[4:5], v[0:3], off sc1
	ds_read2_b32 v[4:5], v58 offset0:49 offset1:57
	ds_read2_b32 v[6:7], v58 offset0:16 offset1:24
	ds_read2_b32 v[8:9], v58 offset0:82 offset1:90
	ds_read2_b32 v[10:11], v58 offset0:115 offset1:123
	ds_read2_b32 v[14:15], v58 offset0:148 offset1:156
	ds_read2_b32 v[16:17], v58 offset0:181 offset1:189
	ds_read2_b32 v[18:19], v58 offset0:214 offset1:222
	ds_read2_b32 v[20:21], v58 offset0:247 offset1:255
	s_waitcnt lgkmcnt(6)
	v_cvt_pk_bf16_f32 v0, v6, v4
	v_or_b32_e32 v4, v56, v12
	v_lshlrev_b32_e32 v22, 13, v4
	v_lshl_add_u64 v[22:23], s[12:13], 0, v[22:23]
	v_lshl_add_u64 v[22:23], v[22:23], 0, v[128:129]
	v_lshl_add_u64 v[22:23], v[22:23], 0, v[52:53]
	v_add_co_u32_e32 v22, vcc, s4, v22
	s_waitcnt lgkmcnt(4)
	v_cvt_pk_bf16_f32 v1, v8, v10
	s_waitcnt lgkmcnt(2)
	v_cvt_pk_bf16_f32 v2, v14, v16
	s_waitcnt lgkmcnt(0)
	v_cvt_pk_bf16_f32 v3, v18, v20
	v_addc_co_u32_e32 v23, vcc, 0, v23, vcc
	v_or_b32_e32 v4, v57, v12
	global_store_dwordx4 v[22:23], v[0:3], off sc1
	v_lshlrev_b32_e32 v4, 13, v4
	s_nop 0
	v_cvt_pk_bf16_f32 v0, v7, v5
	v_mov_b32_e32 v5, v129
	v_lshl_add_u64 v[4:5], s[12:13], 0, v[4:5]
	v_lshl_add_u64 v[4:5], v[4:5], 0, v[128:129]
	v_lshl_add_u64 v[4:5], v[4:5], 0, v[52:53]
	v_add_co_u32_e32 v4, vcc, 0x1000, v4
	v_cvt_pk_bf16_f32 v1, v9, v11
	v_cvt_pk_bf16_f32 v2, v15, v17
	v_cvt_pk_bf16_f32 v3, v19, v21
	v_addc_co_u32_e32 v5, vcc, 0, v5, vcc
	global_store_dwordx4 v[4:5], v[0:3], off sc1
	s_waitcnt lgkmcnt(0)

; #define LAS __attribute__((address_space(3)))
; DI unsigned cvtpk(float lo, float hi) { f32x2 v = {lo, hi}; bf16x2_t b = __builtin_convertvector(v, bf16x2_t); return __builtin_bit_cast(unsigned, b); }
; template <int KIND>
; DI void transpose_item(const float* W, int K, int N, bf16_t* WT, int ldk, const float* g0, const float* g1, const float* g2, LAS float* scr, int item, int lane) {
;     const int nblk = N / 32, kb = item / nblk, nb = item % nblk, k0 = 64 * kb, n0 = 32 * nb;
;     f32x4 tv[8];
; #pragma unroll
;     for (int i = 0; i < 8; ++i) tv[i] = *(const f32x4*)(W + (size_t)(k0 + 8 * i + (lane >> 3)) * N + n0 + 4 * (lane & 7));
; #pragma unroll
;     for (int i = 0; i < 8; ++i) {
;         const int kk = 8 * i + (lane >> 3), k = k0 + kk;
;         float gn = 1.f;
;         if (KIND == 0 || KIND == 1 || KIND == 2 || KIND == 5 || KIND == 6) gn = g0[k];
;         if (KIND == 4) gn = k < 1024 ? g0[k] : (k < 1536 ? g1[k - 1024] : g2[k - 1536]);
;         LAS float* d = scr + kk * 33 + 4 * (lane & 7);
;         d[0] = tv[i][0] * gn; d[1] = tv[i][1] * gn; d[2] = tv[i][2] * gn; d[3] = tv[i][3] * gn;
;     }
;     asm volatile("s_waitcnt lgkmcnt(0)" ::: "memory");
;     int kd0 = k0;
;     if (KIND == 4) kd0 = k0 < 1024 ? k0 + 512 : (k0 < 1536 ? k0 - 1024 : k0);
;     const int c = lane & 7;
; #pragma unroll
;     for (int j = 0; j < 4; ++j) { const int n = (lane >> 3) + 8 * j; const LAS float* s = scr + (8 * c) * 33 + n;
;         u32x4 o; o.x = cvtpk(s[0 * 33], s[1 * 33]); o.y = cvtpk(s[2 * 33], s[3 * 33]); o.z = cvtpk(s[4 * 33], s[5 * 33]); o.w = cvtpk(s[6 * 33], s[7 * 33]);
;         *(u32x4*)(WT + (size_t)map_n<KIND>(n0 + n) * ldk + kd0 + 8 * c) = o; }
;     asm volatile("s_waitcnt lgkmcnt(0)" ::: "memory");
; }
.LBB0_635:
	s_andn2_saveexec_b64 s[14:15], s[14:15]
	s_cbranch_execz .LBB0_637
	s_load_dwordx4 s[16:19], s[8:9], 0xa8
	v_add_u16_e32 v0, 0xe940, v62
	v_mul_u32_u24_e32 v1, 0xba2f, v0
	v_lshrrev_b32_e32 v1, 23, v1
	v_mul_lo_u16_e32 v2, 0xb0, v1
	v_sub_u16_e32 v0, v0, v2
	s_waitcnt lgkmcnt(0)
	s_add_u32 s18, s18, s1
	v_lshlrev_b16_e32 v13, 6, v1
	v_lshlrev_b16_e32 v12, 5, v0
	s_addc_u32 s19, s19, s0
	v_or_b32_e32 v30, v32, v13
	v_lshlrev_b32_e32 v128, 2, v12
	s_lshl_b64 s[22:23], s[38:39], 2
	v_lshl_add_u64 v[0:1], s[18:19], 0, v[128:129]
	v_lshlrev_b32_e32 v128, 2, v34
	v_mul_u32_u24_e32 v2, 0x1600, v30
	s_add_u32 s16, s16, s22
	v_lshl_add_u64 v[0:1], v[0:1], 0, v[128:129]
	v_lshlrev_b32_e32 v128, 2, v2
	s_addc_u32 s17, s17, s23
	v_lshl_add_u64 v[0:1], v[0:1], 0, v[128:129]
	v_lshlrev_b32_e32 v31, 2, v30
	global_load_dwordx4 v[14:17], v[0:1], off nt
	global_load_dword v30, v31, s[16:17]
	s_mov_b32 s4, 0x2c000
	v_add_co_u32_e32 v2, vcc, s4, v0
	v_add_u32_e32 v53, v33, v35
	s_nop 0
	v_addc_co_u32_e32 v3, vcc, 0, v1, vcc
	global_load_dwordx4 v[18:21], v[2:3], off nt
	s_mov_b32 s4, 0x58000
	v_add_co_u32_e32 v2, vcc, s4, v0
	s_mov_b32 s4, 0x84000
	s_nop 0
	v_addc_co_u32_e32 v3, vcc, 0, v1, vcc
	global_load_dwordx4 v[22:25], v[2:3], off nt
	v_add_co_u32_e32 v2, vcc, s4, v0
	s_mov_b32 s4, 0xb0000
	s_nop 0
	v_addc_co_u32_e32 v3, vcc, 0, v1, vcc
	global_load_dwordx4 v[26:29], v[2:3], off nt
	v_add_co_u32_e32 v2, vcc, s4, v0
	s_mov_b32 s4, 0xdc000
	s_nop 0
	v_addc_co_u32_e32 v3, vcc, 0, v1, vcc
	global_load_dwordx4 v[64:67], v[2:3], off nt
	v_add_co_u32_e32 v2, vcc, s4, v0
	s_mov_b32 s4, 0x108000
	s_nop 0
	v_addc_co_u32_e32 v3, vcc, 0, v1, vcc
	global_load_dwordx4 v[8:11], v[2:3], off nt
	v_add_co_u32_e32 v2, vcc, s4, v0
	s_mov_b32 s4, 0x134000
	s_nop 0
	v_addc_co_u32_e32 v3, vcc, 0, v1, vcc
	global_load_dwordx4 v[4:7], v[2:3], off nt
	v_add_co_u32_e32 v0, vcc, s4, v0
	v_lshlrev_b32_e32 v128, 1, v13
	s_nop 0
	v_addc_co_u32_e32 v1, vcc, 0, v1, vcc
	global_load_dwordx4 v[0:3], v[0:1], off nt
	s_waitcnt vmcnt(7)
	v_pk_mul_f32 v[14:15], v[14:15], v[30:31] op_sel_hi:[1,0]
	ds_write2_b32 v53, v14, v15 offset1:1
	v_pk_mul_f32 v[14:15], v[16:17], v[30:31] op_sel_hi:[1,0]
	ds_write2_b32 v53, v14, v15 offset0:2 offset1:3
	global_load_dword v14, v31, s[16:17] offset:32
	s_waitcnt vmcnt(0)
	v_pk_mul_f32 v[16:17], v[18:19], v[14:15] op_sel_hi:[1,0]
	v_add_u32_e32 v15, 0x420, v53
	ds_write2_b32 v15, v16, v17 offset1:1
	v_pk_mul_f32 v[14:15], v[20:21], v[14:15] op_sel_hi:[1,0]
	v_add_u32_e32 v16, 0x428, v53
	ds_write2_b32 v16, v14, v15 offset1:1
	global_load_dword v14, v31, s[16:17] offset:64
	v_add_u32_e32 v18, v33, v59
	s_waitcnt vmcnt(0)
	v_pk_mul_f32 v[16:17], v[22:23], v[14:15] op_sel_hi:[1,0]
	v_add_u32_e32 v15, 0x840, v53
	ds_write2_b32 v15, v16, v17 offset1:1
	v_pk_mul_f32 v[14:15], v[24:25], v[14:15] op_sel_hi:[1,0]
	v_add_u32_e32 v16, 0x848, v53
	ds_write2_b32 v16, v14, v15 offset1:1
	global_load_dword v14, v31, s[16:17] offset:96
	s_waitcnt vmcnt(0)
	v_pk_mul_f32 v[16:17], v[26:27], v[14:15] op_sel_hi:[1,0]
	v_add_u32_e32 v15, 0xc60, v53
	ds_write2_b32 v15, v16, v17 offset1:1
	v_pk_mul_f32 v[14:15], v[28:29], v[14:15] op_sel_hi:[1,0]
	v_add_u32_e32 v16, 0xc68, v53
	ds_write2_b32 v16, v14, v15 offset1:1
	global_load_dword v14, v31, s[16:17] offset:128
	s_waitcnt vmcnt(0)
	v_pk_mul_f32 v[16:17], v[64:65], v[14:15] op_sel_hi:[1,0]
	v_pk_mul_f32 v[14:15], v[66:67], v[14:15] op_sel_hi:[1,0]
	ds_write2_b32 v18, v14, v15 offset0:2 offset1:3
	global_load_dword v14, v31, s[16:17] offset:160
	ds_write2_b32 v18, v16, v17 offset1:1
	s_waitcnt vmcnt(0)
	v_pk_mul_f32 v[8:9], v[8:9], v[14:15] op_sel_hi:[1,0]
	v_add_u32_e32 v15, 0x420, v18
	ds_write2_b32 v15, v8, v9 offset1:1
	v_pk_mul_f32 v[8:9], v[10:11], v[14:15] op_sel_hi:[1,0]
	v_add_u32_e32 v10, 0x428, v18
	ds_write2_b32 v10, v8, v9 offset1:1
	global_load_dword v8, v31, s[16:17] offset:192
	s_waitcnt vmcnt(0)
	v_pk_mul_f32 v[4:5], v[4:5], v[8:9] op_sel_hi:[1,0]
	v_add_u32_e32 v9, 0x840, v18
	ds_write2_b32 v9, v4, v5 offset1:1
	v_pk_mul_f32 v[4:5], v[6:7], v[8:9] op_sel_hi:[1,0]
	v_add_u32_e32 v6, 0x848, v18
	ds_write2_b32 v6, v4, v5 offset1:1
	global_load_dword v4, v31, s[16:17] offset:224
	s_waitcnt vmcnt(0)
	v_pk_mul_f32 v[0:1], v[0:1], v[4:5] op_sel_hi:[1,0]
	v_add_u32_e32 v5, 0xc60, v18
	ds_write2_b32 v5, v0, v1 offset1:1
	v_pk_mul_f32 v[0:1], v[2:3], v[4:5] op_sel_hi:[1,0]
	v_add_u32_e32 v2, 0xc68, v18
	ds_write2_b32 v2, v0, v1 offset1:1
	s_waitcnt lgkmcnt(0)
	ds_read2_b32 v[6:7], v58 offset0:33 offset1:41
	ds_read2_b32 v[8:9], v58 offset1:8
	ds_read2_b32 v[10:11], v58 offset0:66 offset1:74
	ds_read2_b32 v[14:15], v58 offset0:99 offset1:107
	ds_read2_b32 v[16:17], v58 offset0:132 offset1:140
	ds_read2_b32 v[18:19], v58 offset0:165 offset1:173
	ds_read2_b32 v[20:21], v58 offset0:198 offset1:206
	ds_read2_b32 v[22:23], v58 offset0:231 offset1:239
	v_lshl_add_u64 v[4:5], v[38:39], 0, v[128:129]
	s_waitcnt lgkmcnt(6)
	v_cvt_pk_bf16_f32 v0, v8, v6
	v_or_b32_e32 v6, v32, v12
	v_lshlrev_b32_e32 v128, 13, v6
	v_or_b32_e32 v6, v51, v12
	s_waitcnt lgkmcnt(4)
	v_cvt_pk_bf16_f32 v1, v10, v14
	s_waitcnt lgkmcnt(2)
	v_cvt_pk_bf16_f32 v2, v16, v18
	s_waitcnt lgkmcnt(0)
	v_cvt_pk_bf16_f32 v3, v20, v22
	v_lshl_add_u64 v[24:25], v[4:5], 0, v[128:129]
	v_lshlrev_b32_e32 v128, 13, v6
	global_store_dwordx4 v[24:25], v[0:3], off sc1
	s_nop 1
	v_cvt_pk_bf16_f32 v0, v9, v7
	v_cvt_pk_bf16_f32 v1, v11, v15
	v_cvt_pk_bf16_f32 v2, v17, v19
	v_cvt_pk_bf16_f32 v3, v21, v23
	v_lshl_add_u64 v[6:7], v[4:5], 0, v[128:129]
	global_store_dwordx4 v[6:7], v[0:3], off sc1
	ds_read2_b32 v[6:7], v58 offset0:49 offset1:57
	ds_read2_b32 v[8:9], v58 offset0:16 offset1:24
	ds_read2_b32 v[10:11], v58 offset0:82 offset1:90
	ds_read2_b32 v[14:15], v58 offset0:115 offset1:123
	ds_read2_b32 v[16:17], v58 offset0:148 offset1:156
	ds_read2_b32 v[18:19], v58 offset0:181 offset1:189
	ds_read2_b32 v[20:21], v58 offset0:214 offset1:222
	ds_read2_b32 v[22:23], v58 offset0:247 offset1:255
	s_waitcnt lgkmcnt(6)
	v_cvt_pk_bf16_f32 v0, v8, v6
	v_or_b32_e32 v6, v56, v12
	v_lshlrev_b32_e32 v128, 13, v6
	v_or_b32_e32 v6, v57, v12
	s_waitcnt lgkmcnt(4)
	v_cvt_pk_bf16_f32 v1, v10, v14
	s_waitcnt lgkmcnt(2)
	v_cvt_pk_bf16_f32 v2, v16, v18
	s_waitcnt lgkmcnt(0)
	v_cvt_pk_bf16_f32 v3, v20, v22
	v_lshl_add_u64 v[24:25], v[4:5], 0, v[128:129]
	v_lshlrev_b32_e32 v128, 13, v6
	global_store_dwordx4 v[24:25], v[0:3], off sc1
	v_lshl_add_u64 v[4:5], v[4:5], 0, v[128:129]
	s_nop 0
	v_cvt_pk_bf16_f32 v0, v9, v7
	v_cvt_pk_bf16_f32 v1, v11, v15
	v_cvt_pk_bf16_f32 v2, v17, v19
	v_cvt_pk_bf16_f32 v3, v21, v23
	global_store_dwordx4 v[4:5], v[0:3], off sc1
	s_waitcnt lgkmcnt(0)

; #define LAS __attribute__((address_space(3)))
; DI unsigned cvtpk(float lo, float hi) { f32x2 v = {lo, hi}; bf16x2_t b = __builtin_convertvector(v, bf16x2_t); return __builtin_bit_cast(unsigned, b); }
; template <int KIND>
; DI void transpose_item(const float* W, int K, int N, bf16_t* WT, int ldk, const float* g0, const float* g1, const float* g2, LAS float* scr, int item, int lane) {
;     ...
;         if (KIND == 4) gn = k < 1024 ? g0[k] : (k < 1536 ? g1[k - 1024] : g2[k - 1536]);
;         LAS float* d = scr + kk * 33 + 4 * (lane & 7);
;         d[0] = tv[i][0] * gn; d[1] = tv[i][1] * gn; d[2] = tv[i][2] * gn; d[3] = tv[i][3] * gn;
;     }
;     asm volatile("s_waitcnt lgkmcnt(0)" ::: "memory");
;     int kd0 = k0;
;     if (KIND == 4) kd0 = k0 < 1024 ? k0 + 512 : (k0 < 1536 ? k0 - 1024 : k0);
;     const int c = lane & 7;
; #pragma unroll
;     for (int j = 0; j < 4; ++j) { const int n = (lane >> 3) + 8 * j; const LAS float* s = scr + (8 * c) * 33 + n;
;         u32x4 o; o.x = cvtpk(s[0 * 33], s[1 * 33]); o.y = cvtpk(s[2 * 33], s[3 * 33]); o.z = cvtpk(s[4 * 33], s[5 * 33]); o.w = cvtpk(s[6 * 33], s[7 * 33]);
;         *(u32x4*)(WT + (size_t)map_n<KIND>(n0 + n) * ldk + kd0 + 8 * c) = o; }
;     asm volatile("s_waitcnt lgkmcnt(0)" ::: "memory");
; }
.LBB0_701:
	s_andn2_saveexec_b64 s[6:7], s[34:35]
	v_lshl_add_u64 v[4:5], s[16:17], 0, v[128:129]
	s_mov_b64 s[16:17], 0xe0
	v_lshl_add_u64 v[4:5], v[4:5], 0, s[16:17]
	s_or_b64 exec, exec, s[6:7]
	global_load_dword v4, v[4:5], off
	s_movk_i32 s4, 0x600
	v_cmp_gt_u32_e64 s[6:7], s4, v63
	s_waitcnt vmcnt(0)
	v_pk_mul_f32 v[0:1], v[0:1], v[4:5] op_sel_hi:[1,0]
	v_add_u32_e32 v5, 0xc60, v16
	ds_write2_b32 v5, v0, v1 offset1:1
	v_pk_mul_f32 v[0:1], v[2:3], v[4:5] op_sel_hi:[1,0]
	v_add_u32_e32 v2, 0xc68, v16
	ds_write2_b32 v2, v0, v1 offset1:1
	s_waitcnt lgkmcnt(0)
	ds_read2_b32 v[6:7], v58 offset0:33 offset1:41
	ds_read2_b32 v[8:9], v58 offset1:8
	ds_read2_b32 v[10:11], v58 offset0:66 offset1:74
	ds_read2_b32 v[12:13], v58 offset0:99 offset1:107
	ds_read2_b32 v[14:15], v58 offset0:132 offset1:140
	ds_read2_b32 v[16:17], v58 offset0:165 offset1:173
	ds_read2_b32 v[18:19], v58 offset0:198 offset1:206
	ds_read2_b32 v[20:21], v58 offset0:231 offset1:239
	v_add_u32_e32 v1, 0xfffffc00, v64
	v_add_u32_e32 v0, 0x200, v64
	v_cndmask_b32_e64 v1, v64, v1, s[6:7]
	v_cndmask_b32_e32 v128, v1, v0, vcc
	s_waitcnt lgkmcnt(6)
	v_cvt_pk_bf16_f32 v2, v8, v6
	v_or_b32_e32 v6, v53, v32
	v_lshl_add_u64 v[0:1], v[128:129], 1, v[40:41]
	v_lshlrev_b32_e32 v128, 12, v6
	v_or_b32_e32 v6, v53, v51
	s_waitcnt lgkmcnt(4)
	v_cvt_pk_bf16_f32 v3, v10, v12
	s_waitcnt lgkmcnt(2)
	v_cvt_pk_bf16_f32 v4, v14, v16
	s_waitcnt lgkmcnt(0)
	v_cvt_pk_bf16_f32 v5, v18, v20
	v_lshl_add_u64 v[22:23], v[0:1], 0, v[128:129]
	v_lshlrev_b32_e32 v128, 12, v6
	global_store_dwordx4 v[22:23], v[2:5], off sc1
	s_nop 1
	v_cvt_pk_bf16_f32 v2, v9, v7
	v_cvt_pk_bf16_f32 v3, v11, v13
	v_cvt_pk_bf16_f32 v4, v15, v17
	v_cvt_pk_bf16_f32 v5, v19, v21
	v_lshl_add_u64 v[6:7], v[0:1], 0, v[128:129]
	global_store_dwordx4 v[6:7], v[2:5], off sc1
	ds_read2_b32 v[6:7], v58 offset0:49 offset1:57
	ds_read2_b32 v[8:9], v58 offset0:16 offset1:24
	ds_read2_b32 v[10:11], v58 offset0:82 offset1:90
	ds_read2_b32 v[12:13], v58 offset0:115 offset1:123
	ds_read2_b32 v[14:15], v58 offset0:148 offset1:156
	ds_read2_b32 v[16:17], v58 offset0:181 offset1:189
	ds_read2_b32 v[18:19], v58 offset0:214 offset1:222
	ds_read2_b32 v[20:21], v58 offset0:247 offset1:255
	s_waitcnt lgkmcnt(6)
	v_cvt_pk_bf16_f32 v2, v8, v6
	v_or_b32_e32 v6, v53, v56
	v_lshlrev_b32_e32 v128, 12, v6
	v_or_b32_e32 v6, v53, v57
	s_waitcnt lgkmcnt(4)
	v_cvt_pk_bf16_f32 v3, v10, v12
	s_waitcnt lgkmcnt(2)
	v_cvt_pk_bf16_f32 v4, v14, v16
	s_waitcnt lgkmcnt(0)
	v_cvt_pk_bf16_f32 v5, v18, v20
	v_lshl_add_u64 v[22:23], v[0:1], 0, v[128:129]
	v_lshlrev_b32_e32 v128, 12, v6
	global_store_dwordx4 v[22:23], v[2:5], off sc1
	v_lshl_add_u64 v[0:1], v[0:1], 0, v[128:129]
	s_nop 0
	v_cvt_pk_bf16_f32 v2, v9, v7
	v_cvt_pk_bf16_f32 v3, v11, v13
	v_cvt_pk_bf16_f32 v4, v15, v17
	v_cvt_pk_bf16_f32 v5, v19, v21
	global_store_dwordx4 v[0:1], v[2:5], off sc1
	s_waitcnt lgkmcnt(0)

; #define LAS __attribute__((address_space(3)))
; DI unsigned cvtpk(float lo, float hi) { f32x2 v = {lo, hi}; bf16x2_t b = __builtin_convertvector(v, bf16x2_t); return __builtin_bit_cast(unsigned, b); }
; template <int KIND> DI int map_n(int n) {
;     ...
;     if (KIND == 3) return n < 512 ? 2 * n : 2 * (n - 512) + 1;
; template <int KIND>
; DI void transpose_item(const float* W, int K, int N, bf16_t* WT, int ldk, const float* g0, const float* g1, const float* g2, LAS float* scr, int item, int lane) {
;     const int nblk = N / 32, kb = item / nblk, nb = item % nblk, k0 = 64 * kb, n0 = 32 * nb;
;     f32x4 tv[8];
; #pragma unroll
;     for (int i = 0; i < 8; ++i) tv[i] = *(const f32x4*)(W + (size_t)(k0 + 8 * i + (lane >> 3)) * N + n0 + 4 * (lane & 7));
; #pragma unroll
;     for (int i = 0; i < 8; ++i) {
;         const int kk = 8 * i + (lane >> 3), k = k0 + kk;
;         float gn = 1.f;
;         if (KIND == 0 || KIND == 1 || KIND == 2 || KIND == 5 || KIND == 6) gn = g0[k];
;         if (KIND == 4) gn = k < 1024 ? g0[k] : (k < 1536 ? g1[k - 1024] : g2[k - 1536]);
;         LAS float* d = scr + kk * 33 + 4 * (lane & 7);
;         d[0] = tv[i][0] * gn; d[1] = tv[i][1] * gn; d[2] = tv[i][2] * gn; d[3] = tv[i][3] * gn;
;     }
;     asm volatile("s_waitcnt lgkmcnt(0)" ::: "memory");
;     int kd0 = k0;
;     if (KIND == 4) kd0 = k0 < 1024 ? k0 + 512 : (k0 < 1536 ? k0 - 1024 : k0);
;     const int c = lane & 7;
; #pragma unroll
;     for (int j = 0; j < 4; ++j) { const int n = (lane >> 3) + 8 * j; const LAS float* s = scr + (8 * c) * 33 + n;
;         u32x4 o; o.x = cvtpk(s[0 * 33], s[1 * 33]); o.y = cvtpk(s[2 * 33], s[3 * 33]); o.z = cvtpk(s[4 * 33], s[5 * 33]); o.w = cvtpk(s[6 * 33], s[7 * 33]);
;         *(u32x4*)(WT + (size_t)map_n<KIND>(n0 + n) * ldk + kd0 + 8 * c) = o; }
;     asm volatile("s_waitcnt lgkmcnt(0)" ::: "memory");
; }
.LBB0_705:
	s_andn2_saveexec_b64 s[6:7], s[68:69]
	s_cbranch_execz .LBB0_707
	s_load_dwordx2 s[14:15], s[8:9], 0x78
	v_add_u32_e32 v0, 0xfffe4800, v50
	v_and_b32_e32 v54, 0x3c0, v0
	v_and_b32_e32 v53, 0x1c0, v61
	v_lshlrev_b32_e32 v128, 2, v54
	s_waitcnt lgkmcnt(0)
	s_add_u32 s14, s14, s54
	s_addc_u32 s15, s15, s55
	v_or_b32_e32 v2, v53, v32
	v_lshl_add_u64 v[0:1], s[14:15], 0, v[128:129]
	v_lshlrev_b32_e32 v128, 2, v34
	v_lshl_add_u64 v[0:1], v[0:1], 0, v[128:129]
	v_lshlrev_b32_e32 v128, 12, v2
	v_lshl_add_u64 v[28:29], v[0:1], 0, v[128:129]
	s_mov_b32 s4, 0x8000
	v_add_co_u32_e32 v4, vcc, s4, v28
	global_load_dwordx4 v[0:3], v[28:29], off nt
	s_nop 0
	v_addc_co_u32_e32 v5, vcc, 0, v29, vcc
	s_mov_b32 s4, 0x10000
	global_load_dwordx4 v[4:7], v[4:5], off nt
	v_add_co_u32_e32 v8, vcc, s4, v28
	s_mov_b32 s4, 0x18000
	s_nop 0
	v_addc_co_u32_e32 v9, vcc, 0, v29, vcc
	global_load_dwordx4 v[8:11], v[8:9], off nt
	v_add_co_u32_e32 v12, vcc, s4, v28
	s_mov_b32 s4, 0x20000
	s_nop 0
	v_addc_co_u32_e32 v13, vcc, 0, v29, vcc
	global_load_dwordx4 v[12:15], v[12:13], off nt
	v_add_co_u32_e32 v16, vcc, s4, v28
	s_mov_b32 s4, 0x28000
	s_nop 0
	v_addc_co_u32_e32 v17, vcc, 0, v29, vcc
	global_load_dwordx4 v[16:19], v[16:17], off nt
	v_add_co_u32_e32 v20, vcc, s4, v28
	s_mov_b32 s4, 0x30000
	s_nop 0
	v_addc_co_u32_e32 v21, vcc, 0, v29, vcc
	global_load_dwordx4 v[20:23], v[20:21], off nt
	v_add_co_u32_e32 v24, vcc, s4, v28
	s_mov_b32 s4, 0x38000
	s_nop 0
	v_addc_co_u32_e32 v25, vcc, 0, v29, vcc
	global_load_dwordx4 v[24:27], v[24:25], off nt
	v_add_co_u32_e32 v28, vcc, s4, v28
	v_add_u32_e32 v55, v33, v35
	s_nop 0
	v_addc_co_u32_e32 v29, vcc, 0, v29, vcc
	global_load_dwordx4 v[28:31], v[28:29], off nt
	s_movk_i32 s4, 0x200
	v_cmp_gt_u32_e32 vcc, s4, v54
	v_lshlrev_b32_e32 v128, 1, v53
	s_waitcnt vmcnt(7)
	ds_write2_b32 v55, v0, v1 offset1:1
	ds_write2_b32 v55, v2, v3 offset0:2 offset1:3
	v_add_u32_e32 v0, 0x420, v55
	s_waitcnt vmcnt(6)
	ds_write2_b32 v0, v4, v5 offset1:1
	v_add_u32_e32 v0, 0x428, v55
	ds_write2_b32 v0, v6, v7 offset1:1
	v_add_u32_e32 v0, 0x840, v55
	s_waitcnt vmcnt(5)
	ds_write2_b32 v0, v8, v9 offset1:1
	v_add_u32_e32 v0, 0x848, v55
	ds_write2_b32 v0, v10, v11 offset1:1
	v_add_u32_e32 v0, 0xc60, v55
	s_waitcnt vmcnt(4)
	ds_write2_b32 v0, v12, v13 offset1:1
	v_add_u32_e32 v0, 0xc68, v55
	ds_write2_b32 v0, v14, v15 offset1:1
	v_add_u32_e32 v0, 0x1080, v55
	s_waitcnt vmcnt(3)
	ds_write2_b32 v0, v16, v17 offset1:1
	v_add_u32_e32 v0, 0x1088, v55
	ds_write2_b32 v0, v18, v19 offset1:1
	v_add_u32_e32 v0, 0x14a0, v55
	s_waitcnt vmcnt(2)
	ds_write2_b32 v0, v20, v21 offset1:1
	v_add_u32_e32 v0, 0x14a8, v55
	ds_write2_b32 v0, v22, v23 offset1:1
	v_add_u32_e32 v0, 0x18c0, v55
	s_waitcnt vmcnt(1)
	ds_write2_b32 v0, v24, v25 offset1:1
	v_add_u32_e32 v0, 0x18c8, v55
	ds_write2_b32 v0, v26, v27 offset1:1
	v_add_u32_e32 v0, 0x1ce0, v55
	s_waitcnt vmcnt(0)
	ds_write2_b32 v0, v28, v29 offset1:1
	v_add_u32_e32 v0, 0x1ce8, v55
	ds_write2_b32 v0, v30, v31 offset1:1
	s_waitcnt lgkmcnt(0)
	ds_read2_b32 v[6:7], v58 offset0:33 offset1:41
	ds_read2_b32 v[8:9], v58 offset1:8
	ds_read2_b32 v[10:11], v58 offset0:66 offset1:74
	ds_read2_b32 v[12:13], v58 offset0:99 offset1:107
	ds_read2_b32 v[14:15], v58 offset0:132 offset1:140
	ds_read2_b32 v[16:17], v58 offset0:165 offset1:173
	ds_read2_b32 v[18:19], v58 offset0:198 offset1:206
	ds_read2_b32 v[20:21], v58 offset0:231 offset1:239
	v_lshl_add_u64 v[0:1], v[42:43], 0, v[128:129]
	s_waitcnt lgkmcnt(6)
	v_cvt_pk_bf16_f32 v2, v8, v6
	v_or_b32_e32 v6, v54, v32
	v_lshlrev_b32_e32 v6, 1, v6
	v_add_u32_e32 v8, 0xfffffc01, v6
	v_cndmask_b32_e32 v22, v8, v6, vcc
	v_ashrrev_i32_e32 v23, 31, v22
	v_lshlrev_b64 v[22:23], 10, v[22:23]
	v_or_b32_e32 v6, v54, v51
	s_waitcnt lgkmcnt(4)
	v_cvt_pk_bf16_f32 v3, v10, v12
	s_waitcnt lgkmcnt(2)
	v_cvt_pk_bf16_f32 v4, v14, v16
	s_waitcnt lgkmcnt(0)
	v_cvt_pk_bf16_f32 v5, v18, v20
	v_lshl_add_u64 v[22:23], v[0:1], 0, v[22:23]
	v_lshlrev_b32_e32 v6, 1, v6
	global_store_dwordx4 v[22:23], v[2:5], off sc1
	s_nop 1
	v_cvt_pk_bf16_f32 v2, v9, v7
	v_add_u32_e32 v7, 0xfffffc01, v6
	v_cndmask_b32_e32 v6, v7, v6, vcc
	v_ashrrev_i32_e32 v7, 31, v6
	v_lshlrev_b64 v[6:7], 10, v[6:7]
	v_cvt_pk_bf16_f32 v3, v11, v13
	v_cvt_pk_bf16_f32 v4, v15, v17
	v_cvt_pk_bf16_f32 v5, v19, v21
	v_lshl_add_u64 v[6:7], v[0:1], 0, v[6:7]
	global_store_dwordx4 v[6:7], v[2:5], off sc1
	ds_read2_b32 v[6:7], v58 offset0:49 offset1:57
	ds_read2_b32 v[8:9], v58 offset0:16 offset1:24
	ds_read2_b32 v[10:11], v58 offset0:82 offset1:90
	ds_read2_b32 v[12:13], v58 offset0:115 offset1:123
	ds_read2_b32 v[14:15], v58 offset0:148 offset1:156
	ds_read2_b32 v[16:17], v58 offset0:181 offset1:189
	ds_read2_b32 v[18:19], v58 offset0:214 offset1:222
	ds_read2_b32 v[20:21], v58 offset0:247 offset1:255
	s_waitcnt lgkmcnt(6)
	v_cvt_pk_bf16_f32 v2, v8, v6
	v_or_b32_e32 v6, v54, v56
	v_lshlrev_b32_e32 v6, 1, v6
	v_add_u32_e32 v8, 0xfffffc01, v6
	v_cndmask_b32_e32 v22, v8, v6, vcc
	v_ashrrev_i32_e32 v23, 31, v22
	v_lshlrev_b64 v[22:23], 10, v[22:23]
	v_or_b32_e32 v6, v54, v57
	s_waitcnt lgkmcnt(4)
	v_cvt_pk_bf16_f32 v3, v10, v12
	s_waitcnt lgkmcnt(2)
	v_cvt_pk_bf16_f32 v4, v14, v16
	s_waitcnt lgkmcnt(0)
	v_cvt_pk_bf16_f32 v5, v18, v20
	v_lshl_add_u64 v[22:23], v[0:1], 0, v[22:23]
	v_lshlrev_b32_e32 v6, 1, v6
	global_store_dwordx4 v[22:23], v[2:5], off sc1
	s_nop 1
	v_cvt_pk_bf16_f32 v2, v9, v7
	v_add_u32_e32 v7, 0xfffffc01, v6
	v_cndmask_b32_e32 v6, v7, v6, vcc
	v_ashrrev_i32_e32 v7, 31, v6
	v_lshlrev_b64 v[6:7], 10, v[6:7]
	v_cvt_pk_bf16_f32 v3, v11, v13
	v_cvt_pk_bf16_f32 v4, v15, v17
	v_cvt_pk_bf16_f32 v5, v19, v21
	v_lshl_add_u64 v[0:1], v[0:1], 0, v[6:7]
	global_store_dwordx4 v[0:1], v[2:5], off sc1
	s_waitcnt lgkmcnt(0)

; #define LAS __attribute__((address_space(3)))
; DI unsigned cvtpk(float lo, float hi) { f32x2 v = {lo, hi}; bf16x2_t b = __builtin_convertvector(v, bf16x2_t); return __builtin_bit_cast(unsigned, b); }
; template <int KIND>
; DI void transpose_item(const float* W, int K, int N, bf16_t* WT, int ldk, const float* g0, const float* g1, const float* g2, LAS float* scr, int item, int lane) {
;     const int nblk = N / 32, kb = item / nblk, nb = item % nblk, k0 = 64 * kb, n0 = 32 * nb;
;     f32x4 tv[8];
; #pragma unroll
;     for (int i = 0; i < 8; ++i) tv[i] = *(const f32x4*)(W + (size_t)(k0 + 8 * i + (lane >> 3)) * N + n0 + 4 * (lane & 7));
; #pragma unroll
;     for (int i = 0; i < 8; ++i) {
;         const int kk = 8 * i + (lane >> 3), k = k0 + kk;
;         float gn = 1.f;
;         if (KIND == 0 || KIND == 1 || KIND == 2 || KIND == 5 || KIND == 6) gn = g0[k];
;         if (KIND == 4) gn = k < 1024 ? g0[k] : (k < 1536 ? g1[k - 1024] : g2[k - 1536]);
;         LAS float* d = scr + kk * 33 + 4 * (lane & 7);
;         d[0] = tv[i][0] * gn; d[1] = tv[i][1] * gn; d[2] = tv[i][2] * gn; d[3] = tv[i][3] * gn;
;     }
;     asm volatile("s_waitcnt lgkmcnt(0)" ::: "memory");
;     int kd0 = k0;
;     if (KIND == 4) kd0 = k0 < 1024 ? k0 + 512 : (k0 < 1536 ? k0 - 1024 : k0);
;     const int c = lane & 7;
; #pragma unroll
;     for (int j = 0; j < 4; ++j) { const int n = (lane >> 3) + 8 * j; const LAS float* s = scr + (8 * c) * 33 + n;
;         u32x4 o; o.x = cvtpk(s[0 * 33], s[1 * 33]); o.y = cvtpk(s[2 * 33], s[3 * 33]); o.z = cvtpk(s[4 * 33], s[5 * 33]); o.w = cvtpk(s[6 * 33], s[7 * 33]);
;         *(u32x4*)(WT + (size_t)map_n<KIND>(n0 + n) * ldk + kd0 + 8 * c) = o; }
;     asm volatile("s_waitcnt lgkmcnt(0)" ::: "memory");
; }
.LBB0_708:
	s_andn2_saveexec_b64 s[6:7], s[66:67]
	s_cbranch_execz .LBB0_710
	s_load_dwordx4 s[16:19], s[8:9], 0x28
	v_add_u32_e32 v0, 0xfffff340, v62
	v_and_b32_e32 v13, 0xc0, v0
	v_add_u32_e32 v0, 0xfffe6800, v50
	v_and_b32_e32 v12, 0x7c0, v0
	s_waitcnt lgkmcnt(0)
	s_add_u32 s18, s18, s54
	s_addc_u32 s19, s19, s55
	v_lshlrev_b32_e32 v128, 2, v12
	v_or_b32_e32 v30, v13, v32
	v_lshl_add_u64 v[0:1], s[18:19], 0, v[128:129]
	v_lshlrev_b32_e32 v128, 2, v34
	s_add_u32 s14, s16, s60
	v_lshl_add_u64 v[0:1], v[0:1], 0, v[128:129]
	v_lshlrev_b32_e32 v128, 13, v30
	s_addc_u32 s15, s17, s61
	v_lshl_add_u64 v[0:1], v[0:1], 0, v[128:129]
	v_lshlrev_b32_e32 v31, 2, v30
	global_load_dwordx4 v[14:17], v[0:1], off nt
	global_load_dword v30, v31, s[14:15]
	s_mov_b32 s4, 0x10000
	v_add_co_u32_e32 v2, vcc, s4, v0
	v_add_u32_e32 v53, v33, v35
	s_nop 0
	v_addc_co_u32_e32 v3, vcc, 0, v1, vcc
	global_load_dwordx4 v[18:21], v[2:3], off nt
	s_mov_b32 s4, 0x20000
	v_add_co_u32_e32 v2, vcc, s4, v0
	s_mov_b32 s4, 0x30000
	s_nop 0
	v_addc_co_u32_e32 v3, vcc, 0, v1, vcc
	global_load_dwordx4 v[22:25], v[2:3], off nt
	v_add_co_u32_e32 v2, vcc, s4, v0
	s_mov_b32 s4, 0x50000
	s_nop 0
	v_addc_co_u32_e32 v3, vcc, 0, v1, vcc
	global_load_dwordx4 v[26:29], v[2:3], off nt
	v_add_co_u32_e32 v2, vcc, s89, v0
	v_lshlrev_b32_e32 v128, 1, v13
	s_nop 0
	v_addc_co_u32_e32 v3, vcc, 0, v1, vcc
	global_load_dwordx4 v[64:67], v[2:3], off nt
	v_add_co_u32_e32 v2, vcc, s4, v0
	s_mov_b32 s4, 0x60000
	s_nop 0
	v_addc_co_u32_e32 v3, vcc, 0, v1, vcc
	global_load_dwordx4 v[8:11], v[2:3], off nt
	v_add_co_u32_e32 v2, vcc, s4, v0
	s_mov_b32 s4, 0x70000
	s_nop 0
	v_addc_co_u32_e32 v3, vcc, 0, v1, vcc
	global_load_dwordx4 v[4:7], v[2:3], off nt
	v_add_co_u32_e32 v0, vcc, s4, v0
	s_waitcnt vmcnt(6)
	v_pk_mul_f32 v[14:15], v[14:15], v[30:31] op_sel_hi:[1,0]
	ds_write2_b32 v53, v14, v15 offset1:1
	v_pk_mul_f32 v[14:15], v[16:17], v[30:31] op_sel_hi:[1,0]
	ds_write2_b32 v53, v14, v15 offset0:2 offset1:3
	global_load_dword v14, v31, s[14:15] offset:32
	v_addc_co_u32_e32 v1, vcc, 0, v1, vcc
	global_load_dwordx4 v[0:3], v[0:1], off nt
	s_waitcnt vmcnt(1)
	v_pk_mul_f32 v[16:17], v[18:19], v[14:15] op_sel_hi:[1,0]
	v_add_u32_e32 v15, 0x420, v53
	ds_write2_b32 v15, v16, v17 offset1:1
	v_pk_mul_f32 v[14:15], v[20:21], v[14:15] op_sel_hi:[1,0]
	v_add_u32_e32 v16, 0x428, v53
	ds_write2_b32 v16, v14, v15 offset1:1
	global_load_dword v14, v31, s[14:15] offset:64
	v_add_u32_e32 v18, v33, v59
	s_waitcnt vmcnt(0)
	v_pk_mul_f32 v[16:17], v[22:23], v[14:15] op_sel_hi:[1,0]
	v_add_u32_e32 v15, 0x840, v53
	ds_write2_b32 v15, v16, v17 offset1:1
	v_pk_mul_f32 v[14:15], v[24:25], v[14:15] op_sel_hi:[1,0]
	v_add_u32_e32 v16, 0x848, v53
	ds_write2_b32 v16, v14, v15 offset1:1
	global_load_dword v14, v31, s[14:15] offset:96
	s_waitcnt vmcnt(0)
	v_pk_mul_f32 v[16:17], v[26:27], v[14:15] op_sel_hi:[1,0]
	v_add_u32_e32 v15, 0xc60, v53
	ds_write2_b32 v15, v16, v17 offset1:1
	v_pk_mul_f32 v[14:15], v[28:29], v[14:15] op_sel_hi:[1,0]
	v_add_u32_e32 v16, 0xc68, v53
	ds_write2_b32 v16, v14, v15 offset1:1
	global_load_dword v14, v31, s[14:15] offset:128
	s_waitcnt vmcnt(0)
	v_pk_mul_f32 v[16:17], v[64:65], v[14:15] op_sel_hi:[1,0]
	v_pk_mul_f32 v[14:15], v[66:67], v[14:15] op_sel_hi:[1,0]
	ds_write2_b32 v18, v14, v15 offset0:2 offset1:3
	global_load_dword v14, v31, s[14:15] offset:160
	ds_write2_b32 v18, v16, v17 offset1:1
	s_waitcnt vmcnt(0)
	v_pk_mul_f32 v[8:9], v[8:9], v[14:15] op_sel_hi:[1,0]
	v_add_u32_e32 v15, 0x420, v18
	ds_write2_b32 v15, v8, v9 offset1:1
	v_pk_mul_f32 v[8:9], v[10:11], v[14:15] op_sel_hi:[1,0]
	v_add_u32_e32 v10, 0x428, v18
	ds_write2_b32 v10, v8, v9 offset1:1
	global_load_dword v8, v31, s[14:15] offset:192
	s_waitcnt vmcnt(0)
	v_pk_mul_f32 v[4:5], v[4:5], v[8:9] op_sel_hi:[1,0]
	v_add_u32_e32 v9, 0x840, v18
	ds_write2_b32 v9, v4, v5 offset1:1
	v_pk_mul_f32 v[4:5], v[6:7], v[8:9] op_sel_hi:[1,0]
	v_add_u32_e32 v6, 0x848, v18
	ds_write2_b32 v6, v4, v5 offset1:1
	global_load_dword v4, v31, s[14:15] offset:224
	s_waitcnt vmcnt(0)
	v_pk_mul_f32 v[0:1], v[0:1], v[4:5] op_sel_hi:[1,0]
	v_add_u32_e32 v5, 0xc60, v18
	ds_write2_b32 v5, v0, v1 offset1:1
	v_pk_mul_f32 v[0:1], v[2:3], v[4:5] op_sel_hi:[1,0]
	v_add_u32_e32 v2, 0xc68, v18
	ds_write2_b32 v2, v0, v1 offset1:1
	s_waitcnt lgkmcnt(0)
	ds_read2_b32 v[6:7], v58 offset0:33 offset1:41
	ds_read2_b32 v[8:9], v58 offset1:8
	ds_read2_b32 v[10:11], v58 offset0:66 offset1:74
	ds_read2_b32 v[14:15], v58 offset0:99 offset1:107
	ds_read2_b32 v[16:17], v58 offset0:132 offset1:140
	ds_read2_b32 v[18:19], v58 offset0:165 offset1:173
	ds_read2_b32 v[20:21], v58 offset0:198 offset1:206
	ds_read2_b32 v[22:23], v58 offset0:231 offset1:239
	v_lshl_add_u64 v[4:5], v[44:45], 0, v[128:129]
	s_waitcnt lgkmcnt(6)
	v_cvt_pk_bf16_f32 v0, v8, v6
	v_or_b32_e32 v6, v12, v32
	v_lshlrev_b32_e32 v128, 9, v6
	v_or_b32_e32 v6, v12, v51
	s_waitcnt lgkmcnt(4)
	v_cvt_pk_bf16_f32 v1, v10, v14
	s_waitcnt lgkmcnt(2)
	v_cvt_pk_bf16_f32 v2, v16, v18
	s_waitcnt lgkmcnt(0)
	v_cvt_pk_bf16_f32 v3, v20, v22
	v_lshl_add_u64 v[24:25], v[4:5], 0, v[128:129]
	v_lshlrev_b32_e32 v128, 9, v6
	global_store_dwordx4 v[24:25], v[0:3], off sc1
	s_nop 1
	v_cvt_pk_bf16_f32 v0, v9, v7
	v_cvt_pk_bf16_f32 v1, v11, v15
	v_cvt_pk_bf16_f32 v2, v17, v19
	v_cvt_pk_bf16_f32 v3, v21, v23
	v_lshl_add_u64 v[6:7], v[4:5], 0, v[128:129]
	global_store_dwordx4 v[6:7], v[0:3], off sc1
	ds_read2_b32 v[6:7], v58 offset0:49 offset1:57
	ds_read2_b32 v[8:9], v58 offset0:16 offset1:24
	ds_read2_b32 v[10:11], v58 offset0:82 offset1:90
	ds_read2_b32 v[14:15], v58 offset0:115 offset1:123
	ds_read2_b32 v[16:17], v58 offset0:148 offset1:156
	ds_read2_b32 v[18:19], v58 offset0:181 offset1:189
	ds_read2_b32 v[20:21], v58 offset0:214 offset1:222
	ds_read2_b32 v[22:23], v58 offset0:247 offset1:255
	s_waitcnt lgkmcnt(6)
	v_cvt_pk_bf16_f32 v0, v8, v6
	v_or_b32_e32 v6, v12, v56
	v_lshlrev_b32_e32 v128, 9, v6
	v_or_b32_e32 v6, v12, v57
	s_waitcnt lgkmcnt(4)
	v_cvt_pk_bf16_f32 v1, v10, v14
	s_waitcnt lgkmcnt(2)
	v_cvt_pk_bf16_f32 v2, v16, v18
	s_waitcnt lgkmcnt(0)
	v_cvt_pk_bf16_f32 v3, v20, v22
	v_lshl_add_u64 v[24:25], v[4:5], 0, v[128:129]
	v_lshlrev_b32_e32 v128, 9, v6
	global_store_dwordx4 v[24:25], v[0:3], off sc1
	v_lshl_add_u64 v[4:5], v[4:5], 0, v[128:129]
	s_nop 0
	v_cvt_pk_bf16_f32 v0, v9, v7
	v_cvt_pk_bf16_f32 v1, v11, v15
	v_cvt_pk_bf16_f32 v2, v17, v19
	v_cvt_pk_bf16_f32 v3, v21, v23
	global_store_dwordx4 v[4:5], v[0:3], off sc1
	s_waitcnt lgkmcnt(0)

; #define LAS __attribute__((address_space(3)))
; template <int KIND>
; DI void transpose_item(const float* W, int K, int N, bf16_t* WT, int ldk, const float* g0, const float* g1, const float* g2, LAS float* scr, int item, int lane) {
;     const int nblk = N / 32, kb = item / nblk, nb = item % nblk, k0 = 64 * kb, n0 = 32 * nb;
;     f32x4 tv[8];
; #pragma unroll
;     for (int i = 0; i < 8; ++i) tv[i] = *(const f32x4*)(W + (size_t)(k0 + 8 * i + (lane >> 3)) * N + n0 + 4 * (lane & 7));
; #pragma unroll
;     for (int i = 0; i < 8; ++i) {
;         const int kk = 8 * i + (lane >> 3), k = k0 + kk;
;         float gn = 1.f;
;         if (KIND == 0 || KIND == 1 || KIND == 2 || KIND == 5 || KIND == 6) gn = g0[k];
;         if (KIND == 4) gn = k < 1024 ? g0[k] : (k < 1536 ? g1[k - 1024] : g2[k - 1536]);
;         LAS float* d = scr + kk * 33 + 4 * (lane & 7);
;         d[0] = tv[i][0] * gn; d[1] = tv[i][1] * gn; d[2] = tv[i][2] * gn; d[3] = tv[i][3] * gn;
;     }
;     asm volatile("s_waitcnt lgkmcnt(0)" ::: "memory");
.LBB0_711:
	s_andn2_saveexec_b64 s[14:15], s[64:65]
	s_cbranch_execz .LBB0_713
	s_load_dwordx4 s[16:19], s[8:9], 0x18
	v_add_u16_e32 v0, 0xf4c0, v62
	v_mul_u32_u24_e32 v1, 0xaaab, v0
	v_lshrrev_b32_e32 v1, 21, v1
	v_readlane_b32 s6, v255, 1
	v_mul_lo_u16_e32 v2, 48, v1
	s_mul_i32 s4, s6, 0x300000
	v_sub_u16_e32 v0, v0, v2
	s_waitcnt lgkmcnt(0)
	s_add_u32 s18, s18, s4
	s_mul_hi_u32 s4, s6, 0x300000
	v_lshlrev_b16_e32 v13, 6, v1
	v_lshlrev_b16_e32 v12, 5, v0
	v_readlane_b32 s7, v255, 2
	s_addc_u32 s19, s19, s4
	v_or_b32_e32 v30, v32, v13
	v_lshlrev_b32_e32 v128, 2, v12
	s_lshl_b64 s[6:7], s[52:53], 2
	v_lshl_add_u64 v[0:1], s[18:19], 0, v[128:129]
	v_lshlrev_b32_e32 v128, 2, v34
	v_mul_u32_u24_e32 v2, 0x600, v30
	s_add_u32 s6, s16, s6
	v_lshl_add_u64 v[0:1], v[0:1], 0, v[128:129]
	v_lshlrev_b32_e32 v128, 2, v2
	s_addc_u32 s7, s17, s7
	v_lshl_add_u64 v[0:1], v[0:1], 0, v[128:129]
	v_lshlrev_b32_e32 v31, 2, v30
	global_load_dwordx4 v[14:17], v[0:1], off nt
	global_load_dword v30, v31, s[6:7]
	s_mov_b32 s4, 0xc000
	v_add_co_u32_e32 v2, vcc, s4, v0
	v_add_u32_e32 v53, v33, v35
	s_nop 0
	v_addc_co_u32_e32 v3, vcc, 0, v1, vcc
	global_load_dwordx4 v[18:21], v[2:3], off nt
	s_mov_b32 s4, 0x18000
	v_add_co_u32_e32 v2, vcc, s4, v0
	s_mov_b32 s4, 0x24000
	s_nop 0
	v_addc_co_u32_e32 v3, vcc, 0, v1, vcc
	global_load_dwordx4 v[22:25], v[2:3], off nt
	v_add_co_u32_e32 v2, vcc, s4, v0
	s_mov_b32 s4, 0x30000
	s_nop 0
	v_addc_co_u32_e32 v3, vcc, 0, v1, vcc
	global_load_dwordx4 v[26:29], v[2:3], off nt
	v_add_co_u32_e32 v2, vcc, s4, v0
	s_mov_b32 s4, 0x3c000
	s_nop 0
	v_addc_co_u32_e32 v3, vcc, 0, v1, vcc
	global_load_dwordx4 v[64:67], v[2:3], off nt
	v_add_co_u32_e32 v2, vcc, s4, v0
	s_mov_b32 s4, 0x48000
	s_nop 0
	v_addc_co_u32_e32 v3, vcc, 0, v1, vcc
	global_load_dwordx4 v[8:11], v[2:3], off nt
	v_add_co_u32_e32 v2, vcc, s4, v0
	s_mov_b32 s4, 0x54000
	s_nop 0
	v_addc_co_u32_e32 v3, vcc, 0, v1, vcc
	global_load_dwordx4 v[4:7], v[2:3], off nt
	v_add_co_u32_e32 v0, vcc, s4, v0
	s_movk_i32 s16, 0xa0
	s_nop 0
	v_addc_co_u32_e32 v1, vcc, 0, v1, vcc
	global_load_dwordx4 v[0:3], v[0:1], off nt
	v_lshlrev_b32_e32 v128, 1, v13
	s_movk_i32 s4, 0x80
	s_waitcnt vmcnt(7)
	v_pk_mul_f32 v[14:15], v[14:15], v[30:31] op_sel_hi:[1,0]
	ds_write2_b32 v53, v14, v15 offset1:1
	v_pk_mul_f32 v[14:15], v[16:17], v[30:31] op_sel_hi:[1,0]
	ds_write2_b32 v53, v14, v15 offset0:2 offset1:3
	global_load_dword v14, v31, s[6:7] offset:32
	s_waitcnt vmcnt(0)
	v_pk_mul_f32 v[16:17], v[18:19], v[14:15] op_sel_hi:[1,0]
	v_add_u32_e32 v15, 0x420, v53
	ds_write2_b32 v15, v16, v17 offset1:1
	v_pk_mul_f32 v[14:15], v[20:21], v[14:15] op_sel_hi:[1,0]
	v_add_u32_e32 v16, 0x428, v53
	ds_write2_b32 v16, v14, v15 offset1:1
	global_load_dword v14, v31, s[6:7] offset:64
	v_add_u32_e32 v18, v33, v59
	s_waitcnt vmcnt(0)
	v_pk_mul_f32 v[16:17], v[22:23], v[14:15] op_sel_hi:[1,0]
	v_add_u32_e32 v15, 0x840, v53
	ds_write2_b32 v15, v16, v17 offset1:1
	v_pk_mul_f32 v[14:15], v[24:25], v[14:15] op_sel_hi:[1,0]
	v_add_u32_e32 v16, 0x848, v53
	ds_write2_b32 v16, v14, v15 offset1:1
	global_load_dword v14, v31, s[6:7] offset:96
	s_waitcnt vmcnt(0)
	v_pk_mul_f32 v[16:17], v[26:27], v[14:15] op_sel_hi:[1,0]
	v_add_u32_e32 v15, 0xc60, v53
	ds_write2_b32 v15, v16, v17 offset1:1
	v_pk_mul_f32 v[14:15], v[28:29], v[14:15] op_sel_hi:[1,0]
	v_add_u32_e32 v16, 0xc68, v53
	ds_write2_b32 v16, v14, v15 offset1:1
	global_load_dword v14, v31, s[6:7] offset:128
	s_waitcnt vmcnt(0)
	v_pk_mul_f32 v[16:17], v[64:65], v[14:15] op_sel_hi:[1,0]
	v_pk_mul_f32 v[14:15], v[66:67], v[14:15] op_sel_hi:[1,0]
	ds_write2_b32 v18, v14, v15 offset0:2 offset1:3
	global_load_dword v14, v31, s[6:7] offset:160
	ds_write2_b32 v18, v16, v17 offset1:1
	s_waitcnt vmcnt(0)
	v_pk_mul_f32 v[8:9], v[8:9], v[14:15] op_sel_hi:[1,0]
	v_add_u32_e32 v15, 0x420, v18
	ds_write2_b32 v15, v8, v9 offset1:1
	v_pk_mul_f32 v[8:9], v[10:11], v[14:15] op_sel_hi:[1,0]
	v_add_u32_e32 v10, 0x428, v18
	ds_write2_b32 v10, v8, v9 offset1:1
	global_load_dword v8, v31, s[6:7] offset:192
	s_waitcnt vmcnt(0)
; #define LAS __attribute__((address_space(3)))
; DI unsigned cvtpk(float lo, float hi) { f32x2 v = {lo, hi}; bf16x2_t b = __builtin_convertvector(v, bf16x2_t); return __builtin_bit_cast(unsigned, b); }
; template <int KIND> DI int map_n(int n) {
;     ...
;         const int hd = n / 192, w = n % 192;
;         if (w < 128) return n;
;         const int j = w - 128; return hd * 192 + 128 + (j < 32 ? 2 * j : 2 * (j - 32) + 1);
;     }
; template <int KIND>
; DI void transpose_item(const float* W, int K, int N, bf16_t* WT, int ldk, const float* g0, const float* g1, const float* g2, LAS float* scr, int item, int lane) {
;     ...
;     asm volatile("s_waitcnt lgkmcnt(0)" ::: "memory");
;     int kd0 = k0;
;     if (KIND == 4) kd0 = k0 < 1024 ? k0 + 512 : (k0 < 1536 ? k0 - 1024 : k0);
;     const int c = lane & 7;
; #pragma unroll
;     for (int j = 0; j < 4; ++j) { const int n = (lane >> 3) + 8 * j; const LAS float* s = scr + (8 * c) * 33 + n;
;         u32x4 o; o.x = cvtpk(s[0 * 33], s[1 * 33]); o.y = cvtpk(s[2 * 33], s[3 * 33]); o.z = cvtpk(s[4 * 33], s[5 * 33]); o.w = cvtpk(s[6 * 33], s[7 * 33]);
;         *(u32x4*)(WT + (size_t)map_n<KIND>(n0 + n) * ldk + kd0 + 8 * c) = o; }
;     asm volatile("s_waitcnt lgkmcnt(0)" ::: "memory");
; }
	v_pk_mul_f32 v[4:5], v[4:5], v[8:9] op_sel_hi:[1,0]
	v_add_u32_e32 v9, 0x840, v18
	ds_write2_b32 v9, v4, v5 offset1:1
	v_pk_mul_f32 v[4:5], v[6:7], v[8:9] op_sel_hi:[1,0]
	v_add_u32_e32 v6, 0x848, v18
	ds_write2_b32 v6, v4, v5 offset1:1
	global_load_dword v4, v31, s[6:7] offset:224
	s_waitcnt vmcnt(0)
	v_pk_mul_f32 v[0:1], v[0:1], v[4:5] op_sel_hi:[1,0]
	v_add_u32_e32 v5, 0xc60, v18
	ds_write2_b32 v5, v0, v1 offset1:1
	v_pk_mul_f32 v[0:1], v[2:3], v[4:5] op_sel_hi:[1,0]
	v_add_u32_e32 v2, 0xc68, v18
	ds_write2_b32 v2, v0, v1 offset1:1
	s_waitcnt lgkmcnt(0)
	ds_read2_b32 v[6:7], v58 offset0:33 offset1:41
	ds_read2_b32 v[8:9], v58 offset1:8
	ds_read2_b32 v[10:11], v58 offset0:66 offset1:74
	ds_read2_b32 v[14:15], v58 offset0:99 offset1:107
	ds_read2_b32 v[16:17], v58 offset0:132 offset1:140
	ds_read2_b32 v[18:19], v58 offset0:165 offset1:173
	ds_read2_b32 v[20:21], v58 offset0:198 offset1:206
	ds_read2_b32 v[22:23], v58 offset0:231 offset1:239
	v_lshl_add_u64 v[4:5], v[46:47], 0, v[128:129]
	s_waitcnt lgkmcnt(6)
	v_cvt_pk_bf16_f32 v0, v8, v6
	v_or_b32_e32 v6, v32, v12
	v_mul_u32_u24_e32 v8, 0x2aab, v6
	v_lshrrev_b32_e32 v8, 21, v8
	v_mul_lo_u16_e32 v8, 0xc0, v8
	v_sub_u16_e32 v8, v6, v8
	v_cmp_gt_u16_e64 s[6:7], s16, v8
	v_sub_u32_e32 v13, v6, v8
	s_waitcnt lgkmcnt(4)
	v_cvt_pk_bf16_f32 v1, v10, v14
	v_cmp_gt_u16_e32 vcc, s4, v8
	v_cndmask_b32_e64 v10, v201, v202, s[6:7]
	v_lshl_add_u32 v8, v8, 1, v13
	v_add3_u32 v8, v8, v10, s4
	v_cndmask_b32_e32 v24, v8, v6, vcc
	v_ashrrev_i32_e32 v25, 31, v24
	v_lshlrev_b64 v[24:25], 10, v[24:25]
	s_waitcnt lgkmcnt(2)
	v_cvt_pk_bf16_f32 v2, v16, v18
	s_waitcnt lgkmcnt(0)
	v_cvt_pk_bf16_f32 v3, v20, v22
	v_lshl_add_u64 v[24:25], v[4:5], 0, v[24:25]
	v_or_b32_e32 v6, v51, v12
	global_store_dwordx4 v[24:25], v[0:3], off sc1
	s_nop 1
	v_cvt_pk_bf16_f32 v0, v9, v7
	v_mul_u32_u24_e32 v7, 0x2aab, v6
	v_lshrrev_b32_e32 v7, 21, v7
	v_mul_lo_u16_e32 v7, 0xc0, v7
	v_sub_u16_e32 v7, v6, v7
	v_cmp_gt_u16_e64 s[6:7], s16, v7
	v_sub_u32_e32 v9, v6, v7
	v_cmp_gt_u16_e32 vcc, s4, v7
	v_cndmask_b32_e64 v8, v201, v202, s[6:7]
	v_lshl_add_u32 v7, v7, 1, v9
	v_add3_u32 v7, v7, v8, s4
	v_cndmask_b32_e32 v6, v7, v6, vcc
	v_ashrrev_i32_e32 v7, 31, v6
	v_lshlrev_b64 v[6:7], 10, v[6:7]
	v_cvt_pk_bf16_f32 v1, v11, v15
	v_cvt_pk_bf16_f32 v2, v17, v19
	v_cvt_pk_bf16_f32 v3, v21, v23
	v_lshl_add_u64 v[6:7], v[4:5], 0, v[6:7]
	global_store_dwordx4 v[6:7], v[0:3], off sc1
	ds_read2_b32 v[6:7], v58 offset0:16 offset1:24
	ds_read2_b32 v[8:9], v58 offset0:49 offset1:57
	ds_read2_b32 v[10:11], v58 offset0:82 offset1:90
	ds_read2_b32 v[14:15], v58 offset0:115 offset1:123
	ds_read2_b32 v[16:17], v58 offset0:148 offset1:156
	ds_read2_b32 v[18:19], v58 offset0:181 offset1:189
	ds_read2_b32 v[20:21], v58 offset0:214 offset1:222
	ds_read2_b32 v[22:23], v58 offset0:247 offset1:255
	s_waitcnt lgkmcnt(6)
	v_cvt_pk_bf16_f32 v0, v6, v8
	v_or_b32_e32 v6, v56, v12
	v_mul_u32_u24_e32 v8, 0x2aab, v6
	v_lshrrev_b32_e32 v8, 21, v8
	v_mul_lo_u16_e32 v8, 0xc0, v8
	v_sub_u16_e32 v8, v6, v8
	v_cmp_gt_u16_e64 s[6:7], s16, v8
	v_sub_u32_e32 v13, v6, v8
	s_waitcnt lgkmcnt(4)
	v_cvt_pk_bf16_f32 v1, v10, v14
	v_cmp_gt_u16_e32 vcc, s4, v8
	v_cndmask_b32_e64 v10, v201, v202, s[6:7]
	v_lshl_add_u32 v8, v8, 1, v13
	v_add3_u32 v8, v8, v10, s4
	v_cndmask_b32_e32 v24, v8, v6, vcc
	v_ashrrev_i32_e32 v25, 31, v24
	v_lshlrev_b64 v[24:25], 10, v[24:25]
	s_waitcnt lgkmcnt(2)
	v_cvt_pk_bf16_f32 v2, v16, v18
	s_waitcnt lgkmcnt(0)
	v_cvt_pk_bf16_f32 v3, v20, v22
	v_lshl_add_u64 v[24:25], v[4:5], 0, v[24:25]
	v_or_b32_e32 v6, v57, v12
	global_store_dwordx4 v[24:25], v[0:3], off sc1
	s_nop 1
	v_cvt_pk_bf16_f32 v0, v7, v9
	v_mul_u32_u24_e32 v7, 0x2aab, v6
	v_lshrrev_b32_e32 v7, 21, v7
	v_mul_lo_u16_e32 v7, 0xc0, v7
	v_sub_u16_e32 v7, v6, v7
	v_cmp_gt_u16_e64 s[6:7], s16, v7
	v_sub_u32_e32 v9, v6, v7
	v_cmp_gt_u16_e32 vcc, s4, v7
	v_cndmask_b32_e64 v8, v201, v202, s[6:7]
	v_lshl_add_u32 v7, v7, 1, v9
	v_add3_u32 v7, v7, v8, s4
	v_cndmask_b32_e32 v6, v7, v6, vcc
	v_ashrrev_i32_e32 v7, 31, v6
	v_lshlrev_b64 v[6:7], 10, v[6:7]
	v_cvt_pk_bf16_f32 v1, v11, v15
	v_cvt_pk_bf16_f32 v2, v17, v19
	v_cvt_pk_bf16_f32 v3, v21, v23
	v_lshl_add_u64 v[4:5], v[4:5], 0, v[6:7]
	global_store_dwordx4 v[4:5], v[0:3], off sc1
	s_waitcnt lgkmcnt(0)

; #define LAS __attribute__((address_space(3)))
; DI unsigned cvtpk(float lo, float hi) { f32x2 v = {lo, hi}; bf16x2_t b = __builtin_convertvector(v, bf16x2_t); return __builtin_bit_cast(unsigned, b); }
; template <int KIND> DI int map_n(int n) {
;     if (KIND == 0) {
;         if (n < 768) return n;
;         if (n < 832) { const int j = n - 768; return 2816 + (j < 32 ? 2 * j : 2 * (j - 32) + 1); }
;         return n - 64;
;     }
; template <int KIND>
; DI void transpose_item(const float* W, int K, int N, bf16_t* WT, int ldk, const float* g0, const float* g1, const float* g2, LAS float* scr, int item, int lane) {
;     ...
;     for (int j = 0; j < 4; ++j) { const int n = (lane >> 3) + 8 * j; const LAS float* s = scr + (8 * c) * 33 + n;
;         u32x4 o; o.x = cvtpk(s[0 * 33], s[1 * 33]); o.y = cvtpk(s[2 * 33], s[3 * 33]); o.z = cvtpk(s[4 * 33], s[5 * 33]); o.w = cvtpk(s[6 * 33], s[7 * 33]);
;         *(u32x4*)(WT + (size_t)map_n<KIND>(n0 + n) * ldk + kd0 + 8 * c) = o; }
.LBB0_721:
	s_or_b64 exec, exec, s[14:15]
	v_ashrrev_i32_e32 v15, 31, v14
	v_lshl_add_u64 v[0:1], v[10:11], 1, v[48:49]
	s_waitcnt lgkmcnt(3)
	v_cvt_pk_bf16_f32 v2, v2, v3
	s_waitcnt lgkmcnt(2)
	v_cvt_pk_bf16_f32 v3, v4, v5
	s_waitcnt lgkmcnt(1)
	v_cvt_pk_bf16_f32 v4, v6, v7
	v_lshlrev_b64 v[6:7], 12, v[14:15]
	s_waitcnt lgkmcnt(0)
	v_cvt_pk_bf16_f32 v5, v12, v13
	v_lshl_add_u64 v[6:7], v[0:1], 0, v[6:7]
	global_store_dwordx4 v[6:7], v[2:5], off sc1
	ds_read2_b32 v[2:3], v58 offset0:8 offset1:41
	ds_read2_b32 v[4:5], v58 offset0:74 offset1:107
	ds_read2_b32 v[6:7], v58 offset0:140 offset1:173
	ds_read2_b32 v[10:11], v58 offset0:206 offset1:239
	v_add_u32_e32 v13, 8, v9
	s_movk_i32 s4, 0x2ff
	v_or_b32_e32 v12, v17, v51
	v_cmp_lt_i32_e32 vcc, s4, v13
	s_and_saveexec_b64 s[14:15], vcc
	s_cbranch_execz .LBB0_727
	s_movk_i32 s4, 0x33f
	v_cmp_lt_u32_e32 vcc, s4, v8
	s_and_saveexec_b64 s[16:17], vcc
	s_xor_b64 s[16:17], exec, s[16:17]
	v_subrev_u32_e32 v12, 64, v12
	s_andn2_saveexec_b64 s[16:17], s[16:17]
	s_movk_i32 s4, 0x320
	v_cmp_gt_u32_e32 vcc, s4, v8
	s_movk_i32 s4, 0x1680
	v_mul_lo_u32 v13, v16, s4
	v_cndmask_b32_e32 v12, v203, v204, vcc
	v_sub_u32_e32 v12, v12, v13
	s_movk_i32 s4, 0xffe0
	v_add3_u32 v12, v60, v12, s4
	s_or_b64 exec, exec, s[16:17]
.LBB0_727:
	s_or_b64 exec, exec, s[14:15]
	v_ashrrev_i32_e32 v13, 31, v12
	s_waitcnt lgkmcnt(3)
	v_cvt_pk_bf16_f32 v2, v2, v3
	s_waitcnt lgkmcnt(2)
	v_cvt_pk_bf16_f32 v3, v4, v5
	s_waitcnt lgkmcnt(1)
	v_cvt_pk_bf16_f32 v4, v6, v7
	v_lshlrev_b64 v[6:7], 12, v[12:13]
	s_waitcnt lgkmcnt(0)
	v_cvt_pk_bf16_f32 v5, v10, v11
	v_lshl_add_u64 v[6:7], v[0:1], 0, v[6:7]
	global_store_dwordx4 v[6:7], v[2:5], off sc1
	ds_read2_b32 v[2:3], v58 offset0:16 offset1:49
	ds_read2_b32 v[4:5], v58 offset0:82 offset1:115
	ds_read2_b32 v[6:7], v58 offset0:148 offset1:181
	ds_read2_b32 v[10:11], v58 offset0:214 offset1:247
	v_add_u32_e32 v13, 16, v9
	s_movk_i32 s4, 0x2ff
	v_or_b32_e32 v12, v17, v56
	v_cmp_lt_i32_e32 vcc, s4, v13
	s_and_saveexec_b64 s[14:15], vcc
	s_cbranch_execz .LBB0_733
	s_movk_i32 s4, 0x33f
	v_cmp_lt_u32_e32 vcc, s4, v8
	s_and_saveexec_b64 s[16:17], vcc
	s_xor_b64 s[16:17], exec, s[16:17]
	v_subrev_u32_e32 v12, 64, v12
	s_andn2_saveexec_b64 s[16:17], s[16:17]
	s_movk_i32 s4, 0x320
	v_cmp_gt_u32_e32 vcc, s4, v8
	s_movk_i32 s4, 0x1680
	v_mul_lo_u32 v13, v16, s4
	v_cndmask_b32_e32 v12, v203, v204, vcc
	v_sub_u32_e32 v12, v12, v13
	v_add3_u32 v12, v60, v12, -16
	s_or_b64 exec, exec, s[16:17]
.LBB0_733:
	s_or_b64 exec, exec, s[14:15]
	v_ashrrev_i32_e32 v13, 31, v12
	s_waitcnt lgkmcnt(3)
	v_cvt_pk_bf16_f32 v2, v2, v3
	s_waitcnt lgkmcnt(2)
	v_cvt_pk_bf16_f32 v3, v4, v5
	s_waitcnt lgkmcnt(1)
	v_cvt_pk_bf16_f32 v4, v6, v7
	v_lshlrev_b64 v[6:7], 12, v[12:13]
	s_waitcnt lgkmcnt(0)
	v_cvt_pk_bf16_f32 v5, v10, v11
	v_lshl_add_u64 v[6:7], v[0:1], 0, v[6:7]
	global_store_dwordx4 v[6:7], v[2:5], off sc1
	ds_read2_b32 v[2:3], v58 offset0:24 offset1:57
	ds_read2_b32 v[4:5], v58 offset0:90 offset1:123
	ds_read2_b32 v[6:7], v58 offset0:156 offset1:189
	ds_read2_b32 v[10:11], v58 offset0:222 offset1:255
	v_add_u32_e32 v9, 24, v9
	s_movk_i32 s4, 0x2ff
	v_or_b32_e32 v12, v17, v57
	v_cmp_lt_i32_e32 vcc, s4, v9
	s_and_saveexec_b64 s[14:15], vcc
	s_cbranch_execz .LBB0_622
	s_movk_i32 s4, 0x33f
	v_cmp_lt_u32_e32 vcc, s4, v8
	s_and_saveexec_b64 s[16:17], vcc
	s_xor_b64 s[16:17], exec, s[16:17]
	v_subrev_u32_e32 v12, 64, v12
	s_andn2_saveexec_b64 s[16:17], s[16:17]
	s_cbranch_execz .LBB0_621
	s_movk_i32 s4, 0x320
	v_cmp_gt_u32_e32 vcc, s4, v8
	s_movk_i32 s4, 0x1680
	v_mul_lo_u32 v9, v16, s4
	v_cndmask_b32_e32 v8, v203, v204, vcc
	v_sub_u32_e32 v8, v8, v9
	v_add_u32_e32 v12, v60, v8
	s_branch .LBB0_621

; template <int KIND>
; DI void transpose_item(const float* W, int K, int N, bf16_t* WT, int ldk, const float* g0, const float* g1, const float* g2, LAS float* scr, int item, int lane) {
;     const int nblk = N / 32, kb = item / nblk, nb = item % nblk, k0 = 64 * kb, n0 = 32 * nb;
;     f32x4 tv[8];
; #pragma unroll
;     for (int i = 0; i < 8; ++i) tv[i] = *(const f32x4*)(W + (size_t)(k0 + 8 * i + (lane >> 3)) * N + n0 + 4 * (lane & 7));
; #pragma unroll
;     for (int i = 0; i < 8; ++i) {
;         const int kk = 8 * i + (lane >> 3), k = k0 + kk;
;         float gn = 1.f;
;         if (KIND == 0 || KIND == 1 || KIND == 2 || KIND == 5 || KIND == 6) gn = g0[k];
; DI void convert_weights(PP p, LAS unsigned char* lds, int l, int worker, int nworkers) {
;     ...
;     for (int it = worker; it < I_LAYER; it += nworkers) {
;         int r = it;
;         if (r < I_IN) { transpose_item<0>(p->in[2] + (size_t)l * 2048 * 2880, 2048, 2880, (bf16_t*)(wl + W_IN), 2048, p->in[1] + l * 2048, nullptr, nullptr, scr, r, lane); continue; } r -= I_IN;
;         if (r < I_UQ) { transpose_item<1>(p->in[4] + (size_t)l * 512 * 1536, 512, 1536, (bf16_t*)(wl + W_UQ), 512, p->in[3] + l * 512, nullptr, nullptr, scr, r, lane); continue; } r -= I_UQ;
;         if (r < I_UKV) { transpose_item<2>(p->in[6] + (size_t)l * 256 * 2048, 256, 2048, (bf16_t*)(wl + W_UKV), 256, p->in[5] + l * 256, nullptr, nullptr, scr, r, lane); continue; } r -= I_UKV;
;         if (r < I_GLU) { transpose_item<3>(p->in[15] + (size_t)l * 512 * 1024, 512, 1024, (bf16_t*)(wl + W_GLU), 512, nullptr, nullptr, nullptr, scr, r, lane); continue; } r -= I_GLU;
;         if (r < I_O) { transpose_item<4>(p->in[20] + (size_t)l * 2048 * 2048, 2048, 2048, (bf16_t*)(wl + W_O), 2048, p->in[17] + l * 1024, p->in[18] + l * 512, p->in[19] + l * 512, scr, r, lane); continue; } r -= I_O;
;         if (r < I_G) { transpose_item<5>(p->in[22] + (size_t)l * 2048 * DFF_, 2048, DFF_, (bf16_t*)(wl + W_GU), 2048, p->in[21] + l * 2048, nullptr, nullptr, scr, r, lane); continue; } r -= I_G;
;         if (r < I_G) { transpose_item<6>(p->in[23] + (size_t)l * 2048 * DFF_, 2048, DFF_, (bf16_t*)(wl + W_GU), 2048, p->in[21] + l * 2048, nullptr, nullptr, scr, r, lane); continue; } r -= I_G;
;         transpose_item<7>(p->in[24] + (size_t)l * DFF_ * 2048, DFF_, 2048, (bf16_t*)(wl + W_DN), DFF_, nullptr, nullptr, nullptr, scr, r, lane);
.LBB0_1379:
	s_movk_i32 s4, 0xb3f
	v_cmp_lt_i32_e32 vcc, s4, v62
	s_and_saveexec_b64 s[6:7], vcc
	s_xor_b64 s[64:65], exec, s[6:7]
	s_cbranch_execz .LBB0_1469
	s_movk_i32 s4, 0xcbf
	v_cmp_lt_u32_e32 vcc, s4, v62
	s_and_saveexec_b64 s[6:7], vcc
	s_xor_b64 s[66:67], exec, s[6:7]
	s_cbranch_execz .LBB0_1466
	s_movk_i32 s4, 0xdbf
	v_cmp_lt_u32_e32 vcc, s4, v62
	s_and_saveexec_b64 s[6:7], vcc
	s_xor_b64 s[68:69], exec, s[6:7]
	s_cbranch_execz .LBB0_1463
	s_movk_i32 s4, 0xebf
	v_cmp_lt_u32_e32 vcc, s4, v62
	s_and_saveexec_b64 s[6:7], vcc
	s_xor_b64 s[70:71], exec, s[6:7]
	s_cbranch_execz .LBB0_1460
	s_movk_i32 s4, 0x16bf
	v_cmp_lt_u32_e32 vcc, s4, v62
	s_and_saveexec_b64 s[6:7], vcc
	s_xor_b64 s[6:7], exec, s[6:7]
	s_cbranch_execz .LBB0_1393
	s_movk_i32 s4, 0x2cbf
	v_cmp_lt_u32_e32 vcc, s4, v62
	s_and_saveexec_b64 s[14:15], vcc
	s_xor_b64 s[14:15], exec, s[14:15]
	s_cbranch_execz .LBB0_1390
	s_movk_i32 s4, 0x42bf
	v_cmp_lt_u32_e32 vcc, s4, v62
	s_and_saveexec_b64 s[16:17], vcc
	s_xor_b64 s[16:17], exec, s[16:17]
	s_cbranch_execz .LBB0_1387
	s_load_dwordx2 s[18:19], s[8:9], 0xc0
	v_add_u32_e32 v0, 0xffffbd40, v62
	v_and_b32_e32 v53, 0x1fc0, v0
	v_add_u32_e32 v0, 0xfff7a800, v50
	v_and_b32_e32 v54, 0x7e0, v0
	s_waitcnt lgkmcnt(0)
	s_add_u32 s18, s18, s1
	s_addc_u32 s19, s19, s0
	v_lshlrev_b32_e32 v128, 2, v54
	v_or_b32_e32 v2, v53, v32
	v_lshl_add_u64 v[0:1], s[18:19], 0, v[128:129]
	v_lshlrev_b32_e32 v128, 2, v34
	v_lshl_add_u64 v[0:1], v[0:1], 0, v[128:129]
	v_lshlrev_b32_e32 v128, 13, v2
	v_lshl_add_u64 v[28:29], v[0:1], 0, v[128:129]
	s_mov_b32 s4, 0x10000
	v_add_co_u32_e32 v4, vcc, s4, v28
	global_load_dwordx4 v[0:3], v[28:29], off nt
	s_nop 0
	v_addc_co_u32_e32 v5, vcc, 0, v29, vcc
	s_mov_b32 s4, 0x20000
	global_load_dwordx4 v[4:7], v[4:5], off nt
	v_add_co_u32_e32 v8, vcc, s4, v28
	s_mov_b32 s4, 0x30000
	s_nop 0
	v_addc_co_u32_e32 v9, vcc, 0, v29, vcc
	global_load_dwordx4 v[8:11], v[8:9], off nt
	v_add_co_u32_e32 v12, vcc, s4, v28
	s_mov_b32 s4, 0x50000
	s_nop 0
	v_addc_co_u32_e32 v13, vcc, 0, v29, vcc
	global_load_dwordx4 v[12:15], v[12:13], off nt
	v_add_co_u32_e32 v16, vcc, s89, v28
	v_add_u32_e32 v55, v33, v35
	s_nop 0
	v_addc_co_u32_e32 v17, vcc, 0, v29, vcc
	global_load_dwordx4 v[16:19], v[16:17], off nt
	v_add_co_u32_e32 v20, vcc, s4, v28
	s_mov_b32 s4, 0x60000
	s_nop 0
	v_addc_co_u32_e32 v21, vcc, 0, v29, vcc
	global_load_dwordx4 v[20:23], v[20:21], off nt
	v_add_co_u32_e32 v24, vcc, s4, v28
	s_mov_b32 s4, 0x70000
	s_nop 0
	v_addc_co_u32_e32 v25, vcc, 0, v29, vcc
	global_load_dwordx4 v[24:27], v[24:25], off nt
	v_add_co_u32_e32 v28, vcc, s4, v28
	v_lshlrev_b32_e32 v128, 1, v53
	s_nop 0
	v_addc_co_u32_e32 v29, vcc, 0, v29, vcc
	global_load_dwordx4 v[28:31], v[28:29], off nt
	s_waitcnt vmcnt(7)
	ds_write2_b32 v55, v0, v1 offset1:1
	ds_write2_b32 v55, v2, v3 offset0:2 offset1:3
	v_add_u32_e32 v0, 0x420, v55
	s_waitcnt vmcnt(6)
	ds_write2_b32 v0, v4, v5 offset1:1
	v_add_u32_e32 v0, 0x428, v55
	ds_write2_b32 v0, v6, v7 offset1:1
	v_add_u32_e32 v0, 0x840, v55
	s_waitcnt vmcnt(5)
	ds_write2_b32 v0, v8, v9 offset1:1
	v_add_u32_e32 v0, 0x848, v55
	ds_write2_b32 v0, v10, v11 offset1:1
	v_add_u32_e32 v0, 0xc60, v55
	s_waitcnt vmcnt(4)
	ds_write2_b32 v0, v12, v13 offset1:1
	v_add_u32_e32 v0, 0xc68, v55
	ds_write2_b32 v0, v14, v15 offset1:1
	v_add_u32_e32 v0, 0x1080, v55
	s_waitcnt vmcnt(3)
	ds_write2_b32 v0, v16, v17 offset1:1
	v_add_u32_e32 v0, 0x1088, v55
	ds_write2_b32 v0, v18, v19 offset1:1
	v_add_u32_e32 v0, 0x14a0, v55
	s_waitcnt vmcnt(2)
	ds_write2_b32 v0, v20, v21 offset1:1
	v_add_u32_e32 v0, 0x14a8, v55
	ds_write2_b32 v0, v22, v23 offset1:1
	v_add_u32_e32 v0, 0x18c0, v55
	s_waitcnt vmcnt(1)
	ds_write2_b32 v0, v24, v25 offset1:1
	v_add_u32_e32 v0, 0x18c8, v55
	ds_write2_b32 v0, v26, v27 offset1:1
	v_add_u32_e32 v0, 0x1ce0, v55
	s_waitcnt vmcnt(0)
	ds_write2_b32 v0, v28, v29 offset1:1
	v_add_u32_e32 v0, 0x1ce8, v55
	ds_write2_b32 v0, v30, v31 offset1:1
	s_waitcnt lgkmcnt(0)
	ds_read2_b32 v[6:7], v58 offset0:33 offset1:41
	ds_read2_b32 v[8:9], v58 offset1:8
	ds_read2_b32 v[10:11], v58 offset0:66 offset1:74
	ds_read2_b32 v[12:13], v58 offset0:99 offset1:107
	ds_read2_b32 v[14:15], v58 offset0:132 offset1:140
	ds_read2_b32 v[16:17], v58 offset0:165 offset1:173
	ds_read2_b32 v[18:19], v58 offset0:198 offset1:206
	ds_read2_b32 v[20:21], v58 offset0:231 offset1:239
	v_lshl_add_u64 v[0:1], v[36:37], 0, v[128:129]
	s_waitcnt lgkmcnt(6)
	v_cvt_pk_bf16_f32 v2, v8, v6
	v_or_b32_e32 v6, v54, v32
	v_mul_u32_u24_e32 v128, 0x2c00, v6
	v_or_b32_e32 v6, v54, v51
	s_waitcnt lgkmcnt(4)
	v_cvt_pk_bf16_f32 v3, v10, v12
	s_waitcnt lgkmcnt(2)
	v_cvt_pk_bf16_f32 v4, v14, v16
	s_waitcnt lgkmcnt(0)
	v_cvt_pk_bf16_f32 v5, v18, v20
	v_lshl_add_u64 v[22:23], v[0:1], 0, v[128:129]
	v_mul_u32_u24_e32 v128, 0x2c00, v6
	global_store_dwordx4 v[22:23], v[2:5], off sc1
	s_nop 1
	v_cvt_pk_bf16_f32 v2, v9, v7
	v_cvt_pk_bf16_f32 v3, v11, v13
	v_cvt_pk_bf16_f32 v4, v15, v17
	v_cvt_pk_bf16_f32 v5, v19, v21
	v_lshl_add_u64 v[6:7], v[0:1], 0, v[128:129]
	global_store_dwordx4 v[6:7], v[2:5], off sc1
	ds_read2_b32 v[6:7], v58 offset0:16 offset1:24
	ds_read2_b32 v[8:9], v58 offset0:49 offset1:57
	ds_read2_b32 v[10:11], v58 offset0:82 offset1:90
	ds_read2_b32 v[12:13], v58 offset0:115 offset1:123
	ds_read2_b32 v[14:15], v58 offset0:148 offset1:156
	ds_read2_b32 v[16:17], v58 offset0:181 offset1:189
	ds_read2_b32 v[18:19], v58 offset0:214 offset1:222
	ds_read2_b32 v[20:21], v58 offset0:247 offset1:255
	s_waitcnt lgkmcnt(6)
	v_cvt_pk_bf16_f32 v2, v6, v8
	v_or_b32_e32 v6, v54, v56
	v_mul_u32_u24_e32 v128, 0x2c00, v6
	v_or_b32_e32 v6, v54, v57
	s_waitcnt lgkmcnt(4)
	v_cvt_pk_bf16_f32 v3, v10, v12
	s_waitcnt lgkmcnt(2)
	v_cvt_pk_bf16_f32 v4, v14, v16
	s_waitcnt lgkmcnt(0)
	v_cvt_pk_bf16_f32 v5, v18, v20
	v_lshl_add_u64 v[22:23], v[0:1], 0, v[128:129]
	v_mul_u32_u24_e32 v128, 0x2c00, v6
	global_store_dwordx4 v[22:23], v[2:5], off sc1
	v_lshl_add_u64 v[0:1], v[0:1], 0, v[128:129]
	s_nop 0
	v_cvt_pk_bf16_f32 v2, v7, v9
	v_cvt_pk_bf16_f32 v3, v11, v13
	v_cvt_pk_bf16_f32 v4, v15, v17
	v_cvt_pk_bf16_f32 v5, v19, v21
	global_store_dwordx4 v[0:1], v[2:5], off sc1
	s_waitcnt lgkmcnt(0)

; #define LAS __attribute__((address_space(3)))
; DI unsigned cvtpk(float lo, float hi) { f32x2 v = {lo, hi}; bf16x2_t b = __builtin_convertvector(v, bf16x2_t); return __builtin_bit_cast(unsigned, b); }
; template <int KIND>
; DI void transpose_item(const float* W, int K, int N, bf16_t* WT, int ldk, const float* g0, const float* g1, const float* g2, LAS float* scr, int item, int lane) {
;     const int nblk = N / 32, kb = item / nblk, nb = item % nblk, k0 = 64 * kb, n0 = 32 * nb;
;     f32x4 tv[8];
; #pragma unroll
;     for (int i = 0; i < 8; ++i) tv[i] = *(const f32x4*)(W + (size_t)(k0 + 8 * i + (lane >> 3)) * N + n0 + 4 * (lane & 7));
; #pragma unroll
;     for (int i = 0; i < 8; ++i) {
;         const int kk = 8 * i + (lane >> 3), k = k0 + kk;
;         float gn = 1.f;
;         if (KIND == 0 || KIND == 1 || KIND == 2 || KIND == 5 || KIND == 6) gn = g0[k];
;         if (KIND == 4) gn = k < 1024 ? g0[k] : (k < 1536 ? g1[k - 1024] : g2[k - 1536]);
;         LAS float* d = scr + kk * 33 + 4 * (lane & 7);
;         d[0] = tv[i][0] * gn; d[1] = tv[i][1] * gn; d[2] = tv[i][2] * gn; d[3] = tv[i][3] * gn;
;     }
;     asm volatile("s_waitcnt lgkmcnt(0)" ::: "memory");
;     int kd0 = k0;
;     if (KIND == 4) kd0 = k0 < 1024 ? k0 + 512 : (k0 < 1536 ? k0 - 1024 : k0);
;     const int c = lane & 7;
; #pragma unroll
;     for (int j = 0; j < 4; ++j) { const int n = (lane >> 3) + 8 * j; const LAS float* s = scr + (8 * c) * 33 + n;
;         u32x4 o; o.x = cvtpk(s[0 * 33], s[1 * 33]); o.y = cvtpk(s[2 * 33], s[3 * 33]); o.z = cvtpk(s[4 * 33], s[5 * 33]); o.w = cvtpk(s[6 * 33], s[7 * 33]);
;         *(u32x4*)(WT + (size_t)map_n<KIND>(n0 + n) * ldk + kd0 + 8 * c) = o; }
;     asm volatile("s_waitcnt lgkmcnt(0)" ::: "memory");
; }
.LBB0_1460:
	s_andn2_saveexec_b64 s[6:7], s[70:71]
	s_cbranch_execz .LBB0_1462
	s_load_dwordx2 s[14:15], s[8:9], 0x78
	v_add_u32_e32 v0, 0xfffe4800, v50
	v_and_b32_e32 v54, 0x3e0, v0
	v_and_b32_e32 v53, 0x1c0, v61
	v_lshlrev_b32_e32 v128, 2, v54
	s_waitcnt lgkmcnt(0)
	s_add_u32 s14, s14, s56
	s_addc_u32 s15, s15, s57
	v_or_b32_e32 v2, v53, v32
	v_lshl_add_u64 v[0:1], s[14:15], 0, v[128:129]
	v_lshlrev_b32_e32 v128, 2, v34
	v_lshl_add_u64 v[0:1], v[0:1], 0, v[128:129]
	v_lshlrev_b32_e32 v128, 12, v2
	v_lshl_add_u64 v[28:29], v[0:1], 0, v[128:129]
	s_mov_b32 s4, 0x8000
	v_add_co_u32_e32 v4, vcc, s4, v28
	global_load_dwordx4 v[0:3], v[28:29], off nt
	s_nop 0
	v_addc_co_u32_e32 v5, vcc, 0, v29, vcc
	s_mov_b32 s4, 0x10000
	global_load_dwordx4 v[4:7], v[4:5], off nt
	v_add_co_u32_e32 v8, vcc, s4, v28
	s_mov_b32 s4, 0x18000
	s_nop 0
	v_addc_co_u32_e32 v9, vcc, 0, v29, vcc
	global_load_dwordx4 v[8:11], v[8:9], off nt
	v_add_co_u32_e32 v12, vcc, s4, v28
	s_mov_b32 s4, 0x20000
	s_nop 0
	v_addc_co_u32_e32 v13, vcc, 0, v29, vcc
	global_load_dwordx4 v[12:15], v[12:13], off nt
	v_add_co_u32_e32 v16, vcc, s4, v28
	s_mov_b32 s4, 0x28000
	s_nop 0
	v_addc_co_u32_e32 v17, vcc, 0, v29, vcc
	global_load_dwordx4 v[16:19], v[16:17], off nt
	v_add_co_u32_e32 v20, vcc, s4, v28
	s_mov_b32 s4, 0x30000
	s_nop 0
	v_addc_co_u32_e32 v21, vcc, 0, v29, vcc
	global_load_dwordx4 v[20:23], v[20:21], off nt
	v_add_co_u32_e32 v24, vcc, s4, v28
	s_mov_b32 s4, 0x38000
	s_nop 0
	v_addc_co_u32_e32 v25, vcc, 0, v29, vcc
	global_load_dwordx4 v[24:27], v[24:25], off nt
	v_add_co_u32_e32 v28, vcc, s4, v28
	v_add_u32_e32 v55, v33, v35
	s_nop 0
	v_addc_co_u32_e32 v29, vcc, 0, v29, vcc
	global_load_dwordx4 v[28:31], v[28:29], off nt
	s_movk_i32 s4, 0x200
	v_cmp_gt_u32_e32 vcc, s4, v54
	v_lshlrev_b32_e32 v128, 1, v53
	s_waitcnt vmcnt(7)
	ds_write2_b32 v55, v0, v1 offset1:1
	ds_write2_b32 v55, v2, v3 offset0:2 offset1:3
	v_add_u32_e32 v0, 0x420, v55
	s_waitcnt vmcnt(6)
	ds_write2_b32 v0, v4, v5 offset1:1
	v_add_u32_e32 v0, 0x428, v55
	ds_write2_b32 v0, v6, v7 offset1:1
	v_add_u32_e32 v0, 0x840, v55
	s_waitcnt vmcnt(5)
	ds_write2_b32 v0, v8, v9 offset1:1
	v_add_u32_e32 v0, 0x848, v55
	ds_write2_b32 v0, v10, v11 offset1:1
	v_add_u32_e32 v0, 0xc60, v55
	s_waitcnt vmcnt(4)
	ds_write2_b32 v0, v12, v13 offset1:1
	v_add_u32_e32 v0, 0xc68, v55
	ds_write2_b32 v0, v14, v15 offset1:1
	v_add_u32_e32 v0, 0x1080, v55
	s_waitcnt vmcnt(3)
	ds_write2_b32 v0, v16, v17 offset1:1
	v_add_u32_e32 v0, 0x1088, v55
	ds_write2_b32 v0, v18, v19 offset1:1
	v_add_u32_e32 v0, 0x14a0, v55
	s_waitcnt vmcnt(2)
	ds_write2_b32 v0, v20, v21 offset1:1
	v_add_u32_e32 v0, 0x14a8, v55
	ds_write2_b32 v0, v22, v23 offset1:1
	v_add_u32_e32 v0, 0x18c0, v55
	s_waitcnt vmcnt(1)
	ds_write2_b32 v0, v24, v25 offset1:1
	v_add_u32_e32 v0, 0x18c8, v55
	ds_write2_b32 v0, v26, v27 offset1:1
	v_add_u32_e32 v0, 0x1ce0, v55
	s_waitcnt vmcnt(0)
	ds_write2_b32 v0, v28, v29 offset1:1
	v_add_u32_e32 v0, 0x1ce8, v55
	ds_write2_b32 v0, v30, v31 offset1:1
	s_waitcnt lgkmcnt(0)
	ds_read2_b32 v[6:7], v58 offset0:33 offset1:41
	ds_read2_b32 v[8:9], v58 offset1:8
	ds_read2_b32 v[10:11], v58 offset0:66 offset1:74
	ds_read2_b32 v[12:13], v58 offset0:99 offset1:107
	ds_read2_b32 v[14:15], v58 offset0:132 offset1:140
	ds_read2_b32 v[16:17], v58 offset0:165 offset1:173
	ds_read2_b32 v[18:19], v58 offset0:198 offset1:206
	ds_read2_b32 v[20:21], v58 offset0:231 offset1:239
	v_lshl_add_u64 v[0:1], v[42:43], 0, v[128:129]
	s_waitcnt lgkmcnt(6)
	v_cvt_pk_bf16_f32 v2, v8, v6
	v_or_b32_e32 v6, v54, v32
	v_lshlrev_b32_e32 v6, 1, v6
	v_add_u32_e32 v8, 0xfffffc01, v6
	v_cndmask_b32_e32 v22, v8, v6, vcc
	v_ashrrev_i32_e32 v23, 31, v22
	v_lshlrev_b64 v[22:23], 10, v[22:23]
	v_or_b32_e32 v6, v54, v51
	s_waitcnt lgkmcnt(4)
	v_cvt_pk_bf16_f32 v3, v10, v12
	s_waitcnt lgkmcnt(2)
	v_cvt_pk_bf16_f32 v4, v14, v16
	s_waitcnt lgkmcnt(0)
	v_cvt_pk_bf16_f32 v5, v18, v20
	v_lshl_add_u64 v[22:23], v[0:1], 0, v[22:23]
	v_lshlrev_b32_e32 v6, 1, v6
	global_store_dwordx4 v[22:23], v[2:5], off sc1
	s_nop 1
	v_cvt_pk_bf16_f32 v2, v9, v7
	v_add_u32_e32 v7, 0xfffffc01, v6
	v_cndmask_b32_e32 v6, v7, v6, vcc
	v_ashrrev_i32_e32 v7, 31, v6
	v_lshlrev_b64 v[6:7], 10, v[6:7]
	v_cvt_pk_bf16_f32 v3, v11, v13
	v_cvt_pk_bf16_f32 v4, v15, v17
	v_cvt_pk_bf16_f32 v5, v19, v21
	v_lshl_add_u64 v[6:7], v[0:1], 0, v[6:7]
	global_store_dwordx4 v[6:7], v[2:5], off sc1
	ds_read2_b32 v[6:7], v58 offset0:49 offset1:57
	ds_read2_b32 v[8:9], v58 offset0:16 offset1:24
	ds_read2_b32 v[10:11], v58 offset0:82 offset1:90
	ds_read2_b32 v[12:13], v58 offset0:115 offset1:123
	ds_read2_b32 v[14:15], v58 offset0:148 offset1:156
	ds_read2_b32 v[16:17], v58 offset0:181 offset1:189
	ds_read2_b32 v[18:19], v58 offset0:214 offset1:222
	ds_read2_b32 v[20:21], v58 offset0:247 offset1:255
	s_waitcnt lgkmcnt(6)
	v_cvt_pk_bf16_f32 v2, v8, v6
	v_or_b32_e32 v6, v54, v56
	v_lshlrev_b32_e32 v6, 1, v6
	v_add_u32_e32 v8, 0xfffffc01, v6
	v_cndmask_b32_e32 v22, v8, v6, vcc
	v_ashrrev_i32_e32 v23, 31, v22
	v_lshlrev_b64 v[22:23], 10, v[22:23]
	v_or_b32_e32 v6, v54, v57
	s_waitcnt lgkmcnt(4)
	v_cvt_pk_bf16_f32 v3, v10, v12
	s_waitcnt lgkmcnt(2)
	v_cvt_pk_bf16_f32 v4, v14, v16
	s_waitcnt lgkmcnt(0)
	v_cvt_pk_bf16_f32 v5, v18, v20
	v_lshl_add_u64 v[22:23], v[0:1], 0, v[22:23]
	v_lshlrev_b32_e32 v6, 1, v6
	global_store_dwordx4 v[22:23], v[2:5], off sc1
	s_nop 1
	v_cvt_pk_bf16_f32 v2, v9, v7
	v_add_u32_e32 v7, 0xfffffc01, v6
	v_cndmask_b32_e32 v6, v7, v6, vcc
	v_ashrrev_i32_e32 v7, 31, v6
	v_lshlrev_b64 v[6:7], 10, v[6:7]
	v_cvt_pk_bf16_f32 v3, v11, v13
	v_cvt_pk_bf16_f32 v4, v15, v17
	v_cvt_pk_bf16_f32 v5, v19, v21
	v_lshl_add_u64 v[0:1], v[0:1], 0, v[6:7]
	global_store_dwordx4 v[0:1], v[2:5], off sc1
	s_waitcnt lgkmcnt(0)

; #define LAS __attribute__((address_space(3)))
; DI unsigned cvtpk(float lo, float hi) { f32x2 v = {lo, hi}; bf16x2_t b = __builtin_convertvector(v, bf16x2_t); return __builtin_bit_cast(unsigned, b); }
; template <int KIND>
; DI void transpose_item(const float* W, int K, int N, bf16_t* WT, int ldk, const float* g0, const float* g1, const float* g2, LAS float* scr, int item, int lane) {
;     const int nblk = N / 32, kb = item / nblk, nb = item % nblk, k0 = 64 * kb, n0 = 32 * nb;
;     f32x4 tv[8];
; #pragma unroll
;     for (int i = 0; i < 8; ++i) tv[i] = *(const f32x4*)(W + (size_t)(k0 + 8 * i + (lane >> 3)) * N + n0 + 4 * (lane & 7));
; #pragma unroll
;     for (int i = 0; i < 8; ++i) {
;         const int kk = 8 * i + (lane >> 3), k = k0 + kk;
;         float gn = 1.f;
;         if (KIND == 0 || KIND == 1 || KIND == 2 || KIND == 5 || KIND == 6) gn = g0[k];
;         if (KIND == 4) gn = k < 1024 ? g0[k] : (k < 1536 ? g1[k - 1024] : g2[k - 1536]);
;         LAS float* d = scr + kk * 33 + 4 * (lane & 7);
;         d[0] = tv[i][0] * gn; d[1] = tv[i][1] * gn; d[2] = tv[i][2] * gn; d[3] = tv[i][3] * gn;
;     }
;     asm volatile("s_waitcnt lgkmcnt(0)" ::: "memory");
;     int kd0 = k0;
;     if (KIND == 4) kd0 = k0 < 1024 ? k0 + 512 : (k0 < 1536 ? k0 - 1024 : k0);
;     const int c = lane & 7;
; #pragma unroll
;     for (int j = 0; j < 4; ++j) { const int n = (lane >> 3) + 8 * j; const LAS float* s = scr + (8 * c) * 33 + n;
;         u32x4 o; o.x = cvtpk(s[0 * 33], s[1 * 33]); o.y = cvtpk(s[2 * 33], s[3 * 33]); o.z = cvtpk(s[4 * 33], s[5 * 33]); o.w = cvtpk(s[6 * 33], s[7 * 33]);
;         *(u32x4*)(WT + (size_t)map_n<KIND>(n0 + n) * ldk + kd0 + 8 * c) = o; }
;     asm volatile("s_waitcnt lgkmcnt(0)" ::: "memory");
; }
.LBB0_1463:
	s_andn2_saveexec_b64 s[6:7], s[68:69]
	s_cbranch_execz .LBB0_1465
	s_load_dwordx4 s[16:19], s[8:9], 0x28
	v_add_u32_e32 v0, 0xfffff340, v62
	v_and_b32_e32 v13, 0xc0, v0
	v_add_u32_e32 v0, 0xfffe6800, v50
	v_and_b32_e32 v12, 0x7e0, v0
	s_waitcnt lgkmcnt(0)
	s_add_u32 s18, s18, s56
	s_addc_u32 s19, s19, s57
	v_lshlrev_b32_e32 v128, 2, v12
	v_or_b32_e32 v30, v13, v32
	v_lshl_add_u64 v[0:1], s[18:19], 0, v[128:129]
	v_lshlrev_b32_e32 v128, 2, v34
	s_add_u32 s14, s16, s62
	v_lshl_add_u64 v[0:1], v[0:1], 0, v[128:129]
	v_lshlrev_b32_e32 v128, 13, v30
	s_addc_u32 s15, s17, s63
	v_lshl_add_u64 v[0:1], v[0:1], 0, v[128:129]
	v_lshlrev_b32_e32 v31, 2, v30
	global_load_dwordx4 v[14:17], v[0:1], off nt
	global_load_dword v30, v31, s[14:15]
	s_mov_b32 s4, 0x10000
	v_add_co_u32_e32 v2, vcc, s4, v0
	v_add_u32_e32 v53, v33, v35
	s_nop 0
	v_addc_co_u32_e32 v3, vcc, 0, v1, vcc
	global_load_dwordx4 v[18:21], v[2:3], off nt
	s_mov_b32 s4, 0x20000
	v_add_co_u32_e32 v2, vcc, s4, v0
	s_mov_b32 s4, 0x30000
	s_nop 0
	v_addc_co_u32_e32 v3, vcc, 0, v1, vcc
	global_load_dwordx4 v[22:25], v[2:3], off nt
	v_add_co_u32_e32 v2, vcc, s4, v0
	s_mov_b32 s4, 0x50000
	s_nop 0
	v_addc_co_u32_e32 v3, vcc, 0, v1, vcc
	global_load_dwordx4 v[26:29], v[2:3], off nt
	v_add_co_u32_e32 v2, vcc, s89, v0
	v_lshlrev_b32_e32 v128, 1, v13
	s_nop 0
	v_addc_co_u32_e32 v3, vcc, 0, v1, vcc
	global_load_dwordx4 v[64:67], v[2:3], off nt
	v_add_co_u32_e32 v2, vcc, s4, v0
	s_mov_b32 s4, 0x60000
	s_nop 0
	v_addc_co_u32_e32 v3, vcc, 0, v1, vcc
	global_load_dwordx4 v[8:11], v[2:3], off nt
	v_add_co_u32_e32 v2, vcc, s4, v0
	s_mov_b32 s4, 0x70000
	s_nop 0
	v_addc_co_u32_e32 v3, vcc, 0, v1, vcc
	global_load_dwordx4 v[4:7], v[2:3], off nt
	v_add_co_u32_e32 v0, vcc, s4, v0
	s_waitcnt vmcnt(6)
	v_pk_mul_f32 v[14:15], v[14:15], v[30:31] op_sel_hi:[1,0]
	ds_write2_b32 v53, v14, v15 offset1:1
	v_pk_mul_f32 v[14:15], v[16:17], v[30:31] op_sel_hi:[1,0]
	ds_write2_b32 v53, v14, v15 offset0:2 offset1:3
	global_load_dword v14, v31, s[14:15] offset:32
	v_addc_co_u32_e32 v1, vcc, 0, v1, vcc
	global_load_dwordx4 v[0:3], v[0:1], off nt
	s_waitcnt vmcnt(1)
	v_pk_mul_f32 v[16:17], v[18:19], v[14:15] op_sel_hi:[1,0]
	v_add_u32_e32 v15, 0x420, v53
	ds_write2_b32 v15, v16, v17 offset1:1
	v_pk_mul_f32 v[14:15], v[20:21], v[14:15] op_sel_hi:[1,0]
	v_add_u32_e32 v16, 0x428, v53
	ds_write2_b32 v16, v14, v15 offset1:1
	global_load_dword v14, v31, s[14:15] offset:64
	v_add_u32_e32 v18, v33, v59
	s_waitcnt vmcnt(0)
	v_pk_mul_f32 v[16:17], v[22:23], v[14:15] op_sel_hi:[1,0]
	v_add_u32_e32 v15, 0x840, v53
	ds_write2_b32 v15, v16, v17 offset1:1
	v_pk_mul_f32 v[14:15], v[24:25], v[14:15] op_sel_hi:[1,0]
	v_add_u32_e32 v16, 0x848, v53
	ds_write2_b32 v16, v14, v15 offset1:1
	global_load_dword v14, v31, s[14:15] offset:96
	s_waitcnt vmcnt(0)
	v_pk_mul_f32 v[16:17], v[26:27], v[14:15] op_sel_hi:[1,0]
	v_add_u32_e32 v15, 0xc60, v53
	ds_write2_b32 v15, v16, v17 offset1:1
	v_pk_mul_f32 v[14:15], v[28:29], v[14:15] op_sel_hi:[1,0]
	v_add_u32_e32 v16, 0xc68, v53
	ds_write2_b32 v16, v14, v15 offset1:1
	global_load_dword v14, v31, s[14:15] offset:128
	s_waitcnt vmcnt(0)
	v_pk_mul_f32 v[16:17], v[64:65], v[14:15] op_sel_hi:[1,0]
	v_pk_mul_f32 v[14:15], v[66:67], v[14:15] op_sel_hi:[1,0]
	ds_write2_b32 v18, v14, v15 offset0:2 offset1:3
	global_load_dword v14, v31, s[14:15] offset:160
	ds_write2_b32 v18, v16, v17 offset1:1
	s_waitcnt vmcnt(0)
	v_pk_mul_f32 v[8:9], v[8:9], v[14:15] op_sel_hi:[1,0]
	v_add_u32_e32 v15, 0x420, v18
	ds_write2_b32 v15, v8, v9 offset1:1
	v_pk_mul_f32 v[8:9], v[10:11], v[14:15] op_sel_hi:[1,0]
	v_add_u32_e32 v10, 0x428, v18
	ds_write2_b32 v10, v8, v9 offset1:1
	global_load_dword v8, v31, s[14:15] offset:192
	s_waitcnt vmcnt(0)
	v_pk_mul_f32 v[4:5], v[4:5], v[8:9] op_sel_hi:[1,0]
	v_add_u32_e32 v9, 0x840, v18
	ds_write2_b32 v9, v4, v5 offset1:1
	v_pk_mul_f32 v[4:5], v[6:7], v[8:9] op_sel_hi:[1,0]
	v_add_u32_e32 v6, 0x848, v18
	ds_write2_b32 v6, v4, v5 offset1:1
	global_load_dword v4, v31, s[14:15] offset:224
	s_waitcnt vmcnt(0)
	v_pk_mul_f32 v[0:1], v[0:1], v[4:5] op_sel_hi:[1,0]
	v_add_u32_e32 v5, 0xc60, v18
	ds_write2_b32 v5, v0, v1 offset1:1
	v_pk_mul_f32 v[0:1], v[2:3], v[4:5] op_sel_hi:[1,0]
	v_add_u32_e32 v2, 0xc68, v18
	ds_write2_b32 v2, v0, v1 offset1:1
	s_waitcnt lgkmcnt(0)
	ds_read2_b32 v[6:7], v58 offset0:33 offset1:41
	ds_read2_b32 v[8:9], v58 offset1:8
	ds_read2_b32 v[10:11], v58 offset0:66 offset1:74
	ds_read2_b32 v[14:15], v58 offset0:99 offset1:107
	ds_read2_b32 v[16:17], v58 offset0:132 offset1:140
	ds_read2_b32 v[18:19], v58 offset0:165 offset1:173
	ds_read2_b32 v[20:21], v58 offset0:198 offset1:206
	ds_read2_b32 v[22:23], v58 offset0:231 offset1:239
	v_lshl_add_u64 v[4:5], v[44:45], 0, v[128:129]
	s_waitcnt lgkmcnt(6)
	v_cvt_pk_bf16_f32 v0, v8, v6
	v_or_b32_e32 v6, v12, v32
	v_lshlrev_b32_e32 v128, 9, v6
	v_or_b32_e32 v6, v12, v51
	s_waitcnt lgkmcnt(4)
	v_cvt_pk_bf16_f32 v1, v10, v14
	s_waitcnt lgkmcnt(2)
	v_cvt_pk_bf16_f32 v2, v16, v18
	s_waitcnt lgkmcnt(0)
	v_cvt_pk_bf16_f32 v3, v20, v22
	v_lshl_add_u64 v[24:25], v[4:5], 0, v[128:129]
	v_lshlrev_b32_e32 v128, 9, v6
	global_store_dwordx4 v[24:25], v[0:3], off sc1
	s_nop 1
	v_cvt_pk_bf16_f32 v0, v9, v7
	v_cvt_pk_bf16_f32 v1, v11, v15
	v_cvt_pk_bf16_f32 v2, v17, v19
	v_cvt_pk_bf16_f32 v3, v21, v23
	v_lshl_add_u64 v[6:7], v[4:5], 0, v[128:129]
	global_store_dwordx4 v[6:7], v[0:3], off sc1
	ds_read2_b32 v[6:7], v58 offset0:49 offset1:57
	ds_read2_b32 v[8:9], v58 offset0:16 offset1:24
	ds_read2_b32 v[10:11], v58 offset0:82 offset1:90
	ds_read2_b32 v[14:15], v58 offset0:115 offset1:123
	ds_read2_b32 v[16:17], v58 offset0:148 offset1:156
	ds_read2_b32 v[18:19], v58 offset0:181 offset1:189
	ds_read2_b32 v[20:21], v58 offset0:214 offset1:222
	ds_read2_b32 v[22:23], v58 offset0:247 offset1:255
	s_waitcnt lgkmcnt(6)
	v_cvt_pk_bf16_f32 v0, v8, v6
	v_or_b32_e32 v6, v12, v56
	v_lshlrev_b32_e32 v128, 9, v6
	v_or_b32_e32 v6, v12, v57
	s_waitcnt lgkmcnt(4)
	v_cvt_pk_bf16_f32 v1, v10, v14
	s_waitcnt lgkmcnt(2)
	v_cvt_pk_bf16_f32 v2, v16, v18
	s_waitcnt lgkmcnt(0)
	v_cvt_pk_bf16_f32 v3, v20, v22
	v_lshl_add_u64 v[24:25], v[4:5], 0, v[128:129]
	v_lshlrev_b32_e32 v128, 9, v6
	global_store_dwordx4 v[24:25], v[0:3], off sc1
	v_lshl_add_u64 v[4:5], v[4:5], 0, v[128:129]
	s_nop 0
	v_cvt_pk_bf16_f32 v0, v9, v7
	v_cvt_pk_bf16_f32 v1, v11, v15
	v_cvt_pk_bf16_f32 v2, v17, v19
	v_cvt_pk_bf16_f32 v3, v21, v23
	global_store_dwordx4 v[4:5], v[0:3], off sc1
	s_waitcnt lgkmcnt(0)

; #define LAS __attribute__((address_space(3)))
; template <int KIND>
; DI void transpose_item(const float* W, int K, int N, bf16_t* WT, int ldk, const float* g0, const float* g1, const float* g2, LAS float* scr, int item, int lane) {
;     const int nblk = N / 32, kb = item / nblk, nb = item % nblk, k0 = 64 * kb, n0 = 32 * nb;
;     f32x4 tv[8];
; #pragma unroll
;     for (int i = 0; i < 8; ++i) tv[i] = *(const f32x4*)(W + (size_t)(k0 + 8 * i + (lane >> 3)) * N + n0 + 4 * (lane & 7));
; #pragma unroll
;     for (int i = 0; i < 8; ++i) {
;         const int kk = 8 * i + (lane >> 3), k = k0 + kk;
;         float gn = 1.f;
;         if (KIND == 0 || KIND == 1 || KIND == 2 || KIND == 5 || KIND == 6) gn = g0[k];
;         if (KIND == 4) gn = k < 1024 ? g0[k] : (k < 1536 ? g1[k - 1024] : g2[k - 1536]);
;         LAS float* d = scr + kk * 33 + 4 * (lane & 7);
;         d[0] = tv[i][0] * gn; d[1] = tv[i][1] * gn; d[2] = tv[i][2] * gn; d[3] = tv[i][3] * gn;
;     }
;     asm volatile("s_waitcnt lgkmcnt(0)" ::: "memory");
.LBB0_1466:
	s_andn2_saveexec_b64 s[14:15], s[66:67]
	s_cbranch_execz .LBB0_1468
	s_load_dwordx4 s[16:19], s[8:9], 0x18
	v_add_u16_e32 v0, 0xf4c0, v62
	v_mul_u32_u24_e32 v1, 0xaaab, v0
	v_lshrrev_b32_e32 v1, 21, v1
	v_readlane_b32 s6, v255, 1
	v_mul_lo_u16_e32 v2, 48, v1
	s_mul_i32 s4, s6, 0x300000
	v_sub_u16_e32 v0, v0, v2
	s_waitcnt lgkmcnt(0)
	s_add_u32 s18, s18, s4
	s_mul_hi_u32 s4, s6, 0x300000
	v_lshlrev_b16_e32 v13, 6, v1
	v_lshlrev_b16_e32 v12, 5, v0
	v_readlane_b32 s7, v255, 2
	s_addc_u32 s19, s19, s4
	v_or_b32_e32 v30, v32, v13
	v_lshlrev_b32_e32 v128, 2, v12
	s_lshl_b64 s[6:7], s[44:45], 2
	v_lshl_add_u64 v[0:1], s[18:19], 0, v[128:129]
	v_lshlrev_b32_e32 v128, 2, v34
	v_mul_u32_u24_e32 v2, 0x600, v30
	s_add_u32 s6, s16, s6
	v_lshl_add_u64 v[0:1], v[0:1], 0, v[128:129]
	v_lshlrev_b32_e32 v128, 2, v2
	s_addc_u32 s7, s17, s7
	v_lshl_add_u64 v[0:1], v[0:1], 0, v[128:129]
	v_lshlrev_b32_e32 v31, 2, v30
	global_load_dwordx4 v[14:17], v[0:1], off nt
	global_load_dword v30, v31, s[6:7]
	s_mov_b32 s4, 0xc000
	v_add_co_u32_e32 v2, vcc, s4, v0
	v_add_u32_e32 v53, v33, v35
	s_nop 0
	v_addc_co_u32_e32 v3, vcc, 0, v1, vcc
	global_load_dwordx4 v[18:21], v[2:3], off nt
	s_mov_b32 s4, 0x18000
	v_add_co_u32_e32 v2, vcc, s4, v0
	s_mov_b32 s4, 0x24000
	s_nop 0
	v_addc_co_u32_e32 v3, vcc, 0, v1, vcc
	global_load_dwordx4 v[22:25], v[2:3], off nt
	v_add_co_u32_e32 v2, vcc, s4, v0
	s_mov_b32 s4, 0x30000
	s_nop 0
	v_addc_co_u32_e32 v3, vcc, 0, v1, vcc
	global_load_dwordx4 v[26:29], v[2:3], off nt
	v_add_co_u32_e32 v2, vcc, s4, v0
	s_mov_b32 s4, 0x3c000
	s_nop 0
	v_addc_co_u32_e32 v3, vcc, 0, v1, vcc
	global_load_dwordx4 v[64:67], v[2:3], off nt
	v_add_co_u32_e32 v2, vcc, s4, v0
	s_mov_b32 s4, 0x48000
	s_nop 0
	v_addc_co_u32_e32 v3, vcc, 0, v1, vcc
	global_load_dwordx4 v[8:11], v[2:3], off nt
	v_add_co_u32_e32 v2, vcc, s4, v0
	s_mov_b32 s4, 0x54000
	s_nop 0
	v_addc_co_u32_e32 v3, vcc, 0, v1, vcc
	global_load_dwordx4 v[4:7], v[2:3], off nt
	v_add_co_u32_e32 v0, vcc, s4, v0
	s_movk_i32 s16, 0xa0
	s_nop 0
	v_addc_co_u32_e32 v1, vcc, 0, v1, vcc
	global_load_dwordx4 v[0:3], v[0:1], off nt
	v_lshlrev_b32_e32 v128, 1, v13
	s_movk_i32 s4, 0x80
	s_waitcnt vmcnt(7)
	v_pk_mul_f32 v[14:15], v[14:15], v[30:31] op_sel_hi:[1,0]
	ds_write2_b32 v53, v14, v15 offset1:1
	v_pk_mul_f32 v[14:15], v[16:17], v[30:31] op_sel_hi:[1,0]
	ds_write2_b32 v53, v14, v15 offset0:2 offset1:3
	global_load_dword v14, v31, s[6:7] offset:32
	s_waitcnt vmcnt(0)
	v_pk_mul_f32 v[16:17], v[18:19], v[14:15] op_sel_hi:[1,0]
	v_add_u32_e32 v15, 0x420, v53
	ds_write2_b32 v15, v16, v17 offset1:1
	v_pk_mul_f32 v[14:15], v[20:21], v[14:15] op_sel_hi:[1,0]
	v_add_u32_e32 v16, 0x428, v53
	ds_write2_b32 v16, v14, v15 offset1:1
	global_load_dword v14, v31, s[6:7] offset:64
	v_add_u32_e32 v18, v33, v59
	s_waitcnt vmcnt(0)
	v_pk_mul_f32 v[16:17], v[22:23], v[14:15] op_sel_hi:[1,0]
	v_add_u32_e32 v15, 0x840, v53
	ds_write2_b32 v15, v16, v17 offset1:1
	v_pk_mul_f32 v[14:15], v[24:25], v[14:15] op_sel_hi:[1,0]
	v_add_u32_e32 v16, 0x848, v53
	ds_write2_b32 v16, v14, v15 offset1:1
	global_load_dword v14, v31, s[6:7] offset:96
	s_waitcnt vmcnt(0)
	v_pk_mul_f32 v[16:17], v[26:27], v[14:15] op_sel_hi:[1,0]
	v_add_u32_e32 v15, 0xc60, v53
	ds_write2_b32 v15, v16, v17 offset1:1
	v_pk_mul_f32 v[14:15], v[28:29], v[14:15] op_sel_hi:[1,0]
	v_add_u32_e32 v16, 0xc68, v53
	ds_write2_b32 v16, v14, v15 offset1:1
	global_load_dword v14, v31, s[6:7] offset:128
	s_waitcnt vmcnt(0)
	v_pk_mul_f32 v[16:17], v[64:65], v[14:15] op_sel_hi:[1,0]
	v_pk_mul_f32 v[14:15], v[66:67], v[14:15] op_sel_hi:[1,0]
	ds_write2_b32 v18, v14, v15 offset0:2 offset1:3
	global_load_dword v14, v31, s[6:7] offset:160
	ds_write2_b32 v18, v16, v17 offset1:1
	s_waitcnt vmcnt(0)
	v_pk_mul_f32 v[8:9], v[8:9], v[14:15] op_sel_hi:[1,0]
	v_add_u32_e32 v15, 0x420, v18
	ds_write2_b32 v15, v8, v9 offset1:1
	v_pk_mul_f32 v[8:9], v[10:11], v[14:15] op_sel_hi:[1,0]
	v_add_u32_e32 v10, 0x428, v18
	ds_write2_b32 v10, v8, v9 offset1:1
	global_load_dword v8, v31, s[6:7] offset:192
	s_waitcnt vmcnt(0)
; #define LAS __attribute__((address_space(3)))
; DI unsigned cvtpk(float lo, float hi) { f32x2 v = {lo, hi}; bf16x2_t b = __builtin_convertvector(v, bf16x2_t); return __builtin_bit_cast(unsigned, b); }
; template <int KIND> DI int map_n(int n) {
;     ...
;         const int hd = n / 192, w = n % 192;
;         if (w < 128) return n;
;         const int j = w - 128; return hd * 192 + 128 + (j < 32 ? 2 * j : 2 * (j - 32) + 1);
;     }
; template <int KIND>
; DI void transpose_item(const float* W, int K, int N, bf16_t* WT, int ldk, const float* g0, const float* g1, const float* g2, LAS float* scr, int item, int lane) {
;     ...
;     asm volatile("s_waitcnt lgkmcnt(0)" ::: "memory");
;     int kd0 = k0;
;     if (KIND == 4) kd0 = k0 < 1024 ? k0 + 512 : (k0 < 1536 ? k0 - 1024 : k0);
;     const int c = lane & 7;
; #pragma unroll
;     for (int j = 0; j < 4; ++j) { const int n = (lane >> 3) + 8 * j; const LAS float* s = scr + (8 * c) * 33 + n;
;         u32x4 o; o.x = cvtpk(s[0 * 33], s[1 * 33]); o.y = cvtpk(s[2 * 33], s[3 * 33]); o.z = cvtpk(s[4 * 33], s[5 * 33]); o.w = cvtpk(s[6 * 33], s[7 * 33]);
;         *(u32x4*)(WT + (size_t)map_n<KIND>(n0 + n) * ldk + kd0 + 8 * c) = o; }
;     asm volatile("s_waitcnt lgkmcnt(0)" ::: "memory");
; }
	v_pk_mul_f32 v[4:5], v[4:5], v[8:9] op_sel_hi:[1,0]
	v_add_u32_e32 v9, 0x840, v18
	ds_write2_b32 v9, v4, v5 offset1:1
	v_pk_mul_f32 v[4:5], v[6:7], v[8:9] op_sel_hi:[1,0]
	v_add_u32_e32 v6, 0x848, v18
	ds_write2_b32 v6, v4, v5 offset1:1
	global_load_dword v4, v31, s[6:7] offset:224
	s_waitcnt vmcnt(0)
	v_pk_mul_f32 v[0:1], v[0:1], v[4:5] op_sel_hi:[1,0]
	v_add_u32_e32 v5, 0xc60, v18
	ds_write2_b32 v5, v0, v1 offset1:1
	v_pk_mul_f32 v[0:1], v[2:3], v[4:5] op_sel_hi:[1,0]
	v_add_u32_e32 v2, 0xc68, v18
	ds_write2_b32 v2, v0, v1 offset1:1
	s_waitcnt lgkmcnt(0)
	ds_read2_b32 v[6:7], v58 offset0:33 offset1:41
	ds_read2_b32 v[8:9], v58 offset1:8
	ds_read2_b32 v[10:11], v58 offset0:66 offset1:74
	ds_read2_b32 v[14:15], v58 offset0:99 offset1:107
	ds_read2_b32 v[16:17], v58 offset0:132 offset1:140
	ds_read2_b32 v[18:19], v58 offset0:165 offset1:173
	ds_read2_b32 v[20:21], v58 offset0:198 offset1:206
	ds_read2_b32 v[22:23], v58 offset0:231 offset1:239
	v_lshl_add_u64 v[4:5], v[46:47], 0, v[128:129]
	s_waitcnt lgkmcnt(6)
	v_cvt_pk_bf16_f32 v0, v8, v6
	v_or_b32_e32 v6, v32, v12
	v_mul_u32_u24_e32 v8, 0x2aab, v6
	v_lshrrev_b32_e32 v8, 21, v8
	v_mul_lo_u16_e32 v8, 0xc0, v8
	v_sub_u16_e32 v8, v6, v8
	v_cmp_gt_u16_e64 s[6:7], s16, v8
	v_sub_u32_e32 v13, v6, v8
	s_waitcnt lgkmcnt(4)
	v_cvt_pk_bf16_f32 v1, v10, v14
	v_cmp_gt_u16_e32 vcc, s4, v8
	v_cndmask_b32_e64 v10, v201, v202, s[6:7]
	v_lshl_add_u32 v8, v8, 1, v13
	v_add3_u32 v8, v8, v10, s4
	v_cndmask_b32_e32 v24, v8, v6, vcc
	v_ashrrev_i32_e32 v25, 31, v24
	v_lshlrev_b64 v[24:25], 10, v[24:25]
	s_waitcnt lgkmcnt(2)
	v_cvt_pk_bf16_f32 v2, v16, v18
	s_waitcnt lgkmcnt(0)
	v_cvt_pk_bf16_f32 v3, v20, v22
	v_lshl_add_u64 v[24:25], v[4:5], 0, v[24:25]
	v_or_b32_e32 v6, v51, v12
	global_store_dwordx4 v[24:25], v[0:3], off sc1
	s_nop 1
	v_cvt_pk_bf16_f32 v0, v9, v7
	v_mul_u32_u24_e32 v7, 0x2aab, v6
	v_lshrrev_b32_e32 v7, 21, v7
	v_mul_lo_u16_e32 v7, 0xc0, v7
	v_sub_u16_e32 v7, v6, v7
	v_cmp_gt_u16_e64 s[6:7], s16, v7
	v_sub_u32_e32 v9, v6, v7
	v_cmp_gt_u16_e32 vcc, s4, v7
	v_cndmask_b32_e64 v8, v201, v202, s[6:7]
	v_lshl_add_u32 v7, v7, 1, v9
	v_add3_u32 v7, v7, v8, s4
	v_cndmask_b32_e32 v6, v7, v6, vcc
	v_ashrrev_i32_e32 v7, 31, v6
	v_lshlrev_b64 v[6:7], 10, v[6:7]
	v_cvt_pk_bf16_f32 v1, v11, v15
	v_cvt_pk_bf16_f32 v2, v17, v19
	v_cvt_pk_bf16_f32 v3, v21, v23
	v_lshl_add_u64 v[6:7], v[4:5], 0, v[6:7]
	global_store_dwordx4 v[6:7], v[0:3], off sc1
	ds_read2_b32 v[6:7], v58 offset0:16 offset1:24
	ds_read2_b32 v[8:9], v58 offset0:49 offset1:57
	ds_read2_b32 v[10:11], v58 offset0:82 offset1:90
	ds_read2_b32 v[14:15], v58 offset0:115 offset1:123
	ds_read2_b32 v[16:17], v58 offset0:148 offset1:156
	ds_read2_b32 v[18:19], v58 offset0:181 offset1:189
	ds_read2_b32 v[20:21], v58 offset0:214 offset1:222
	ds_read2_b32 v[22:23], v58 offset0:247 offset1:255
	s_waitcnt lgkmcnt(6)
	v_cvt_pk_bf16_f32 v0, v6, v8
	v_or_b32_e32 v6, v56, v12
	v_mul_u32_u24_e32 v8, 0x2aab, v6
	v_lshrrev_b32_e32 v8, 21, v8
	v_mul_lo_u16_e32 v8, 0xc0, v8
	v_sub_u16_e32 v8, v6, v8
	v_cmp_gt_u16_e64 s[6:7], s16, v8
	v_sub_u32_e32 v13, v6, v8
	s_waitcnt lgkmcnt(4)
	v_cvt_pk_bf16_f32 v1, v10, v14
	v_cmp_gt_u16_e32 vcc, s4, v8
	v_cndmask_b32_e64 v10, v201, v202, s[6:7]
	v_lshl_add_u32 v8, v8, 1, v13
	v_add3_u32 v8, v8, v10, s4
	v_cndmask_b32_e32 v24, v8, v6, vcc
	v_ashrrev_i32_e32 v25, 31, v24
	v_lshlrev_b64 v[24:25], 10, v[24:25]
	s_waitcnt lgkmcnt(2)
	v_cvt_pk_bf16_f32 v2, v16, v18
	s_waitcnt lgkmcnt(0)
	v_cvt_pk_bf16_f32 v3, v20, v22
	v_lshl_add_u64 v[24:25], v[4:5], 0, v[24:25]
	v_or_b32_e32 v6, v57, v12
	global_store_dwordx4 v[24:25], v[0:3], off sc1
	s_nop 1
	v_cvt_pk_bf16_f32 v0, v7, v9
	v_mul_u32_u24_e32 v7, 0x2aab, v6
	v_lshrrev_b32_e32 v7, 21, v7
	v_mul_lo_u16_e32 v7, 0xc0, v7
	v_sub_u16_e32 v7, v6, v7
	v_cmp_gt_u16_e64 s[6:7], s16, v7
	v_sub_u32_e32 v9, v6, v7
	v_cmp_gt_u16_e32 vcc, s4, v7
	v_cndmask_b32_e64 v8, v201, v202, s[6:7]
	v_lshl_add_u32 v7, v7, 1, v9
	v_add3_u32 v7, v7, v8, s4
	v_cndmask_b32_e32 v6, v7, v6, vcc
	v_ashrrev_i32_e32 v7, 31, v6
	v_lshlrev_b64 v[6:7], 10, v[6:7]
	v_cvt_pk_bf16_f32 v1, v11, v15
	v_cvt_pk_bf16_f32 v2, v17, v19
	v_cvt_pk_bf16_f32 v3, v21, v23
	v_lshl_add_u64 v[4:5], v[4:5], 0, v[6:7]
	global_store_dwordx4 v[4:5], v[0:3], off sc1
	s_waitcnt lgkmcnt(0)
